# GEMM K-loop: one A-half LDS-DMA stage moved from the 6-DMA load segment to the next 2-DMA segment (DMAs per segment 2,4,4,6; vmcnt 8,6,8,8), on top of attention negm + MOD prefetch + G4/G5 barrier ski
# baseline (speedup 1.0000x reference)
.LBB0_196:
	s_add_u32 s24, s22, 0xfffc0080
	s_addc_u32 s25, s23, -1
	s_add_i32 s49, 0, 0x10000
	s_cmp_eq_u32 s48, 12
	s_cselect_b32 s27, s7, s25
	s_cselect_b32 s26, s42, s24
	s_cselect_b32 s25, s9, s47
	s_cselect_b32 s24, s43, s46
	s_add_i32 s52, 0, 0x14000
	v_add_u32_e32 v156, s49, v141
	v_add_u32_e32 v172, s52, v141
	ds_read_b128 v[144:147], v156
	ds_read_b128 v[148:151], v156 offset:1024
	ds_read_b128 v[152:155], v156 offset:2048
	ds_read_b128 v[156:159], v156 offset:3072
	ds_read_b128 v[160:163], v172
	ds_read_b128 v[164:167], v172 offset:1024
	ds_read_b128 v[168:171], v172 offset:2048
	ds_read_b128 v[172:175], v172 offset:3072
	v_lshl_add_u64 v[208:209], s[22:23], 0, v[136:137]
	s_add_i32 m0, s35, 0xc000
	ds_read_b128 v[176:179], v143
	ds_read_b128 v[180:183], v143 offset:1024
	ds_read_b128 v[184:187], v143 offset:2048
	ds_read_b128 v[188:191], v143 offset:3072
	ds_read_b128 v[192:195], v143 offset:4096
	ds_read_b128 v[196:199], v143 offset:5120
	ds_read_b128 v[200:203], v143 offset:6144
	ds_read_b128 v[204:207], v143 offset:7168
	global_load_lds_dwordx4 v[208:209], off
	v_lshl_add_u64 v[208:209], s[22:23], 0, v[138:139]
	s_add_i32 m0, s35, 0xe000
	s_nop 0
	global_load_lds_dwordx4 v[208:209], off
	s_waitcnt vmcnt(8)
	s_waitcnt lgkmcnt(0)
	s_barrier
	s_setprio 1
	s_waitcnt lgkmcnt(0)
	v_mfma_f32_16x16x32_bf16 v[126:129], v[144:147], v[176:179], v[126:129]
	v_mfma_f32_16x16x32_bf16 v[118:121], v[152:155], v[176:179], v[118:121]
	v_mfma_f32_16x16x32_bf16 v[110:113], v[144:147], v[184:187], v[110:113]
	v_mfma_f32_16x16x32_bf16 v[102:105], v[152:155], v[184:187], v[102:105]
	v_mfma_f32_16x16x32_bf16 v[94:97], v[144:147], v[192:195], v[94:97]
	v_mfma_f32_16x16x32_bf16 v[86:89], v[152:155], v[192:195], v[86:89]
	v_mfma_f32_16x16x32_bf16 v[78:81], v[144:147], v[200:203], v[78:81]
	v_mfma_f32_16x16x32_bf16 v[70:73], v[152:155], v[200:203], v[70:73]
	v_mfma_f32_16x16x32_bf16 v[126:129], v[148:151], v[180:183], v[126:129]
	v_mfma_f32_16x16x32_bf16 v[118:121], v[156:159], v[180:183], v[118:121]
	v_mfma_f32_16x16x32_bf16 v[110:113], v[148:151], v[188:191], v[110:113]
	v_mfma_f32_16x16x32_bf16 v[102:105], v[156:159], v[188:191], v[102:105]
	v_mfma_f32_16x16x32_bf16 v[94:97], v[148:151], v[196:199], v[94:97]
	v_mfma_f32_16x16x32_bf16 v[86:89], v[156:159], v[196:199], v[86:89]
	v_mfma_f32_16x16x32_bf16 v[78:81], v[148:151], v[204:207], v[78:81]
	v_mfma_f32_16x16x32_bf16 v[70:73], v[156:159], v[204:207], v[70:73]
	s_setprio 0
	s_setprio 1
	v_mfma_f32_16x16x32_bf16 v[122:125], v[160:163], v[176:179], v[122:125]
	v_mfma_f32_16x16x32_bf16 v[114:117], v[168:171], v[176:179], v[114:117]
	v_mfma_f32_16x16x32_bf16 v[106:109], v[160:163], v[184:187], v[106:109]
	v_mfma_f32_16x16x32_bf16 v[98:101], v[168:171], v[184:187], v[98:101]
	v_mfma_f32_16x16x32_bf16 v[90:93], v[160:163], v[192:195], v[90:93]
	v_mfma_f32_16x16x32_bf16 v[82:85], v[168:171], v[192:195], v[82:85]
	v_mfma_f32_16x16x32_bf16 v[74:77], v[160:163], v[200:203], v[74:77]
	v_mfma_f32_16x16x32_bf16 v[66:69], v[168:171], v[200:203], v[66:69]
	v_mfma_f32_16x16x32_bf16 v[122:125], v[164:167], v[180:183], v[122:125]
	v_mfma_f32_16x16x32_bf16 v[114:117], v[172:175], v[180:183], v[114:117]
	v_mfma_f32_16x16x32_bf16 v[106:109], v[164:167], v[188:191], v[106:109]
	v_mfma_f32_16x16x32_bf16 v[98:101], v[172:175], v[188:191], v[98:101]
	v_mfma_f32_16x16x32_bf16 v[90:93], v[164:167], v[196:199], v[90:93]
	v_mfma_f32_16x16x32_bf16 v[82:85], v[172:175], v[196:199], v[82:85]
	v_mfma_f32_16x16x32_bf16 v[74:77], v[164:167], v[204:207], v[74:77]
	v_mfma_f32_16x16x32_bf16 v[66:69], v[172:175], v[204:207], v[66:69]
	s_setprio 0
	s_barrier
	s_add_i32 s49, s49, s34
	v_lshl_add_u64 v[208:209], s[24:25], 0, v[0:1]
	s_mov_b32 m0, s49
	ds_read_b128 v[176:179], v143 offset:16384
	ds_read_b128 v[180:183], v143 offset:17408
	ds_read_b128 v[184:187], v143 offset:18432
	ds_read_b128 v[188:191], v143 offset:19456
	ds_read_b128 v[192:195], v143 offset:20480
	ds_read_b128 v[196:199], v143 offset:21504
	ds_read_b128 v[200:203], v143 offset:22528
	ds_read_b128 v[204:207], v143 offset:23552
	global_load_lds_dwordx4 v[208:209], off
	s_add_i32 m0, s49, 0x2000
	s_add_u32 s50, s24, 0x40000
	v_lshl_add_u64 v[210:211], s[24:25], 0, v[130:131]
	s_addc_u32 s51, s25, 0
	s_add_i32 s49, s52, s34
	global_load_lds_dwordx4 v[210:211], off
	v_lshl_add_u64 v[212:213], s[50:51], 0, v[0:1]
	s_mov_b32 m0, s49
	v_lshl_add_u64 v[214:215], s[26:27], 0, v[132:133]
	global_load_lds_dwordx4 v[212:213], off
	v_lshl_add_u64 v[212:213], s[50:51], 0, v[130:131]
	s_add_i32 m0, s49, 0x2000
	s_nop 0
	global_load_lds_dwordx4 v[212:213], off
	s_waitcnt vmcnt(6)
	s_waitcnt lgkmcnt(0)
	s_barrier
	s_setprio 1
	s_waitcnt lgkmcnt(0)
	v_mfma_f32_16x16x32_bf16 v[62:65], v[144:147], v[176:179], v[62:65]
	v_mfma_f32_16x16x32_bf16 v[54:57], v[152:155], v[176:179], v[54:57]
	v_mfma_f32_16x16x32_bf16 v[46:49], v[144:147], v[184:187], v[46:49]
	v_mfma_f32_16x16x32_bf16 v[38:41], v[152:155], v[184:187], v[38:41]
	v_mfma_f32_16x16x32_bf16 v[30:33], v[144:147], v[192:195], v[30:33]
	v_mfma_f32_16x16x32_bf16 v[22:25], v[152:155], v[192:195], v[22:25]
	v_mfma_f32_16x16x32_bf16 v[14:17], v[144:147], v[200:203], v[14:17]
	v_mfma_f32_16x16x32_bf16 v[6:9], v[152:155], v[200:203], v[6:9]
	v_mfma_f32_16x16x32_bf16 v[62:65], v[148:151], v[180:183], v[62:65]
	v_mfma_f32_16x16x32_bf16 v[54:57], v[156:159], v[180:183], v[54:57]
	v_mfma_f32_16x16x32_bf16 v[46:49], v[148:151], v[188:191], v[46:49]
	v_mfma_f32_16x16x32_bf16 v[38:41], v[156:159], v[188:191], v[38:41]
	v_mfma_f32_16x16x32_bf16 v[30:33], v[148:151], v[196:199], v[30:33]
	v_mfma_f32_16x16x32_bf16 v[22:25], v[156:159], v[196:199], v[22:25]
	v_mfma_f32_16x16x32_bf16 v[14:17], v[148:151], v[204:207], v[14:17]
	v_mfma_f32_16x16x32_bf16 v[6:9], v[156:159], v[204:207], v[6:9]
	s_setprio 0
	s_setprio 1
	v_mfma_f32_16x16x32_bf16 v[58:61], v[160:163], v[176:179], v[58:61]
	v_mfma_f32_16x16x32_bf16 v[50:53], v[168:171], v[176:179], v[50:53]
	v_mfma_f32_16x16x32_bf16 v[42:45], v[160:163], v[184:187], v[42:45]
	v_mfma_f32_16x16x32_bf16 v[34:37], v[168:171], v[184:187], v[34:37]
	v_mfma_f32_16x16x32_bf16 v[26:29], v[160:163], v[192:195], v[26:29]
	v_mfma_f32_16x16x32_bf16 v[18:21], v[168:171], v[192:195], v[18:21]
	v_mfma_f32_16x16x32_bf16 v[10:13], v[160:163], v[200:203], v[10:13]
	v_mfma_f32_16x16x32_bf16 v[2:5], v[168:171], v[200:203], v[2:5]
	v_mfma_f32_16x16x32_bf16 v[58:61], v[164:167], v[180:183], v[58:61]
	v_mfma_f32_16x16x32_bf16 v[50:53], v[172:175], v[180:183], v[50:53]
	v_mfma_f32_16x16x32_bf16 v[42:45], v[164:167], v[188:191], v[42:45]
	v_mfma_f32_16x16x32_bf16 v[34:37], v[172:175], v[188:191], v[34:37]
	v_mfma_f32_16x16x32_bf16 v[26:29], v[164:167], v[196:199], v[26:29]
	v_mfma_f32_16x16x32_bf16 v[18:21], v[172:175], v[196:199], v[18:21]
	v_mfma_f32_16x16x32_bf16 v[10:13], v[164:167], v[204:207], v[10:13]
	v_mfma_f32_16x16x32_bf16 v[2:5], v[172:175], v[204:207], v[2:5]
	s_setprio 0
	s_barrier
	s_add_i32 s49, 0, 0x18000
	s_add_i32 s50, 0, 0x1c000
	v_add_u32_e32 v156, s49, v141
	v_add_u32_e32 v172, s50, v141
	ds_read_b128 v[144:147], v156
	ds_read_b128 v[148:151], v156 offset:1024
	ds_read_b128 v[152:155], v156 offset:2048
	ds_read_b128 v[156:159], v156 offset:3072
	ds_read_b128 v[160:163], v172
	ds_read_b128 v[164:167], v172 offset:1024
	ds_read_b128 v[168:171], v172 offset:2048
	ds_read_b128 v[172:175], v172 offset:3072
	v_lshl_add_u64 v[212:213], s[26:27], 0, v[134:135]
	s_mov_b32 m0, s35
	s_nop 0
	global_load_lds_dwordx4 v[212:213], off
	s_mov_b32 m0, s36
	s_nop 0
	global_load_lds_dwordx4 v[214:215], off
	s_add_u32 s26, s26, 0x40000
	s_addc_u32 s27, s27, 0
	s_mov_b32 m0, s37
	v_lshl_add_u64 v[216:217], s[26:27], 0, v[134:135]
	ds_read_b128 v[176:179], v143 offset:32768
	ds_read_b128 v[180:183], v143 offset:33792
	ds_read_b128 v[184:187], v143 offset:34816
	ds_read_b128 v[188:191], v143 offset:35840
	ds_read_b128 v[192:195], v143 offset:36864
	ds_read_b128 v[196:199], v143 offset:37888
	ds_read_b128 v[200:203], v143 offset:38912
	ds_read_b128 v[204:207], v143 offset:39936
	global_load_lds_dwordx4 v[216:217], off
	v_lshl_add_u64 v[216:217], s[26:27], 0, v[132:133]
	s_mov_b32 m0, s38
	s_nop 0
	global_load_lds_dwordx4 v[216:217], off
	s_waitcnt vmcnt(8)
	s_waitcnt lgkmcnt(0)
	s_barrier
	s_setprio 1
	s_waitcnt lgkmcnt(0)
	v_mfma_f32_16x16x32_bf16 v[126:129], v[144:147], v[176:179], v[126:129]
	v_mfma_f32_16x16x32_bf16 v[118:121], v[152:155], v[176:179], v[118:121]
	v_mfma_f32_16x16x32_bf16 v[110:113], v[144:147], v[184:187], v[110:113]
	v_mfma_f32_16x16x32_bf16 v[102:105], v[152:155], v[184:187], v[102:105]
	v_mfma_f32_16x16x32_bf16 v[94:97], v[144:147], v[192:195], v[94:97]
	v_mfma_f32_16x16x32_bf16 v[86:89], v[152:155], v[192:195], v[86:89]
	v_mfma_f32_16x16x32_bf16 v[78:81], v[144:147], v[200:203], v[78:81]
	v_mfma_f32_16x16x32_bf16 v[70:73], v[152:155], v[200:203], v[70:73]
	v_mfma_f32_16x16x32_bf16 v[126:129], v[148:151], v[180:183], v[126:129]
	v_mfma_f32_16x16x32_bf16 v[118:121], v[156:159], v[180:183], v[118:121]
	v_mfma_f32_16x16x32_bf16 v[110:113], v[148:151], v[188:191], v[110:113]
	v_mfma_f32_16x16x32_bf16 v[102:105], v[156:159], v[188:191], v[102:105]
	v_mfma_f32_16x16x32_bf16 v[94:97], v[148:151], v[196:199], v[94:97]
	v_mfma_f32_16x16x32_bf16 v[86:89], v[156:159], v[196:199], v[86:89]
	v_mfma_f32_16x16x32_bf16 v[78:81], v[148:151], v[204:207], v[78:81]
	v_mfma_f32_16x16x32_bf16 v[70:73], v[156:159], v[204:207], v[70:73]
	s_setprio 0
	s_setprio 1
	v_mfma_f32_16x16x32_bf16 v[122:125], v[160:163], v[176:179], v[122:125]
	v_mfma_f32_16x16x32_bf16 v[114:117], v[168:171], v[176:179], v[114:117]
	v_mfma_f32_16x16x32_bf16 v[106:109], v[160:163], v[184:187], v[106:109]
	v_mfma_f32_16x16x32_bf16 v[98:101], v[168:171], v[184:187], v[98:101]
	v_mfma_f32_16x16x32_bf16 v[90:93], v[160:163], v[192:195], v[90:93]
	v_mfma_f32_16x16x32_bf16 v[82:85], v[168:171], v[192:195], v[82:85]
	v_mfma_f32_16x16x32_bf16 v[74:77], v[160:163], v[200:203], v[74:77]
	v_mfma_f32_16x16x32_bf16 v[66:69], v[168:171], v[200:203], v[66:69]
	v_mfma_f32_16x16x32_bf16 v[122:125], v[164:167], v[180:183], v[122:125]
	v_mfma_f32_16x16x32_bf16 v[114:117], v[172:175], v[180:183], v[114:117]
	v_mfma_f32_16x16x32_bf16 v[106:109], v[164:167], v[188:191], v[106:109]
	v_mfma_f32_16x16x32_bf16 v[98:101], v[172:175], v[188:191], v[98:101]
	v_mfma_f32_16x16x32_bf16 v[90:93], v[164:167], v[196:199], v[90:93]
	v_mfma_f32_16x16x32_bf16 v[82:85], v[172:175], v[196:199], v[82:85]
	v_mfma_f32_16x16x32_bf16 v[74:77], v[164:167], v[204:207], v[74:77]
	v_mfma_f32_16x16x32_bf16 v[66:69], v[172:175], v[204:207], v[66:69]
	s_setprio 0
	s_barrier
	s_add_i32 s26, s49, s34
	v_lshl_add_u64 v[208:209], v[208:209], 0, s[80:81]
	s_mov_b32 m0, s26
	ds_read_b128 v[176:179], v143 offset:49152
	ds_read_b128 v[180:183], v143 offset:50176
	ds_read_b128 v[184:187], v143 offset:51200
	ds_read_b128 v[188:191], v143 offset:52224
	ds_read_b128 v[192:195], v143 offset:53248
	ds_read_b128 v[196:199], v143 offset:54272
	ds_read_b128 v[200:203], v143 offset:55296
	ds_read_b128 v[204:207], v143 offset:56320
	global_load_lds_dwordx4 v[208:209], off
	s_add_i32 m0, s26, 0x2000
	s_add_u32 s24, s24, 0x40080
	v_lshl_add_u64 v[208:209], v[210:211], 0, s[80:81]
	s_addc_u32 s25, s25, 0
	s_add_i32 s26, s50, s34
	global_load_lds_dwordx4 v[208:209], off
	v_lshl_add_u64 v[208:209], s[24:25], 0, v[0:1]
	s_mov_b32 m0, s26
	s_nop 0
	global_load_lds_dwordx4 v[208:209], off
	v_lshl_add_u64 v[208:209], s[24:25], 0, v[130:131]
	s_add_i32 m0, s26, 0x2000
	s_nop 0
	global_load_lds_dwordx4 v[208:209], off
	v_lshl_add_u64 v[208:209], v[212:213], 0, s[80:81]
	s_mov_b32 m0, s39
	s_nop 0
	global_load_lds_dwordx4 v[208:209], off
	v_lshl_add_u64 v[208:209], v[214:215], 0, s[80:81]
	s_mov_b32 m0, s40
	s_nop 0
	global_load_lds_dwordx4 v[208:209], off
	s_waitcnt vmcnt(8)
	s_waitcnt lgkmcnt(0)
	s_barrier
	s_setprio 1
	s_waitcnt lgkmcnt(0)
	v_mfma_f32_16x16x32_bf16 v[62:65], v[144:147], v[176:179], v[62:65]
	v_mfma_f32_16x16x32_bf16 v[54:57], v[152:155], v[176:179], v[54:57]
	v_mfma_f32_16x16x32_bf16 v[46:49], v[144:147], v[184:187], v[46:49]
	v_mfma_f32_16x16x32_bf16 v[38:41], v[152:155], v[184:187], v[38:41]
	v_mfma_f32_16x16x32_bf16 v[30:33], v[144:147], v[192:195], v[30:33]
	v_mfma_f32_16x16x32_bf16 v[22:25], v[152:155], v[192:195], v[22:25]
	v_mfma_f32_16x16x32_bf16 v[14:17], v[144:147], v[200:203], v[14:17]
	v_mfma_f32_16x16x32_bf16 v[6:9], v[152:155], v[200:203], v[6:9]
	v_mfma_f32_16x16x32_bf16 v[62:65], v[148:151], v[180:183], v[62:65]
	v_mfma_f32_16x16x32_bf16 v[54:57], v[156:159], v[180:183], v[54:57]
	v_mfma_f32_16x16x32_bf16 v[46:49], v[148:151], v[188:191], v[46:49]
	v_mfma_f32_16x16x32_bf16 v[38:41], v[156:159], v[188:191], v[38:41]
	v_mfma_f32_16x16x32_bf16 v[30:33], v[148:151], v[196:199], v[30:33]
	v_mfma_f32_16x16x32_bf16 v[22:25], v[156:159], v[196:199], v[22:25]
	v_mfma_f32_16x16x32_bf16 v[14:17], v[148:151], v[204:207], v[14:17]
	v_mfma_f32_16x16x32_bf16 v[6:9], v[156:159], v[204:207], v[6:9]
	s_setprio 0
	s_setprio 1
	v_mfma_f32_16x16x32_bf16 v[58:61], v[160:163], v[176:179], v[58:61]
	v_mfma_f32_16x16x32_bf16 v[50:53], v[168:171], v[176:179], v[50:53]
	v_mfma_f32_16x16x32_bf16 v[42:45], v[160:163], v[184:187], v[42:45]
	v_mfma_f32_16x16x32_bf16 v[34:37], v[168:171], v[184:187], v[34:37]
	v_mfma_f32_16x16x32_bf16 v[26:29], v[160:163], v[192:195], v[26:29]
	v_mfma_f32_16x16x32_bf16 v[18:21], v[168:171], v[192:195], v[18:21]
	v_mfma_f32_16x16x32_bf16 v[10:13], v[160:163], v[200:203], v[10:13]
	v_mfma_f32_16x16x32_bf16 v[2:5], v[168:171], v[200:203], v[2:5]
	v_mfma_f32_16x16x32_bf16 v[58:61], v[164:167], v[180:183], v[58:61]
	v_mfma_f32_16x16x32_bf16 v[50:53], v[172:175], v[180:183], v[50:53]
	v_mfma_f32_16x16x32_bf16 v[42:45], v[164:167], v[188:191], v[42:45]
	v_mfma_f32_16x16x32_bf16 v[34:37], v[172:175], v[188:191], v[34:37]
	v_mfma_f32_16x16x32_bf16 v[26:29], v[164:167], v[196:199], v[26:29]
	v_mfma_f32_16x16x32_bf16 v[18:21], v[172:175], v[196:199], v[18:21]
	v_mfma_f32_16x16x32_bf16 v[10:13], v[164:167], v[204:207], v[10:13]
	v_mfma_f32_16x16x32_bf16 v[2:5], v[172:175], v[204:207], v[2:5]
	s_setprio 0
	s_barrier
	s_add_i32 s48, s48, 2
	s_add_u32 s22, s22, 0x100
	s_addc_u32 s23, s23, 0
	s_add_u32 s46, s46, 0x100
	s_addc_u32 s47, s47, 0
	s_cmp_gt_u32 s48, 13
	s_cbranch_scc0 .LBB0_196
	s_and_b64 vcc, exec, s[4:5]
	s_cbranch_vccz .LBB0_199
	s_barrier

.LBB0_280:
	s_add_u32 s10, s0, 0x100
	s_addc_u32 s11, s1, 0
	s_add_i32 s68, 0, 0x10000
	s_cmp_eq_u32 s43, 40
	s_cselect_b32 s41, s31, s11
	s_cselect_b32 s40, s30, s10
	s_cselect_b32 s39, s35, s42
	s_cselect_b32 s38, s34, s37
	s_add_i32 s69, 0, 0x14000
	v_add_u32_e32 v142, s68, v193
	v_add_u32_e32 v158, s69, v193
	ds_read_b128 v[130:133], v142
	ds_read_b128 v[134:137], v142 offset:1024
	ds_read_b128 v[138:141], v142 offset:2048
	ds_read_b128 v[142:145], v142 offset:3072
	ds_read_b128 v[146:149], v158
	ds_read_b128 v[150:153], v158 offset:1024
	ds_read_b128 v[154:157], v158 offset:2048
	ds_read_b128 v[158:161], v158 offset:3072
	v_lshl_add_u64 v[190:191], s[0:1], 0, v[170:171]
	s_add_i32 m0, s53, 0xc000
	ds_read_b128 v[174:177], v199
	ds_read_b128 v[178:181], v199 offset:1024
	ds_read_b128 v[182:185], v199 offset:2048
	ds_read_b128 v[186:189], v199 offset:3072
	ds_read_b128 v[206:209], v199 offset:4096
	ds_read_b128 v[210:213], v199 offset:5120
	ds_read_b128 v[214:217], v199 offset:6144
	ds_read_b128 v[218:221], v199 offset:7168
	global_load_lds_dwordx4 v[190:191], off
	v_lshl_add_u64 v[190:191], s[0:1], 0, v[172:173]
	s_add_i32 m0, s53, 0xe000
	s_nop 0
	global_load_lds_dwordx4 v[190:191], off
	s_waitcnt vmcnt(8)
	s_waitcnt lgkmcnt(0)
	s_barrier
	s_setprio 1
	s_waitcnt lgkmcnt(0)
	v_mfma_f32_16x16x32_bf16 v[126:129], v[130:133], v[174:177], v[126:129]
	v_mfma_f32_16x16x32_bf16 v[122:125], v[138:141], v[174:177], v[122:125]
	v_mfma_f32_16x16x32_bf16 v[110:113], v[130:133], v[182:185], v[110:113]
	v_mfma_f32_16x16x32_bf16 v[106:109], v[138:141], v[182:185], v[106:109]
	v_mfma_f32_16x16x32_bf16 v[94:97], v[130:133], v[206:209], v[94:97]
	v_mfma_f32_16x16x32_bf16 v[90:93], v[138:141], v[206:209], v[90:93]
	v_mfma_f32_16x16x32_bf16 v[78:81], v[130:133], v[214:217], v[78:81]
	v_mfma_f32_16x16x32_bf16 v[74:77], v[138:141], v[214:217], v[74:77]
	v_mfma_f32_16x16x32_bf16 v[126:129], v[134:137], v[178:181], v[126:129]
	v_mfma_f32_16x16x32_bf16 v[122:125], v[142:145], v[178:181], v[122:125]
	v_mfma_f32_16x16x32_bf16 v[110:113], v[134:137], v[186:189], v[110:113]
	v_mfma_f32_16x16x32_bf16 v[106:109], v[142:145], v[186:189], v[106:109]
	v_mfma_f32_16x16x32_bf16 v[94:97], v[134:137], v[210:213], v[94:97]
	v_mfma_f32_16x16x32_bf16 v[90:93], v[142:145], v[210:213], v[90:93]
	v_mfma_f32_16x16x32_bf16 v[78:81], v[134:137], v[218:221], v[78:81]
	v_mfma_f32_16x16x32_bf16 v[74:77], v[142:145], v[218:221], v[74:77]
	s_setprio 0
	s_setprio 1
	v_mfma_f32_16x16x32_bf16 v[118:121], v[146:149], v[174:177], v[118:121]
	v_mfma_f32_16x16x32_bf16 v[114:117], v[154:157], v[174:177], v[114:117]
	v_mfma_f32_16x16x32_bf16 v[102:105], v[146:149], v[182:185], v[102:105]
	v_mfma_f32_16x16x32_bf16 v[98:101], v[154:157], v[182:185], v[98:101]
	v_mfma_f32_16x16x32_bf16 v[86:89], v[146:149], v[206:209], v[86:89]
	v_mfma_f32_16x16x32_bf16 v[82:85], v[154:157], v[206:209], v[82:85]
	v_mfma_f32_16x16x32_bf16 v[70:73], v[146:149], v[214:217], v[70:73]
	v_mfma_f32_16x16x32_bf16 v[66:69], v[154:157], v[214:217], v[66:69]
	v_mfma_f32_16x16x32_bf16 v[118:121], v[150:153], v[178:181], v[118:121]
	v_mfma_f32_16x16x32_bf16 v[114:117], v[158:161], v[178:181], v[114:117]
	v_mfma_f32_16x16x32_bf16 v[102:105], v[150:153], v[186:189], v[102:105]
	v_mfma_f32_16x16x32_bf16 v[98:101], v[158:161], v[186:189], v[98:101]
	v_mfma_f32_16x16x32_bf16 v[86:89], v[150:153], v[210:213], v[86:89]
	v_mfma_f32_16x16x32_bf16 v[82:85], v[158:161], v[210:213], v[82:85]
	v_mfma_f32_16x16x32_bf16 v[70:73], v[150:153], v[218:221], v[70:73]
	v_mfma_f32_16x16x32_bf16 v[66:69], v[158:161], v[218:221], v[66:69]
	s_setprio 0
	s_barrier
	s_add_i32 s0, s68, s52
	v_lshl_add_u64 v[190:191], s[38:39], 0, v[0:1]
	s_mov_b32 m0, s0
	ds_read_b128 v[174:177], v199 offset:16384
	ds_read_b128 v[178:181], v199 offset:17408
	ds_read_b128 v[182:185], v199 offset:18432
	ds_read_b128 v[186:189], v199 offset:19456
	ds_read_b128 v[206:209], v199 offset:20480
	ds_read_b128 v[210:213], v199 offset:21504
	ds_read_b128 v[214:217], v199 offset:22528
	ds_read_b128 v[218:221], v199 offset:23552
	global_load_lds_dwordx4 v[190:191], off
	s_add_i32 m0, s0, 0x2000
	s_add_u32 s0, s38, 0xb0000
	v_lshl_add_u64 v[222:223], s[38:39], 0, v[166:167]
	s_addc_u32 s1, s39, 0
	s_add_i32 s68, s69, s52
	global_load_lds_dwordx4 v[222:223], off
	v_lshl_add_u64 v[224:225], s[0:1], 0, v[0:1]
	s_mov_b32 m0, s68
	v_lshl_add_u64 v[226:227], s[40:41], 0, v[164:165]
	global_load_lds_dwordx4 v[224:225], off
	v_lshl_add_u64 v[224:225], s[0:1], 0, v[166:167]
	s_add_i32 m0, s68, 0x2000
	s_nop 0
	global_load_lds_dwordx4 v[224:225], off
	s_waitcnt vmcnt(6)
	s_waitcnt lgkmcnt(0)
	s_barrier
	s_setprio 1
	s_waitcnt lgkmcnt(0)
	v_mfma_f32_16x16x32_bf16 v[62:65], v[130:133], v[174:177], v[62:65]
	v_mfma_f32_16x16x32_bf16 v[58:61], v[138:141], v[174:177], v[58:61]
	v_mfma_f32_16x16x32_bf16 v[46:49], v[130:133], v[182:185], v[46:49]
	v_mfma_f32_16x16x32_bf16 v[42:45], v[138:141], v[182:185], v[42:45]
	v_mfma_f32_16x16x32_bf16 v[30:33], v[130:133], v[206:209], v[30:33]
	v_mfma_f32_16x16x32_bf16 v[26:29], v[138:141], v[206:209], v[26:29]
	v_mfma_f32_16x16x32_bf16 v[14:17], v[130:133], v[214:217], v[14:17]
	v_mfma_f32_16x16x32_bf16 v[10:13], v[138:141], v[214:217], v[10:13]
	v_mfma_f32_16x16x32_bf16 v[62:65], v[134:137], v[178:181], v[62:65]
	v_mfma_f32_16x16x32_bf16 v[58:61], v[142:145], v[178:181], v[58:61]
	v_mfma_f32_16x16x32_bf16 v[46:49], v[134:137], v[186:189], v[46:49]
	v_mfma_f32_16x16x32_bf16 v[42:45], v[142:145], v[186:189], v[42:45]
	v_mfma_f32_16x16x32_bf16 v[30:33], v[134:137], v[210:213], v[30:33]
	v_mfma_f32_16x16x32_bf16 v[26:29], v[142:145], v[210:213], v[26:29]
	v_mfma_f32_16x16x32_bf16 v[14:17], v[134:137], v[218:221], v[14:17]
	v_mfma_f32_16x16x32_bf16 v[10:13], v[142:145], v[218:221], v[10:13]
	s_setprio 0
	s_setprio 1
	v_mfma_f32_16x16x32_bf16 v[54:57], v[146:149], v[174:177], v[54:57]
	v_mfma_f32_16x16x32_bf16 v[50:53], v[154:157], v[174:177], v[50:53]
	v_mfma_f32_16x16x32_bf16 v[38:41], v[146:149], v[182:185], v[38:41]
	v_mfma_f32_16x16x32_bf16 v[34:37], v[154:157], v[182:185], v[34:37]
	v_mfma_f32_16x16x32_bf16 v[22:25], v[146:149], v[206:209], v[22:25]
	v_mfma_f32_16x16x32_bf16 v[18:21], v[154:157], v[206:209], v[18:21]
	v_mfma_f32_16x16x32_bf16 v[6:9], v[146:149], v[214:217], v[6:9]
	v_mfma_f32_16x16x32_bf16 v[2:5], v[154:157], v[214:217], v[2:5]
	v_mfma_f32_16x16x32_bf16 v[54:57], v[150:153], v[178:181], v[54:57]
	v_mfma_f32_16x16x32_bf16 v[50:53], v[158:161], v[178:181], v[50:53]
	v_mfma_f32_16x16x32_bf16 v[38:41], v[150:153], v[186:189], v[38:41]
	v_mfma_f32_16x16x32_bf16 v[34:37], v[158:161], v[186:189], v[34:37]
	v_mfma_f32_16x16x32_bf16 v[22:25], v[150:153], v[210:213], v[22:25]
	v_mfma_f32_16x16x32_bf16 v[18:21], v[158:161], v[210:213], v[18:21]
	v_mfma_f32_16x16x32_bf16 v[6:9], v[150:153], v[218:221], v[6:9]
	v_mfma_f32_16x16x32_bf16 v[2:5], v[158:161], v[218:221], v[2:5]
	s_setprio 0
	s_barrier
	s_add_i32 s68, 0, 0x18000
	s_add_i32 s69, 0, 0x1c000
	v_add_u32_e32 v142, s68, v193
	v_add_u32_e32 v158, s69, v193
	ds_read_b128 v[130:133], v142
	ds_read_b128 v[134:137], v142 offset:1024
	ds_read_b128 v[138:141], v142 offset:2048
	ds_read_b128 v[142:145], v142 offset:3072
	ds_read_b128 v[146:149], v158
	ds_read_b128 v[150:153], v158 offset:1024
	ds_read_b128 v[154:157], v158 offset:2048
	ds_read_b128 v[158:161], v158 offset:3072
	s_add_u32 s0, s40, 0xb0000
	s_addc_u32 s1, s41, 0
	v_lshl_add_u64 v[224:225], s[40:41], 0, v[162:163]
	s_mov_b32 m0, s53
	s_nop 0
	global_load_lds_dwordx4 v[224:225], off
	s_mov_b32 m0, s54
	s_nop 0
	global_load_lds_dwordx4 v[226:227], off
	s_mov_b32 m0, s55
	v_lshl_add_u64 v[228:229], s[0:1], 0, v[162:163]
	ds_read_b128 v[174:177], v199 offset:32768
	ds_read_b128 v[178:181], v199 offset:33792
	ds_read_b128 v[182:185], v199 offset:34816
	ds_read_b128 v[186:189], v199 offset:35840
	ds_read_b128 v[206:209], v199 offset:36864
	ds_read_b128 v[210:213], v199 offset:37888
	ds_read_b128 v[214:217], v199 offset:38912
	ds_read_b128 v[218:221], v199 offset:39936
	global_load_lds_dwordx4 v[228:229], off
	v_lshl_add_u64 v[228:229], s[0:1], 0, v[164:165]
	s_mov_b32 m0, s56
	s_nop 0
	global_load_lds_dwordx4 v[228:229], off
	s_waitcnt vmcnt(8)
	s_waitcnt lgkmcnt(0)
	s_barrier
	s_setprio 1
	s_waitcnt lgkmcnt(0)
	v_mfma_f32_16x16x32_bf16 v[126:129], v[130:133], v[174:177], v[126:129]
	v_mfma_f32_16x16x32_bf16 v[122:125], v[138:141], v[174:177], v[122:125]
	v_mfma_f32_16x16x32_bf16 v[110:113], v[130:133], v[182:185], v[110:113]
	v_mfma_f32_16x16x32_bf16 v[106:109], v[138:141], v[182:185], v[106:109]
	v_mfma_f32_16x16x32_bf16 v[94:97], v[130:133], v[206:209], v[94:97]
	v_mfma_f32_16x16x32_bf16 v[90:93], v[138:141], v[206:209], v[90:93]
	v_mfma_f32_16x16x32_bf16 v[78:81], v[130:133], v[214:217], v[78:81]
	v_mfma_f32_16x16x32_bf16 v[74:77], v[138:141], v[214:217], v[74:77]
	v_mfma_f32_16x16x32_bf16 v[126:129], v[134:137], v[178:181], v[126:129]
	v_mfma_f32_16x16x32_bf16 v[122:125], v[142:145], v[178:181], v[122:125]
	v_mfma_f32_16x16x32_bf16 v[110:113], v[134:137], v[186:189], v[110:113]
	v_mfma_f32_16x16x32_bf16 v[106:109], v[142:145], v[186:189], v[106:109]
	v_mfma_f32_16x16x32_bf16 v[94:97], v[134:137], v[210:213], v[94:97]
	v_mfma_f32_16x16x32_bf16 v[90:93], v[142:145], v[210:213], v[90:93]
	v_mfma_f32_16x16x32_bf16 v[78:81], v[134:137], v[218:221], v[78:81]
	v_mfma_f32_16x16x32_bf16 v[74:77], v[142:145], v[218:221], v[74:77]
	s_setprio 0
	s_setprio 1
	v_mfma_f32_16x16x32_bf16 v[118:121], v[146:149], v[174:177], v[118:121]
	v_mfma_f32_16x16x32_bf16 v[114:117], v[154:157], v[174:177], v[114:117]
	v_mfma_f32_16x16x32_bf16 v[102:105], v[146:149], v[182:185], v[102:105]
	v_mfma_f32_16x16x32_bf16 v[98:101], v[154:157], v[182:185], v[98:101]
	v_mfma_f32_16x16x32_bf16 v[86:89], v[146:149], v[206:209], v[86:89]
	v_mfma_f32_16x16x32_bf16 v[82:85], v[154:157], v[206:209], v[82:85]
	v_mfma_f32_16x16x32_bf16 v[70:73], v[146:149], v[214:217], v[70:73]
	v_mfma_f32_16x16x32_bf16 v[66:69], v[154:157], v[214:217], v[66:69]
	v_mfma_f32_16x16x32_bf16 v[118:121], v[150:153], v[178:181], v[118:121]
	v_mfma_f32_16x16x32_bf16 v[114:117], v[158:161], v[178:181], v[114:117]
	v_mfma_f32_16x16x32_bf16 v[102:105], v[150:153], v[186:189], v[102:105]
	v_mfma_f32_16x16x32_bf16 v[98:101], v[158:161], v[186:189], v[98:101]
	v_mfma_f32_16x16x32_bf16 v[86:89], v[150:153], v[210:213], v[86:89]
	v_mfma_f32_16x16x32_bf16 v[82:85], v[158:161], v[210:213], v[82:85]
	v_mfma_f32_16x16x32_bf16 v[70:73], v[150:153], v[218:221], v[70:73]
	v_mfma_f32_16x16x32_bf16 v[66:69], v[158:161], v[218:221], v[66:69]
	s_setprio 0
	s_barrier
	s_add_i32 s0, s68, s52
	v_lshl_add_u64 v[190:191], v[190:191], 0, s[80:81]
	s_mov_b32 m0, s0
	ds_read_b128 v[174:177], v199 offset:49152
	ds_read_b128 v[178:181], v199 offset:50176
	ds_read_b128 v[182:185], v199 offset:51200
	ds_read_b128 v[186:189], v199 offset:52224
	ds_read_b128 v[206:209], v199 offset:53248
	ds_read_b128 v[210:213], v199 offset:54272
	ds_read_b128 v[214:217], v199 offset:55296
	ds_read_b128 v[218:221], v199 offset:56320
	global_load_lds_dwordx4 v[190:191], off
	s_add_i32 m0, s0, 0x2000
	s_add_u32 s0, s38, 0xb0080
	v_lshl_add_u64 v[190:191], v[222:223], 0, s[80:81]
	s_addc_u32 s1, s39, 0
	s_add_i32 s38, s69, s52
	global_load_lds_dwordx4 v[190:191], off
	v_lshl_add_u64 v[190:191], s[0:1], 0, v[0:1]
	s_mov_b32 m0, s38
	s_nop 0
	global_load_lds_dwordx4 v[190:191], off
	v_lshl_add_u64 v[190:191], s[0:1], 0, v[166:167]
	s_add_i32 m0, s38, 0x2000
	s_nop 0
	global_load_lds_dwordx4 v[190:191], off
	v_lshl_add_u64 v[190:191], v[224:225], 0, s[80:81]
	s_mov_b32 m0, s59
	s_nop 0
	global_load_lds_dwordx4 v[190:191], off
	v_lshl_add_u64 v[190:191], v[226:227], 0, s[80:81]
	s_mov_b32 m0, s60
	s_nop 0
	global_load_lds_dwordx4 v[190:191], off
	s_waitcnt vmcnt(8)
	s_waitcnt lgkmcnt(0)
	s_barrier
	s_setprio 1
	s_waitcnt lgkmcnt(0)
	v_mfma_f32_16x16x32_bf16 v[62:65], v[130:133], v[174:177], v[62:65]
	v_mfma_f32_16x16x32_bf16 v[58:61], v[138:141], v[174:177], v[58:61]
	v_mfma_f32_16x16x32_bf16 v[46:49], v[130:133], v[182:185], v[46:49]
	v_mfma_f32_16x16x32_bf16 v[42:45], v[138:141], v[182:185], v[42:45]
	v_mfma_f32_16x16x32_bf16 v[30:33], v[130:133], v[206:209], v[30:33]
	v_mfma_f32_16x16x32_bf16 v[26:29], v[138:141], v[206:209], v[26:29]
	v_mfma_f32_16x16x32_bf16 v[14:17], v[130:133], v[214:217], v[14:17]
	v_mfma_f32_16x16x32_bf16 v[10:13], v[138:141], v[214:217], v[10:13]
	v_mfma_f32_16x16x32_bf16 v[62:65], v[134:137], v[178:181], v[62:65]
	v_mfma_f32_16x16x32_bf16 v[58:61], v[142:145], v[178:181], v[58:61]
	v_mfma_f32_16x16x32_bf16 v[46:49], v[134:137], v[186:189], v[46:49]
	v_mfma_f32_16x16x32_bf16 v[42:45], v[142:145], v[186:189], v[42:45]
	v_mfma_f32_16x16x32_bf16 v[30:33], v[134:137], v[210:213], v[30:33]
	v_mfma_f32_16x16x32_bf16 v[26:29], v[142:145], v[210:213], v[26:29]
	v_mfma_f32_16x16x32_bf16 v[14:17], v[134:137], v[218:221], v[14:17]
	v_mfma_f32_16x16x32_bf16 v[10:13], v[142:145], v[218:221], v[10:13]
	s_setprio 0
	s_setprio 1
	v_mfma_f32_16x16x32_bf16 v[54:57], v[146:149], v[174:177], v[54:57]
	v_mfma_f32_16x16x32_bf16 v[50:53], v[154:157], v[174:177], v[50:53]
	v_mfma_f32_16x16x32_bf16 v[38:41], v[146:149], v[182:185], v[38:41]
	v_mfma_f32_16x16x32_bf16 v[34:37], v[154:157], v[182:185], v[34:37]
	v_mfma_f32_16x16x32_bf16 v[22:25], v[146:149], v[206:209], v[22:25]
	v_mfma_f32_16x16x32_bf16 v[18:21], v[154:157], v[206:209], v[18:21]
	v_mfma_f32_16x16x32_bf16 v[6:9], v[146:149], v[214:217], v[6:9]
	v_mfma_f32_16x16x32_bf16 v[2:5], v[154:157], v[214:217], v[2:5]
	v_mfma_f32_16x16x32_bf16 v[54:57], v[150:153], v[178:181], v[54:57]
	v_mfma_f32_16x16x32_bf16 v[50:53], v[158:161], v[178:181], v[50:53]
	v_mfma_f32_16x16x32_bf16 v[38:41], v[150:153], v[186:189], v[38:41]
	v_mfma_f32_16x16x32_bf16 v[34:37], v[158:161], v[186:189], v[34:37]
	v_mfma_f32_16x16x32_bf16 v[22:25], v[150:153], v[210:213], v[22:25]
	v_mfma_f32_16x16x32_bf16 v[18:21], v[158:161], v[210:213], v[18:21]
	v_mfma_f32_16x16x32_bf16 v[6:9], v[150:153], v[218:221], v[6:9]
	v_mfma_f32_16x16x32_bf16 v[2:5], v[158:161], v[218:221], v[2:5]
	s_setprio 0
	s_barrier
	s_add_i32 s43, s43, 2
	s_add_u32 s37, s37, 0x100
	s_addc_u32 s42, s42, 0
	s_cmp_gt_u32 s43, 41
	s_mov_b64 s[0:1], s[10:11]
	s_cbranch_scc0 .LBB0_280
	s_and_b64 vcc, exec, s[20:21]
	s_cbranch_vccz .LBB0_283
	s_barrier

.LBB0_452:
	s_add_u32 s6, s4, 0xfffc0080
	s_addc_u32 s7, s5, -1
	s_add_i32 s57, 0, 0x10000
	s_cmp_eq_u32 s37, 12
	s_cselect_b32 s35, s1, s7
	s_cselect_b32 s34, s3, s6
	v_add_u32_e32 v0, s57, v176
	s_cselect_b32 s7, s23, s36
	s_cselect_b32 s6, s25, s33
	s_add_i32 s60, 0, 0x14000
	ds_read_b128 v[18:21], v0
	ds_read_b128 v[22:25], v0 offset:1024
	ds_read_b128 v[34:37], v0 offset:2048
	ds_read_b128 v[38:41], v0 offset:3072
	v_add_u32_e32 v0, s60, v176
	ds_read_b128 v[162:165], v0
	ds_read_b128 v[166:169], v0 offset:1024
	ds_read_b128 v[170:173], v0 offset:2048
	ds_read_b128 v[178:181], v0 offset:3072
	v_lshl_add_u64 v[174:175], s[4:5], 0, v[158:159]
	s_add_i32 m0, s50, 0xc000
	ds_read_b128 v[182:185], v177
	ds_read_b128 v[186:189], v177 offset:1024
	ds_read_b128 v[190:193], v177 offset:2048
	ds_read_b128 v[194:197], v177 offset:3072
	ds_read_b128 v[198:201], v177 offset:4096
	ds_read_b128 v[202:205], v177 offset:5120
	ds_read_b128 v[206:209], v177 offset:6144
	ds_read_b128 v[210:213], v177 offset:7168
	global_load_lds_dwordx4 v[174:175], off
	v_lshl_add_u64 v[174:175], s[4:5], 0, v[160:161]
	s_add_i32 m0, s50, 0xe000
	s_nop 0
	global_load_lds_dwordx4 v[174:175], off
	s_waitcnt vmcnt(8)
	s_waitcnt lgkmcnt(0)
	s_barrier
	s_setprio 1
	s_waitcnt lgkmcnt(0)
	v_mfma_f32_16x16x32_bf16 v[142:145], v[18:21], v[182:185], v[142:145]
	v_mfma_f32_16x16x32_bf16 v[138:141], v[34:37], v[182:185], v[138:141]
	v_mfma_f32_16x16x32_bf16 v[126:129], v[18:21], v[190:193], v[126:129]
	v_mfma_f32_16x16x32_bf16 v[122:125], v[34:37], v[190:193], v[122:125]
	v_mfma_f32_16x16x32_bf16 v[110:113], v[18:21], v[198:201], v[110:113]
	v_mfma_f32_16x16x32_bf16 v[106:109], v[34:37], v[198:201], v[106:109]
	v_mfma_f32_16x16x32_bf16 v[94:97], v[18:21], v[206:209], v[94:97]
	v_mfma_f32_16x16x32_bf16 v[90:93], v[34:37], v[206:209], v[90:93]
	v_mfma_f32_16x16x32_bf16 v[142:145], v[22:25], v[186:189], v[142:145]
	v_mfma_f32_16x16x32_bf16 v[138:141], v[38:41], v[186:189], v[138:141]
	v_mfma_f32_16x16x32_bf16 v[126:129], v[22:25], v[194:197], v[126:129]
	v_mfma_f32_16x16x32_bf16 v[122:125], v[38:41], v[194:197], v[122:125]
	v_mfma_f32_16x16x32_bf16 v[110:113], v[22:25], v[202:205], v[110:113]
	v_mfma_f32_16x16x32_bf16 v[106:109], v[38:41], v[202:205], v[106:109]
	v_mfma_f32_16x16x32_bf16 v[94:97], v[22:25], v[210:213], v[94:97]
	v_mfma_f32_16x16x32_bf16 v[90:93], v[38:41], v[210:213], v[90:93]
	s_setprio 0
	s_setprio 1
	v_mfma_f32_16x16x32_bf16 v[134:137], v[162:165], v[182:185], v[134:137]
	v_mfma_f32_16x16x32_bf16 v[130:133], v[170:173], v[182:185], v[130:133]
	v_mfma_f32_16x16x32_bf16 v[118:121], v[162:165], v[190:193], v[118:121]
	v_mfma_f32_16x16x32_bf16 v[114:117], v[170:173], v[190:193], v[114:117]
	v_mfma_f32_16x16x32_bf16 v[102:105], v[162:165], v[198:201], v[102:105]
	v_mfma_f32_16x16x32_bf16 v[98:101], v[170:173], v[198:201], v[98:101]
	v_mfma_f32_16x16x32_bf16 v[86:89], v[162:165], v[206:209], v[86:89]
	v_mfma_f32_16x16x32_bf16 v[82:85], v[170:173], v[206:209], v[82:85]
	v_mfma_f32_16x16x32_bf16 v[134:137], v[166:169], v[186:189], v[134:137]
	v_mfma_f32_16x16x32_bf16 v[130:133], v[178:181], v[186:189], v[130:133]
	v_mfma_f32_16x16x32_bf16 v[118:121], v[166:169], v[194:197], v[118:121]
	v_mfma_f32_16x16x32_bf16 v[114:117], v[178:181], v[194:197], v[114:117]
	v_mfma_f32_16x16x32_bf16 v[102:105], v[166:169], v[202:205], v[102:105]
	v_mfma_f32_16x16x32_bf16 v[98:101], v[178:181], v[202:205], v[98:101]
	v_mfma_f32_16x16x32_bf16 v[86:89], v[166:169], v[210:213], v[86:89]
	v_mfma_f32_16x16x32_bf16 v[82:85], v[178:181], v[210:213], v[82:85]
	s_setprio 0
	s_barrier
	s_add_i32 s57, s57, s49
	v_lshl_add_u64 v[174:175], s[6:7], 0, v[148:149]
	s_mov_b32 m0, s57
	ds_read_b128 v[182:185], v177 offset:16384
	ds_read_b128 v[186:189], v177 offset:17408
	ds_read_b128 v[190:193], v177 offset:18432
	ds_read_b128 v[194:197], v177 offset:19456
	ds_read_b128 v[198:201], v177 offset:20480
	ds_read_b128 v[202:205], v177 offset:21504
	ds_read_b128 v[206:209], v177 offset:22528
	ds_read_b128 v[210:213], v177 offset:23552
	global_load_lds_dwordx4 v[174:175], off
	s_add_i32 m0, s57, 0x2000
	s_add_u32 s58, s6, 0x40000
	v_lshl_add_u64 v[214:215], s[6:7], 0, v[152:153]
	s_addc_u32 s59, s7, 0
	s_add_i32 s57, s60, s49
	global_load_lds_dwordx4 v[214:215], off
	v_lshl_add_u64 v[216:217], s[58:59], 0, v[148:149]
	s_mov_b32 m0, s57
	v_lshl_add_u64 v[218:219], s[34:35], 0, v[150:151]
	global_load_lds_dwordx4 v[216:217], off
	v_lshl_add_u64 v[216:217], s[58:59], 0, v[152:153]
	s_add_i32 m0, s57, 0x2000
	s_nop 0
	global_load_lds_dwordx4 v[216:217], off
	s_waitcnt vmcnt(6)
	s_waitcnt lgkmcnt(0)
	s_barrier
	s_setprio 1
	s_waitcnt lgkmcnt(0)
	v_mfma_f32_16x16x32_bf16 v[78:81], v[18:21], v[182:185], v[78:81]
	v_mfma_f32_16x16x32_bf16 v[74:77], v[34:37], v[182:185], v[74:77]
	v_mfma_f32_16x16x32_bf16 v[62:65], v[18:21], v[190:193], v[62:65]
	v_mfma_f32_16x16x32_bf16 v[58:61], v[34:37], v[190:193], v[58:61]
	v_mfma_f32_16x16x32_bf16 v[46:49], v[18:21], v[198:201], v[46:49]
	v_mfma_f32_16x16x32_bf16 v[42:45], v[34:37], v[198:201], v[42:45]
	v_mfma_f32_16x16x32_bf16 v[14:17], v[18:21], v[206:209], v[14:17]
	v_mfma_f32_16x16x32_bf16 v[10:13], v[34:37], v[206:209], v[10:13]
	v_mfma_f32_16x16x32_bf16 v[78:81], v[22:25], v[186:189], v[78:81]
	v_mfma_f32_16x16x32_bf16 v[74:77], v[38:41], v[186:189], v[74:77]
	v_mfma_f32_16x16x32_bf16 v[62:65], v[22:25], v[194:197], v[62:65]
	v_mfma_f32_16x16x32_bf16 v[58:61], v[38:41], v[194:197], v[58:61]
	v_mfma_f32_16x16x32_bf16 v[46:49], v[22:25], v[202:205], v[46:49]
	v_mfma_f32_16x16x32_bf16 v[42:45], v[38:41], v[202:205], v[42:45]
	v_mfma_f32_16x16x32_bf16 v[14:17], v[22:25], v[210:213], v[14:17]
	v_mfma_f32_16x16x32_bf16 v[10:13], v[38:41], v[210:213], v[10:13]
	s_setprio 0
	s_setprio 1
	v_mfma_f32_16x16x32_bf16 v[30:33], v[162:165], v[198:201], v[30:33]
	v_mfma_f32_16x16x32_bf16 v[26:29], v[170:173], v[198:201], v[26:29]
	v_mfma_f32_16x16x32_bf16 v[6:9], v[162:165], v[206:209], v[6:9]
	v_mfma_f32_16x16x32_bf16 v[2:5], v[170:173], v[206:209], v[2:5]
	v_mfma_f32_16x16x32_bf16 v[18:21], v[162:165], v[182:185], v[70:73]
	v_mfma_f32_16x16x32_bf16 v[22:25], v[170:173], v[182:185], v[66:69]
	v_mfma_f32_16x16x32_bf16 v[34:37], v[162:165], v[190:193], v[54:57]
	v_mfma_f32_16x16x32_bf16 v[38:41], v[170:173], v[190:193], v[50:53]
	v_mfma_f32_16x16x32_bf16 v[30:33], v[166:169], v[202:205], v[30:33]
	v_mfma_f32_16x16x32_bf16 v[26:29], v[178:181], v[202:205], v[26:29]
	v_mfma_f32_16x16x32_bf16 v[6:9], v[166:169], v[210:213], v[6:9]
	v_mfma_f32_16x16x32_bf16 v[2:5], v[178:181], v[210:213], v[2:5]
	v_mfma_f32_16x16x32_bf16 v[18:21], v[166:169], v[186:189], v[18:21]
	v_mfma_f32_16x16x32_bf16 v[22:25], v[178:181], v[186:189], v[22:25]
	v_mfma_f32_16x16x32_bf16 v[34:37], v[166:169], v[194:197], v[34:37]
	v_mfma_f32_16x16x32_bf16 v[38:41], v[178:181], v[194:197], v[38:41]
	s_setprio 0
	s_barrier
	s_add_i32 s57, 0, 0x18000
	v_add_u32_e32 v0, s57, v176
	s_add_i32 s58, 0, 0x1c000
	ds_read_b128 v[50:53], v0
	ds_read_b128 v[54:57], v0 offset:1024
	ds_read_b128 v[66:69], v0 offset:2048
	ds_read_b128 v[70:73], v0 offset:3072
	v_add_u32_e32 v0, s58, v176
	ds_read_b128 v[162:165], v0
	ds_read_b128 v[166:169], v0 offset:1024
	ds_read_b128 v[170:173], v0 offset:2048
	ds_read_b128 v[178:181], v0 offset:3072
	v_lshl_add_u64 v[216:217], s[34:35], 0, v[146:147]
	s_mov_b32 m0, s50
	s_nop 0
	global_load_lds_dwordx4 v[216:217], off
	s_mov_b32 m0, s51
	s_nop 0
	global_load_lds_dwordx4 v[218:219], off
	s_add_u32 s34, s34, 0x40000
	s_addc_u32 s35, s35, 0
	s_mov_b32 m0, s52
	v_lshl_add_u64 v[220:221], s[34:35], 0, v[146:147]
	ds_read_b128 v[182:185], v177 offset:32768
	ds_read_b128 v[186:189], v177 offset:33792
	ds_read_b128 v[190:193], v177 offset:34816
	ds_read_b128 v[194:197], v177 offset:35840
	ds_read_b128 v[198:201], v177 offset:36864
	ds_read_b128 v[202:205], v177 offset:37888
	ds_read_b128 v[206:209], v177 offset:38912
	ds_read_b128 v[210:213], v177 offset:39936
	global_load_lds_dwordx4 v[220:221], off
	v_lshl_add_u64 v[220:221], s[34:35], 0, v[150:151]
	s_mov_b32 m0, s53
	s_nop 0
	global_load_lds_dwordx4 v[220:221], off
	s_waitcnt vmcnt(8)
	s_waitcnt lgkmcnt(0)
	s_barrier
	s_setprio 1
	s_waitcnt lgkmcnt(0)
	v_mfma_f32_16x16x32_bf16 v[142:145], v[50:53], v[182:185], v[142:145]
	v_mfma_f32_16x16x32_bf16 v[138:141], v[66:69], v[182:185], v[138:141]
	v_mfma_f32_16x16x32_bf16 v[126:129], v[50:53], v[190:193], v[126:129]
	v_mfma_f32_16x16x32_bf16 v[122:125], v[66:69], v[190:193], v[122:125]
	v_mfma_f32_16x16x32_bf16 v[110:113], v[50:53], v[198:201], v[110:113]
	v_mfma_f32_16x16x32_bf16 v[106:109], v[66:69], v[198:201], v[106:109]
	v_mfma_f32_16x16x32_bf16 v[94:97], v[50:53], v[206:209], v[94:97]
	v_mfma_f32_16x16x32_bf16 v[90:93], v[66:69], v[206:209], v[90:93]
	v_mfma_f32_16x16x32_bf16 v[142:145], v[54:57], v[186:189], v[142:145]
	v_mfma_f32_16x16x32_bf16 v[138:141], v[70:73], v[186:189], v[138:141]
	v_mfma_f32_16x16x32_bf16 v[126:129], v[54:57], v[194:197], v[126:129]
	v_mfma_f32_16x16x32_bf16 v[122:125], v[70:73], v[194:197], v[122:125]
	v_mfma_f32_16x16x32_bf16 v[110:113], v[54:57], v[202:205], v[110:113]
	v_mfma_f32_16x16x32_bf16 v[106:109], v[70:73], v[202:205], v[106:109]
	v_mfma_f32_16x16x32_bf16 v[94:97], v[54:57], v[210:213], v[94:97]
	v_mfma_f32_16x16x32_bf16 v[90:93], v[70:73], v[210:213], v[90:93]
	s_setprio 0
	s_setprio 1
	v_mfma_f32_16x16x32_bf16 v[134:137], v[162:165], v[182:185], v[134:137]
	v_mfma_f32_16x16x32_bf16 v[130:133], v[170:173], v[182:185], v[130:133]
	v_mfma_f32_16x16x32_bf16 v[118:121], v[162:165], v[190:193], v[118:121]
	v_mfma_f32_16x16x32_bf16 v[114:117], v[170:173], v[190:193], v[114:117]
	v_mfma_f32_16x16x32_bf16 v[102:105], v[162:165], v[198:201], v[102:105]
	v_mfma_f32_16x16x32_bf16 v[98:101], v[170:173], v[198:201], v[98:101]
	v_mfma_f32_16x16x32_bf16 v[86:89], v[162:165], v[206:209], v[86:89]
	v_mfma_f32_16x16x32_bf16 v[82:85], v[170:173], v[206:209], v[82:85]
	v_mfma_f32_16x16x32_bf16 v[134:137], v[166:169], v[186:189], v[134:137]
	v_mfma_f32_16x16x32_bf16 v[130:133], v[178:181], v[186:189], v[130:133]
	v_mfma_f32_16x16x32_bf16 v[118:121], v[166:169], v[194:197], v[118:121]
	v_mfma_f32_16x16x32_bf16 v[114:117], v[178:181], v[194:197], v[114:117]
	v_mfma_f32_16x16x32_bf16 v[102:105], v[166:169], v[202:205], v[102:105]
	v_mfma_f32_16x16x32_bf16 v[98:101], v[178:181], v[202:205], v[98:101]
	v_mfma_f32_16x16x32_bf16 v[86:89], v[166:169], v[210:213], v[86:89]
	v_mfma_f32_16x16x32_bf16 v[82:85], v[178:181], v[210:213], v[82:85]
	s_setprio 0
	s_barrier
	s_add_i32 s34, s57, s49
	v_lshl_add_u64 v[174:175], v[174:175], 0, s[80:81]
	s_mov_b32 m0, s34
	ds_read_b128 v[182:185], v177 offset:49152
	ds_read_b128 v[186:189], v177 offset:50176
	ds_read_b128 v[190:193], v177 offset:51200
	ds_read_b128 v[194:197], v177 offset:52224
	ds_read_b128 v[198:201], v177 offset:53248
	ds_read_b128 v[202:205], v177 offset:54272
	ds_read_b128 v[206:209], v177 offset:55296
	ds_read_b128 v[210:213], v177 offset:56320
	global_load_lds_dwordx4 v[174:175], off
	s_add_i32 m0, s34, 0x2000
	s_add_u32 s6, s6, 0x40080
	v_lshl_add_u64 v[174:175], v[214:215], 0, s[80:81]
	s_addc_u32 s7, s7, 0
	s_add_i32 s34, s58, s49
	global_load_lds_dwordx4 v[174:175], off
	v_lshl_add_u64 v[174:175], s[6:7], 0, v[148:149]
	s_mov_b32 m0, s34
	s_nop 0
	global_load_lds_dwordx4 v[174:175], off
	v_lshl_add_u64 v[174:175], s[6:7], 0, v[152:153]
	s_add_i32 m0, s34, 0x2000
	s_nop 0
	global_load_lds_dwordx4 v[174:175], off
	v_lshl_add_u64 v[174:175], v[216:217], 0, s[80:81]
	s_mov_b32 m0, s54
	s_nop 0
	global_load_lds_dwordx4 v[174:175], off
	v_lshl_add_u64 v[174:175], v[218:219], 0, s[80:81]
	s_mov_b32 m0, s55
	s_nop 0
	global_load_lds_dwordx4 v[174:175], off
	s_waitcnt vmcnt(8)
	s_waitcnt lgkmcnt(0)
	s_barrier
	s_setprio 1
	s_waitcnt lgkmcnt(0)
	v_mfma_f32_16x16x32_bf16 v[78:81], v[50:53], v[182:185], v[78:81]
	v_mfma_f32_16x16x32_bf16 v[74:77], v[66:69], v[182:185], v[74:77]
	v_mfma_f32_16x16x32_bf16 v[62:65], v[50:53], v[190:193], v[62:65]
	v_mfma_f32_16x16x32_bf16 v[58:61], v[66:69], v[190:193], v[58:61]
	v_mfma_f32_16x16x32_bf16 v[46:49], v[50:53], v[198:201], v[46:49]
	v_mfma_f32_16x16x32_bf16 v[42:45], v[66:69], v[198:201], v[42:45]
	v_mfma_f32_16x16x32_bf16 v[14:17], v[50:53], v[206:209], v[14:17]
	v_mfma_f32_16x16x32_bf16 v[10:13], v[66:69], v[206:209], v[10:13]
	v_mfma_f32_16x16x32_bf16 v[78:81], v[54:57], v[186:189], v[78:81]
	v_mfma_f32_16x16x32_bf16 v[74:77], v[70:73], v[186:189], v[74:77]
	v_mfma_f32_16x16x32_bf16 v[62:65], v[54:57], v[194:197], v[62:65]
	v_mfma_f32_16x16x32_bf16 v[58:61], v[70:73], v[194:197], v[58:61]
	v_mfma_f32_16x16x32_bf16 v[46:49], v[54:57], v[202:205], v[46:49]
	v_mfma_f32_16x16x32_bf16 v[42:45], v[70:73], v[202:205], v[42:45]
	v_mfma_f32_16x16x32_bf16 v[14:17], v[54:57], v[210:213], v[14:17]
	v_mfma_f32_16x16x32_bf16 v[10:13], v[70:73], v[210:213], v[10:13]
	s_setprio 0
	s_setprio 1
	v_mfma_f32_16x16x32_bf16 v[18:21], v[162:165], v[182:185], v[18:21]
	v_mfma_f32_16x16x32_bf16 v[70:73], v[166:169], v[186:189], v[18:21]
	v_mfma_f32_16x16x32_bf16 v[18:21], v[170:173], v[182:185], v[22:25]
	v_mfma_f32_16x16x32_bf16 v[66:69], v[178:181], v[186:189], v[18:21]
	v_mfma_f32_16x16x32_bf16 v[18:21], v[162:165], v[190:193], v[34:37]
	v_mfma_f32_16x16x32_bf16 v[54:57], v[166:169], v[194:197], v[18:21]
	v_mfma_f32_16x16x32_bf16 v[18:21], v[170:173], v[190:193], v[38:41]
	v_mfma_f32_16x16x32_bf16 v[50:53], v[178:181], v[194:197], v[18:21]
	v_mfma_f32_16x16x32_bf16 v[18:21], v[162:165], v[198:201], v[30:33]
	v_mfma_f32_16x16x32_bf16 v[30:33], v[166:169], v[202:205], v[18:21]
	v_mfma_f32_16x16x32_bf16 v[18:21], v[170:173], v[198:201], v[26:29]
	v_mfma_f32_16x16x32_bf16 v[6:9], v[162:165], v[206:209], v[6:9]
	v_mfma_f32_16x16x32_bf16 v[2:5], v[170:173], v[206:209], v[2:5]
	v_mfma_f32_16x16x32_bf16 v[26:29], v[178:181], v[202:205], v[18:21]
	v_mfma_f32_16x16x32_bf16 v[6:9], v[166:169], v[210:213], v[6:9]
	v_mfma_f32_16x16x32_bf16 v[2:5], v[178:181], v[210:213], v[2:5]
	s_setprio 0
	s_barrier
	s_add_i32 s37, s37, 2
	s_add_u32 s4, s4, 0x100
	s_addc_u32 s5, s5, 0
	s_add_u32 s33, s33, 0x100
	s_addc_u32 s36, s36, 0
	s_cmp_gt_u32 s37, 13
	s_cbranch_scc0 .LBB0_452
	s_and_b64 vcc, exec, s[18:19]
	s_cbranch_vccz .LBB0_455
	s_barrier

.LBB0_853:
	s_add_u32 s24, s22, 0xfffc0080
	s_addc_u32 s25, s23, -1
	s_add_i32 s51, 0, 0x10000
	s_cmp_eq_u32 s50, 12
	s_cselect_b32 s27, s7, s25
	s_cselect_b32 s26, s19, s24
	s_cselect_b32 s25, s9, s49
	s_cselect_b32 s24, s45, s48
	s_add_i32 s54, 0, 0x14000
	v_add_u32_e32 v158, s51, v143
	v_add_u32_e32 v174, s54, v143
	ds_read_b128 v[146:149], v158
	ds_read_b128 v[150:153], v158 offset:1024
	ds_read_b128 v[154:157], v158 offset:2048
	ds_read_b128 v[158:161], v158 offset:3072
	ds_read_b128 v[162:165], v174
	ds_read_b128 v[166:169], v174 offset:1024
	ds_read_b128 v[170:173], v174 offset:2048
	ds_read_b128 v[174:177], v174 offset:3072
	v_lshl_add_u64 v[178:179], s[22:23], 0, v[136:137]
	s_add_i32 m0, s21, 0xc000
	ds_read_b128 v[182:185], v145
	ds_read_b128 v[186:189], v145 offset:1024
	ds_read_b128 v[190:193], v145 offset:2048
	ds_read_b128 v[194:197], v145 offset:3072
	ds_read_b128 v[198:201], v145 offset:4096
	ds_read_b128 v[202:205], v145 offset:5120
	ds_read_b128 v[206:209], v145 offset:6144
	ds_read_b128 v[210:213], v145 offset:7168
	global_load_lds_dwordx4 v[178:179], off
	v_lshl_add_u64 v[178:179], s[22:23], 0, v[138:139]
	s_add_i32 m0, s21, 0xe000
	s_nop 0
	global_load_lds_dwordx4 v[178:179], off
	s_waitcnt vmcnt(8)
	s_waitcnt lgkmcnt(0)
	s_barrier
	s_setprio 1
	s_waitcnt lgkmcnt(0)
	v_mfma_f32_16x16x32_bf16 v[126:129], v[146:149], v[182:185], v[126:129]
	v_mfma_f32_16x16x32_bf16 v[118:121], v[154:157], v[182:185], v[118:121]
	v_mfma_f32_16x16x32_bf16 v[110:113], v[146:149], v[190:193], v[110:113]
	v_mfma_f32_16x16x32_bf16 v[102:105], v[154:157], v[190:193], v[102:105]
	v_mfma_f32_16x16x32_bf16 v[94:97], v[146:149], v[198:201], v[94:97]
	v_mfma_f32_16x16x32_bf16 v[86:89], v[154:157], v[198:201], v[86:89]
	v_mfma_f32_16x16x32_bf16 v[78:81], v[146:149], v[206:209], v[78:81]
	v_mfma_f32_16x16x32_bf16 v[70:73], v[154:157], v[206:209], v[70:73]
	v_mfma_f32_16x16x32_bf16 v[126:129], v[150:153], v[186:189], v[126:129]
	v_mfma_f32_16x16x32_bf16 v[118:121], v[158:161], v[186:189], v[118:121]
	v_mfma_f32_16x16x32_bf16 v[110:113], v[150:153], v[194:197], v[110:113]
	v_mfma_f32_16x16x32_bf16 v[102:105], v[158:161], v[194:197], v[102:105]
	v_mfma_f32_16x16x32_bf16 v[94:97], v[150:153], v[202:205], v[94:97]
	v_mfma_f32_16x16x32_bf16 v[86:89], v[158:161], v[202:205], v[86:89]
	v_mfma_f32_16x16x32_bf16 v[78:81], v[150:153], v[210:213], v[78:81]
	v_mfma_f32_16x16x32_bf16 v[70:73], v[158:161], v[210:213], v[70:73]
	s_setprio 0
	s_setprio 1
	v_mfma_f32_16x16x32_bf16 v[122:125], v[162:165], v[182:185], v[122:125]
	v_mfma_f32_16x16x32_bf16 v[114:117], v[170:173], v[182:185], v[114:117]
	v_mfma_f32_16x16x32_bf16 v[106:109], v[162:165], v[190:193], v[106:109]
	v_mfma_f32_16x16x32_bf16 v[98:101], v[170:173], v[190:193], v[98:101]
	v_mfma_f32_16x16x32_bf16 v[90:93], v[162:165], v[198:201], v[90:93]
	v_mfma_f32_16x16x32_bf16 v[82:85], v[170:173], v[198:201], v[82:85]
	v_mfma_f32_16x16x32_bf16 v[74:77], v[162:165], v[206:209], v[74:77]
	v_mfma_f32_16x16x32_bf16 v[66:69], v[170:173], v[206:209], v[66:69]
	v_mfma_f32_16x16x32_bf16 v[122:125], v[166:169], v[186:189], v[122:125]
	v_mfma_f32_16x16x32_bf16 v[114:117], v[174:177], v[186:189], v[114:117]
	v_mfma_f32_16x16x32_bf16 v[106:109], v[166:169], v[194:197], v[106:109]
	v_mfma_f32_16x16x32_bf16 v[98:101], v[174:177], v[194:197], v[98:101]
	v_mfma_f32_16x16x32_bf16 v[90:93], v[166:169], v[202:205], v[90:93]
	v_mfma_f32_16x16x32_bf16 v[82:85], v[174:177], v[202:205], v[82:85]
	v_mfma_f32_16x16x32_bf16 v[74:77], v[166:169], v[210:213], v[74:77]
	v_mfma_f32_16x16x32_bf16 v[66:69], v[174:177], v[210:213], v[66:69]
	s_setprio 0
	s_barrier
	s_add_i32 s51, s51, s34
	v_lshl_add_u64 v[178:179], s[24:25], 0, v[0:1]
	s_mov_b32 m0, s51
	ds_read_b128 v[182:185], v145 offset:16384
	ds_read_b128 v[186:189], v145 offset:17408
	ds_read_b128 v[190:193], v145 offset:18432
	ds_read_b128 v[194:197], v145 offset:19456
	ds_read_b128 v[198:201], v145 offset:20480
	ds_read_b128 v[202:205], v145 offset:21504
	ds_read_b128 v[206:209], v145 offset:22528
	ds_read_b128 v[210:213], v145 offset:23552
	global_load_lds_dwordx4 v[178:179], off
	s_add_i32 m0, s51, 0x2000
	s_add_u32 s52, s24, 0x40000
	v_lshl_add_u64 v[214:215], s[24:25], 0, v[130:131]
	s_addc_u32 s53, s25, 0
	s_add_i32 s51, s54, s34
	global_load_lds_dwordx4 v[214:215], off
	v_lshl_add_u64 v[216:217], s[52:53], 0, v[0:1]
	s_mov_b32 m0, s51
	v_lshl_add_u64 v[218:219], s[26:27], 0, v[132:133]
	global_load_lds_dwordx4 v[216:217], off
	v_lshl_add_u64 v[216:217], s[52:53], 0, v[130:131]
	s_add_i32 m0, s51, 0x2000
	s_nop 0
	global_load_lds_dwordx4 v[216:217], off
	s_waitcnt vmcnt(6)
	s_waitcnt lgkmcnt(0)
	s_barrier
	s_setprio 1
	s_waitcnt lgkmcnt(0)
	v_mfma_f32_16x16x32_bf16 v[62:65], v[146:149], v[182:185], v[62:65]
	v_mfma_f32_16x16x32_bf16 v[54:57], v[154:157], v[182:185], v[54:57]
	v_mfma_f32_16x16x32_bf16 v[46:49], v[146:149], v[190:193], v[46:49]
	v_mfma_f32_16x16x32_bf16 v[38:41], v[154:157], v[190:193], v[38:41]
	v_mfma_f32_16x16x32_bf16 v[30:33], v[146:149], v[198:201], v[30:33]
	v_mfma_f32_16x16x32_bf16 v[22:25], v[154:157], v[198:201], v[22:25]
	v_mfma_f32_16x16x32_bf16 v[14:17], v[146:149], v[206:209], v[14:17]
	v_mfma_f32_16x16x32_bf16 v[6:9], v[154:157], v[206:209], v[6:9]
	v_mfma_f32_16x16x32_bf16 v[62:65], v[150:153], v[186:189], v[62:65]
	v_mfma_f32_16x16x32_bf16 v[54:57], v[158:161], v[186:189], v[54:57]
	v_mfma_f32_16x16x32_bf16 v[46:49], v[150:153], v[194:197], v[46:49]
	v_mfma_f32_16x16x32_bf16 v[38:41], v[158:161], v[194:197], v[38:41]
	v_mfma_f32_16x16x32_bf16 v[30:33], v[150:153], v[202:205], v[30:33]
	v_mfma_f32_16x16x32_bf16 v[22:25], v[158:161], v[202:205], v[22:25]
	v_mfma_f32_16x16x32_bf16 v[14:17], v[150:153], v[210:213], v[14:17]
	v_mfma_f32_16x16x32_bf16 v[6:9], v[158:161], v[210:213], v[6:9]
	s_setprio 0
	s_setprio 1
	v_mfma_f32_16x16x32_bf16 v[58:61], v[162:165], v[182:185], v[58:61]
	v_mfma_f32_16x16x32_bf16 v[50:53], v[170:173], v[182:185], v[50:53]
	v_mfma_f32_16x16x32_bf16 v[42:45], v[162:165], v[190:193], v[42:45]
	v_mfma_f32_16x16x32_bf16 v[34:37], v[170:173], v[190:193], v[34:37]
	v_mfma_f32_16x16x32_bf16 v[26:29], v[162:165], v[198:201], v[26:29]
	v_mfma_f32_16x16x32_bf16 v[18:21], v[170:173], v[198:201], v[18:21]
	v_mfma_f32_16x16x32_bf16 v[10:13], v[162:165], v[206:209], v[10:13]
	v_mfma_f32_16x16x32_bf16 v[2:5], v[170:173], v[206:209], v[2:5]
	v_mfma_f32_16x16x32_bf16 v[58:61], v[166:169], v[186:189], v[58:61]
	v_mfma_f32_16x16x32_bf16 v[50:53], v[174:177], v[186:189], v[50:53]
	v_mfma_f32_16x16x32_bf16 v[42:45], v[166:169], v[194:197], v[42:45]
	v_mfma_f32_16x16x32_bf16 v[34:37], v[174:177], v[194:197], v[34:37]
	v_mfma_f32_16x16x32_bf16 v[26:29], v[166:169], v[202:205], v[26:29]
	v_mfma_f32_16x16x32_bf16 v[18:21], v[174:177], v[202:205], v[18:21]
	v_mfma_f32_16x16x32_bf16 v[10:13], v[166:169], v[210:213], v[10:13]
	v_mfma_f32_16x16x32_bf16 v[2:5], v[174:177], v[210:213], v[2:5]
	s_setprio 0
	s_barrier
	s_add_i32 s51, 0, 0x18000
	s_add_i32 s52, 0, 0x1c000
	v_add_u32_e32 v158, s51, v143
	v_add_u32_e32 v174, s52, v143
	ds_read_b128 v[146:149], v158
	ds_read_b128 v[150:153], v158 offset:1024
	ds_read_b128 v[154:157], v158 offset:2048
	ds_read_b128 v[158:161], v158 offset:3072
	ds_read_b128 v[162:165], v174
	ds_read_b128 v[166:169], v174 offset:1024
	ds_read_b128 v[170:173], v174 offset:2048
	ds_read_b128 v[174:177], v174 offset:3072
	v_lshl_add_u64 v[216:217], s[26:27], 0, v[134:135]
	s_mov_b32 m0, s21
	s_nop 0
	global_load_lds_dwordx4 v[216:217], off
	s_mov_b32 m0, s35
	s_nop 0
	global_load_lds_dwordx4 v[218:219], off
	s_add_u32 s26, s26, 0x40000
	s_addc_u32 s27, s27, 0
	s_mov_b32 m0, s40
	v_lshl_add_u64 v[220:221], s[26:27], 0, v[134:135]
	ds_read_b128 v[182:185], v145 offset:32768
	ds_read_b128 v[186:189], v145 offset:33792
	ds_read_b128 v[190:193], v145 offset:34816
	ds_read_b128 v[194:197], v145 offset:35840
	ds_read_b128 v[198:201], v145 offset:36864
	ds_read_b128 v[202:205], v145 offset:37888
	ds_read_b128 v[206:209], v145 offset:38912
	ds_read_b128 v[210:213], v145 offset:39936
	global_load_lds_dwordx4 v[220:221], off
	v_lshl_add_u64 v[220:221], s[26:27], 0, v[132:133]
	s_mov_b32 m0, s41
	s_nop 0
	global_load_lds_dwordx4 v[220:221], off
	s_waitcnt vmcnt(8)
	s_waitcnt lgkmcnt(0)
	s_barrier
	s_setprio 1
	s_waitcnt lgkmcnt(0)
	v_mfma_f32_16x16x32_bf16 v[126:129], v[146:149], v[182:185], v[126:129]
	v_mfma_f32_16x16x32_bf16 v[118:121], v[154:157], v[182:185], v[118:121]
	v_mfma_f32_16x16x32_bf16 v[110:113], v[146:149], v[190:193], v[110:113]
	v_mfma_f32_16x16x32_bf16 v[102:105], v[154:157], v[190:193], v[102:105]
	v_mfma_f32_16x16x32_bf16 v[94:97], v[146:149], v[198:201], v[94:97]
	v_mfma_f32_16x16x32_bf16 v[86:89], v[154:157], v[198:201], v[86:89]
	v_mfma_f32_16x16x32_bf16 v[78:81], v[146:149], v[206:209], v[78:81]
	v_mfma_f32_16x16x32_bf16 v[70:73], v[154:157], v[206:209], v[70:73]
	v_mfma_f32_16x16x32_bf16 v[126:129], v[150:153], v[186:189], v[126:129]
	v_mfma_f32_16x16x32_bf16 v[118:121], v[158:161], v[186:189], v[118:121]
	v_mfma_f32_16x16x32_bf16 v[110:113], v[150:153], v[194:197], v[110:113]
	v_mfma_f32_16x16x32_bf16 v[102:105], v[158:161], v[194:197], v[102:105]
	v_mfma_f32_16x16x32_bf16 v[94:97], v[150:153], v[202:205], v[94:97]
	v_mfma_f32_16x16x32_bf16 v[86:89], v[158:161], v[202:205], v[86:89]
	v_mfma_f32_16x16x32_bf16 v[78:81], v[150:153], v[210:213], v[78:81]
	v_mfma_f32_16x16x32_bf16 v[70:73], v[158:161], v[210:213], v[70:73]
	s_setprio 0
	s_setprio 1
	v_mfma_f32_16x16x32_bf16 v[122:125], v[162:165], v[182:185], v[122:125]
	v_mfma_f32_16x16x32_bf16 v[114:117], v[170:173], v[182:185], v[114:117]
	v_mfma_f32_16x16x32_bf16 v[106:109], v[162:165], v[190:193], v[106:109]
	v_mfma_f32_16x16x32_bf16 v[98:101], v[170:173], v[190:193], v[98:101]
	v_mfma_f32_16x16x32_bf16 v[90:93], v[162:165], v[198:201], v[90:93]
	v_mfma_f32_16x16x32_bf16 v[82:85], v[170:173], v[198:201], v[82:85]
	v_mfma_f32_16x16x32_bf16 v[74:77], v[162:165], v[206:209], v[74:77]
	v_mfma_f32_16x16x32_bf16 v[66:69], v[170:173], v[206:209], v[66:69]
	v_mfma_f32_16x16x32_bf16 v[122:125], v[166:169], v[186:189], v[122:125]
	v_mfma_f32_16x16x32_bf16 v[114:117], v[174:177], v[186:189], v[114:117]
	v_mfma_f32_16x16x32_bf16 v[106:109], v[166:169], v[194:197], v[106:109]
	v_mfma_f32_16x16x32_bf16 v[98:101], v[174:177], v[194:197], v[98:101]
	v_mfma_f32_16x16x32_bf16 v[90:93], v[166:169], v[202:205], v[90:93]
	v_mfma_f32_16x16x32_bf16 v[82:85], v[174:177], v[202:205], v[82:85]
	v_mfma_f32_16x16x32_bf16 v[74:77], v[166:169], v[210:213], v[74:77]
	v_mfma_f32_16x16x32_bf16 v[66:69], v[174:177], v[210:213], v[66:69]
	s_setprio 0
	s_barrier
	s_add_i32 s26, s51, s34
	v_lshl_add_u64 v[178:179], v[178:179], 0, s[80:81]
	s_mov_b32 m0, s26
	ds_read_b128 v[182:185], v145 offset:49152
	ds_read_b128 v[186:189], v145 offset:50176
	ds_read_b128 v[190:193], v145 offset:51200
	ds_read_b128 v[194:197], v145 offset:52224
	ds_read_b128 v[198:201], v145 offset:53248
	ds_read_b128 v[202:205], v145 offset:54272
	ds_read_b128 v[206:209], v145 offset:55296
	ds_read_b128 v[210:213], v145 offset:56320
	global_load_lds_dwordx4 v[178:179], off
	s_add_i32 m0, s26, 0x2000
	s_add_u32 s24, s24, 0x40080
	v_lshl_add_u64 v[178:179], v[214:215], 0, s[80:81]
	s_addc_u32 s25, s25, 0
	s_add_i32 s26, s52, s34
	global_load_lds_dwordx4 v[178:179], off
	v_lshl_add_u64 v[178:179], s[24:25], 0, v[0:1]
	s_mov_b32 m0, s26
	s_nop 0
	global_load_lds_dwordx4 v[178:179], off
	v_lshl_add_u64 v[178:179], s[24:25], 0, v[130:131]
	s_add_i32 m0, s26, 0x2000
	s_nop 0
	global_load_lds_dwordx4 v[178:179], off
	v_lshl_add_u64 v[178:179], v[216:217], 0, s[80:81]
	s_mov_b32 m0, s42
	s_nop 0
	global_load_lds_dwordx4 v[178:179], off
	v_lshl_add_u64 v[178:179], v[218:219], 0, s[80:81]
	s_mov_b32 m0, s43
	s_nop 0
	global_load_lds_dwordx4 v[178:179], off
	s_waitcnt vmcnt(8)
	s_waitcnt lgkmcnt(0)
	s_barrier
	s_setprio 1
	s_waitcnt lgkmcnt(0)
	v_mfma_f32_16x16x32_bf16 v[62:65], v[146:149], v[182:185], v[62:65]
	v_mfma_f32_16x16x32_bf16 v[54:57], v[154:157], v[182:185], v[54:57]
	v_mfma_f32_16x16x32_bf16 v[46:49], v[146:149], v[190:193], v[46:49]
	v_mfma_f32_16x16x32_bf16 v[38:41], v[154:157], v[190:193], v[38:41]
	v_mfma_f32_16x16x32_bf16 v[30:33], v[146:149], v[198:201], v[30:33]
	v_mfma_f32_16x16x32_bf16 v[22:25], v[154:157], v[198:201], v[22:25]
	v_mfma_f32_16x16x32_bf16 v[14:17], v[146:149], v[206:209], v[14:17]
	v_mfma_f32_16x16x32_bf16 v[6:9], v[154:157], v[206:209], v[6:9]
	v_mfma_f32_16x16x32_bf16 v[62:65], v[150:153], v[186:189], v[62:65]
	v_mfma_f32_16x16x32_bf16 v[54:57], v[158:161], v[186:189], v[54:57]
	v_mfma_f32_16x16x32_bf16 v[46:49], v[150:153], v[194:197], v[46:49]
	v_mfma_f32_16x16x32_bf16 v[38:41], v[158:161], v[194:197], v[38:41]
	v_mfma_f32_16x16x32_bf16 v[30:33], v[150:153], v[202:205], v[30:33]
	v_mfma_f32_16x16x32_bf16 v[22:25], v[158:161], v[202:205], v[22:25]
	v_mfma_f32_16x16x32_bf16 v[14:17], v[150:153], v[210:213], v[14:17]
	v_mfma_f32_16x16x32_bf16 v[6:9], v[158:161], v[210:213], v[6:9]
	s_setprio 0
	s_setprio 1
	v_mfma_f32_16x16x32_bf16 v[58:61], v[162:165], v[182:185], v[58:61]
	v_mfma_f32_16x16x32_bf16 v[50:53], v[170:173], v[182:185], v[50:53]
	v_mfma_f32_16x16x32_bf16 v[42:45], v[162:165], v[190:193], v[42:45]
	v_mfma_f32_16x16x32_bf16 v[34:37], v[170:173], v[190:193], v[34:37]
	v_mfma_f32_16x16x32_bf16 v[26:29], v[162:165], v[198:201], v[26:29]
	v_mfma_f32_16x16x32_bf16 v[18:21], v[170:173], v[198:201], v[18:21]
	v_mfma_f32_16x16x32_bf16 v[10:13], v[162:165], v[206:209], v[10:13]
	v_mfma_f32_16x16x32_bf16 v[2:5], v[170:173], v[206:209], v[2:5]
	v_mfma_f32_16x16x32_bf16 v[58:61], v[166:169], v[186:189], v[58:61]
	v_mfma_f32_16x16x32_bf16 v[50:53], v[174:177], v[186:189], v[50:53]
	v_mfma_f32_16x16x32_bf16 v[42:45], v[166:169], v[194:197], v[42:45]
	v_mfma_f32_16x16x32_bf16 v[34:37], v[174:177], v[194:197], v[34:37]
	v_mfma_f32_16x16x32_bf16 v[26:29], v[166:169], v[202:205], v[26:29]
	v_mfma_f32_16x16x32_bf16 v[18:21], v[174:177], v[202:205], v[18:21]
	v_mfma_f32_16x16x32_bf16 v[10:13], v[166:169], v[210:213], v[10:13]
	v_mfma_f32_16x16x32_bf16 v[2:5], v[174:177], v[210:213], v[2:5]
	s_setprio 0
	s_barrier
	s_add_i32 s50, s50, 2
	s_add_u32 s22, s22, 0x100
	s_addc_u32 s23, s23, 0
	s_add_u32 s48, s48, 0x100
	s_addc_u32 s49, s49, 0
	s_cmp_gt_u32 s50, 13
	s_cbranch_scc0 .LBB0_853
	s_and_b64 vcc, exec, s[4:5]
	s_cbranch_vccz .LBB0_856
	s_barrier

.LBB0_889:
	s_add_u32 s6, s0, 0x100
	s_addc_u32 s7, s1, 0
	s_add_i32 s51, 0, 0x10000
	s_cmp_eq_u32 s50, 40
	s_cselect_b32 s23, s17, s7
	s_cselect_b32 s22, s16, s6
	s_cselect_b32 s21, s19, s47
	s_cselect_b32 s20, s18, s46
	s_add_i32 s52, 0, 0x14000
	v_add_u32_e32 v142, s51, v184
	v_add_u32_e32 v158, s52, v184
	ds_read_b128 v[130:133], v142
	ds_read_b128 v[134:137], v142 offset:1024
	ds_read_b128 v[138:141], v142 offset:2048
	ds_read_b128 v[142:145], v142 offset:3072
	ds_read_b128 v[146:149], v158
	ds_read_b128 v[150:153], v158 offset:1024
	ds_read_b128 v[154:157], v158 offset:2048
	ds_read_b128 v[158:161], v158 offset:3072
	v_lshl_add_u64 v[178:179], s[0:1], 0, v[170:171]
	s_add_i32 m0, s30, 0xc000
	ds_read_b128 v[174:177], v185
	ds_read_b128 v[188:191], v185 offset:1024
	ds_read_b128 v[192:195], v185 offset:2048
	ds_read_b128 v[196:199], v185 offset:3072
	ds_read_b128 v[200:203], v185 offset:4096
	ds_read_b128 v[204:207], v185 offset:5120
	ds_read_b128 v[208:211], v185 offset:6144
	ds_read_b128 v[212:215], v185 offset:7168
	global_load_lds_dwordx4 v[178:179], off
	v_lshl_add_u64 v[178:179], s[0:1], 0, v[172:173]
	s_add_i32 m0, s30, 0xe000
	s_nop 0
	global_load_lds_dwordx4 v[178:179], off
	s_waitcnt vmcnt(8)
	s_waitcnt lgkmcnt(0)
	s_barrier
	s_setprio 1
	s_waitcnt lgkmcnt(0)
	v_mfma_f32_16x16x32_bf16 v[126:129], v[130:133], v[174:177], v[126:129]
	v_mfma_f32_16x16x32_bf16 v[122:125], v[138:141], v[174:177], v[122:125]
	v_mfma_f32_16x16x32_bf16 v[110:113], v[130:133], v[192:195], v[110:113]
	v_mfma_f32_16x16x32_bf16 v[106:109], v[138:141], v[192:195], v[106:109]
	v_mfma_f32_16x16x32_bf16 v[94:97], v[130:133], v[200:203], v[94:97]
	v_mfma_f32_16x16x32_bf16 v[90:93], v[138:141], v[200:203], v[90:93]
	v_mfma_f32_16x16x32_bf16 v[78:81], v[130:133], v[208:211], v[78:81]
	v_mfma_f32_16x16x32_bf16 v[74:77], v[138:141], v[208:211], v[74:77]
	v_mfma_f32_16x16x32_bf16 v[126:129], v[134:137], v[188:191], v[126:129]
	v_mfma_f32_16x16x32_bf16 v[122:125], v[142:145], v[188:191], v[122:125]
	v_mfma_f32_16x16x32_bf16 v[110:113], v[134:137], v[196:199], v[110:113]
	v_mfma_f32_16x16x32_bf16 v[106:109], v[142:145], v[196:199], v[106:109]
	v_mfma_f32_16x16x32_bf16 v[94:97], v[134:137], v[204:207], v[94:97]
	v_mfma_f32_16x16x32_bf16 v[90:93], v[142:145], v[204:207], v[90:93]
	v_mfma_f32_16x16x32_bf16 v[78:81], v[134:137], v[212:215], v[78:81]
	v_mfma_f32_16x16x32_bf16 v[74:77], v[142:145], v[212:215], v[74:77]
	s_setprio 0
	s_setprio 1
	v_mfma_f32_16x16x32_bf16 v[118:121], v[146:149], v[174:177], v[118:121]
	v_mfma_f32_16x16x32_bf16 v[114:117], v[154:157], v[174:177], v[114:117]
	v_mfma_f32_16x16x32_bf16 v[102:105], v[146:149], v[192:195], v[102:105]
	v_mfma_f32_16x16x32_bf16 v[98:101], v[154:157], v[192:195], v[98:101]
	v_mfma_f32_16x16x32_bf16 v[86:89], v[146:149], v[200:203], v[86:89]
	v_mfma_f32_16x16x32_bf16 v[82:85], v[154:157], v[200:203], v[82:85]
	v_mfma_f32_16x16x32_bf16 v[70:73], v[146:149], v[208:211], v[70:73]
	v_mfma_f32_16x16x32_bf16 v[66:69], v[154:157], v[208:211], v[66:69]
	v_mfma_f32_16x16x32_bf16 v[118:121], v[150:153], v[188:191], v[118:121]
	v_mfma_f32_16x16x32_bf16 v[114:117], v[158:161], v[188:191], v[114:117]
	v_mfma_f32_16x16x32_bf16 v[102:105], v[150:153], v[196:199], v[102:105]
	v_mfma_f32_16x16x32_bf16 v[98:101], v[158:161], v[196:199], v[98:101]
	v_mfma_f32_16x16x32_bf16 v[86:89], v[150:153], v[204:207], v[86:89]
	v_mfma_f32_16x16x32_bf16 v[82:85], v[158:161], v[204:207], v[82:85]
	v_mfma_f32_16x16x32_bf16 v[70:73], v[150:153], v[212:215], v[70:73]
	v_mfma_f32_16x16x32_bf16 v[66:69], v[158:161], v[212:215], v[66:69]
	s_setprio 0
	s_barrier
	s_add_i32 s0, s51, s29
	v_lshl_add_u64 v[178:179], s[20:21], 0, v[0:1]
	s_mov_b32 m0, s0
	ds_read_b128 v[174:177], v185 offset:16384
	ds_read_b128 v[188:191], v185 offset:17408
	ds_read_b128 v[192:195], v185 offset:18432
	ds_read_b128 v[196:199], v185 offset:19456
	ds_read_b128 v[200:203], v185 offset:20480
	ds_read_b128 v[204:207], v185 offset:21504
	ds_read_b128 v[208:211], v185 offset:22528
	ds_read_b128 v[212:215], v185 offset:23552
	global_load_lds_dwordx4 v[178:179], off
	s_add_i32 m0, s0, 0x2000
	s_add_u32 s0, s20, 0xb0000
	v_lshl_add_u64 v[216:217], s[20:21], 0, v[166:167]
	s_addc_u32 s1, s21, 0
	s_add_i32 s51, s52, s29
	global_load_lds_dwordx4 v[216:217], off
	v_lshl_add_u64 v[218:219], s[0:1], 0, v[0:1]
	s_mov_b32 m0, s51
	v_lshl_add_u64 v[220:221], s[22:23], 0, v[164:165]
	global_load_lds_dwordx4 v[218:219], off
	v_lshl_add_u64 v[218:219], s[0:1], 0, v[166:167]
	s_add_i32 m0, s51, 0x2000
	s_nop 0
	global_load_lds_dwordx4 v[218:219], off
	s_waitcnt vmcnt(6)
	s_waitcnt lgkmcnt(0)
	s_barrier
	s_setprio 1
	s_waitcnt lgkmcnt(0)
	v_mfma_f32_16x16x32_bf16 v[62:65], v[130:133], v[174:177], v[62:65]
	v_mfma_f32_16x16x32_bf16 v[58:61], v[138:141], v[174:177], v[58:61]
	v_mfma_f32_16x16x32_bf16 v[46:49], v[130:133], v[192:195], v[46:49]
	v_mfma_f32_16x16x32_bf16 v[42:45], v[138:141], v[192:195], v[42:45]
	v_mfma_f32_16x16x32_bf16 v[30:33], v[130:133], v[200:203], v[30:33]
	v_mfma_f32_16x16x32_bf16 v[26:29], v[138:141], v[200:203], v[26:29]
	v_mfma_f32_16x16x32_bf16 v[14:17], v[130:133], v[208:211], v[14:17]
	v_mfma_f32_16x16x32_bf16 v[10:13], v[138:141], v[208:211], v[10:13]
	v_mfma_f32_16x16x32_bf16 v[62:65], v[134:137], v[188:191], v[62:65]
	v_mfma_f32_16x16x32_bf16 v[58:61], v[142:145], v[188:191], v[58:61]
	v_mfma_f32_16x16x32_bf16 v[46:49], v[134:137], v[196:199], v[46:49]
	v_mfma_f32_16x16x32_bf16 v[42:45], v[142:145], v[196:199], v[42:45]
	v_mfma_f32_16x16x32_bf16 v[30:33], v[134:137], v[204:207], v[30:33]
	v_mfma_f32_16x16x32_bf16 v[26:29], v[142:145], v[204:207], v[26:29]
	v_mfma_f32_16x16x32_bf16 v[14:17], v[134:137], v[212:215], v[14:17]
	v_mfma_f32_16x16x32_bf16 v[10:13], v[142:145], v[212:215], v[10:13]
	s_setprio 0
	s_setprio 1
	v_mfma_f32_16x16x32_bf16 v[54:57], v[146:149], v[174:177], v[54:57]
	v_mfma_f32_16x16x32_bf16 v[50:53], v[154:157], v[174:177], v[50:53]
	v_mfma_f32_16x16x32_bf16 v[38:41], v[146:149], v[192:195], v[38:41]
	v_mfma_f32_16x16x32_bf16 v[34:37], v[154:157], v[192:195], v[34:37]
	v_mfma_f32_16x16x32_bf16 v[22:25], v[146:149], v[200:203], v[22:25]
	v_mfma_f32_16x16x32_bf16 v[18:21], v[154:157], v[200:203], v[18:21]
	v_mfma_f32_16x16x32_bf16 v[6:9], v[146:149], v[208:211], v[6:9]
	v_mfma_f32_16x16x32_bf16 v[2:5], v[154:157], v[208:211], v[2:5]
	v_mfma_f32_16x16x32_bf16 v[54:57], v[150:153], v[188:191], v[54:57]
	v_mfma_f32_16x16x32_bf16 v[50:53], v[158:161], v[188:191], v[50:53]
	v_mfma_f32_16x16x32_bf16 v[38:41], v[150:153], v[196:199], v[38:41]
	v_mfma_f32_16x16x32_bf16 v[34:37], v[158:161], v[196:199], v[34:37]
	v_mfma_f32_16x16x32_bf16 v[22:25], v[150:153], v[204:207], v[22:25]
	v_mfma_f32_16x16x32_bf16 v[18:21], v[158:161], v[204:207], v[18:21]
	v_mfma_f32_16x16x32_bf16 v[6:9], v[150:153], v[212:215], v[6:9]
	v_mfma_f32_16x16x32_bf16 v[2:5], v[158:161], v[212:215], v[2:5]
	s_setprio 0
	s_barrier
	s_add_i32 s51, 0, 0x18000
	s_add_i32 s52, 0, 0x1c000
	v_add_u32_e32 v142, s51, v184
	v_add_u32_e32 v158, s52, v184
	ds_read_b128 v[130:133], v142
	ds_read_b128 v[134:137], v142 offset:1024
	ds_read_b128 v[138:141], v142 offset:2048
	ds_read_b128 v[142:145], v142 offset:3072
	ds_read_b128 v[146:149], v158
	ds_read_b128 v[150:153], v158 offset:1024
	ds_read_b128 v[154:157], v158 offset:2048
	ds_read_b128 v[158:161], v158 offset:3072
	s_add_u32 s0, s22, 0xb0000
	s_addc_u32 s1, s23, 0
	v_lshl_add_u64 v[218:219], s[22:23], 0, v[162:163]
	s_mov_b32 m0, s30
	s_nop 0
	global_load_lds_dwordx4 v[218:219], off
	s_mov_b32 m0, s31
	s_nop 0
	global_load_lds_dwordx4 v[220:221], off
	s_mov_b32 m0, s33
	v_lshl_add_u64 v[222:223], s[0:1], 0, v[162:163]
	ds_read_b128 v[174:177], v185 offset:32768
	ds_read_b128 v[188:191], v185 offset:33792
	ds_read_b128 v[192:195], v185 offset:34816
	ds_read_b128 v[196:199], v185 offset:35840
	ds_read_b128 v[200:203], v185 offset:36864
	ds_read_b128 v[204:207], v185 offset:37888
	ds_read_b128 v[208:211], v185 offset:38912
	ds_read_b128 v[212:215], v185 offset:39936
	global_load_lds_dwordx4 v[222:223], off
	v_lshl_add_u64 v[222:223], s[0:1], 0, v[164:165]
	s_mov_b32 m0, s34
	s_nop 0
	global_load_lds_dwordx4 v[222:223], off
	s_waitcnt vmcnt(8)
	s_waitcnt lgkmcnt(0)
	s_barrier
	s_setprio 1
	s_waitcnt lgkmcnt(0)
	v_mfma_f32_16x16x32_bf16 v[126:129], v[130:133], v[174:177], v[126:129]
	v_mfma_f32_16x16x32_bf16 v[122:125], v[138:141], v[174:177], v[122:125]
	v_mfma_f32_16x16x32_bf16 v[110:113], v[130:133], v[192:195], v[110:113]
	v_mfma_f32_16x16x32_bf16 v[106:109], v[138:141], v[192:195], v[106:109]
	v_mfma_f32_16x16x32_bf16 v[94:97], v[130:133], v[200:203], v[94:97]
	v_mfma_f32_16x16x32_bf16 v[90:93], v[138:141], v[200:203], v[90:93]
	v_mfma_f32_16x16x32_bf16 v[78:81], v[130:133], v[208:211], v[78:81]
	v_mfma_f32_16x16x32_bf16 v[74:77], v[138:141], v[208:211], v[74:77]
	v_mfma_f32_16x16x32_bf16 v[126:129], v[134:137], v[188:191], v[126:129]
	v_mfma_f32_16x16x32_bf16 v[122:125], v[142:145], v[188:191], v[122:125]
	v_mfma_f32_16x16x32_bf16 v[110:113], v[134:137], v[196:199], v[110:113]
	v_mfma_f32_16x16x32_bf16 v[106:109], v[142:145], v[196:199], v[106:109]
	v_mfma_f32_16x16x32_bf16 v[94:97], v[134:137], v[204:207], v[94:97]
	v_mfma_f32_16x16x32_bf16 v[90:93], v[142:145], v[204:207], v[90:93]
	v_mfma_f32_16x16x32_bf16 v[78:81], v[134:137], v[212:215], v[78:81]
	v_mfma_f32_16x16x32_bf16 v[74:77], v[142:145], v[212:215], v[74:77]
	s_setprio 0
	s_setprio 1
	v_mfma_f32_16x16x32_bf16 v[118:121], v[146:149], v[174:177], v[118:121]
	v_mfma_f32_16x16x32_bf16 v[114:117], v[154:157], v[174:177], v[114:117]
	v_mfma_f32_16x16x32_bf16 v[102:105], v[146:149], v[192:195], v[102:105]
	v_mfma_f32_16x16x32_bf16 v[98:101], v[154:157], v[192:195], v[98:101]
	v_mfma_f32_16x16x32_bf16 v[86:89], v[146:149], v[200:203], v[86:89]
	v_mfma_f32_16x16x32_bf16 v[82:85], v[154:157], v[200:203], v[82:85]
	v_mfma_f32_16x16x32_bf16 v[70:73], v[146:149], v[208:211], v[70:73]
	v_mfma_f32_16x16x32_bf16 v[66:69], v[154:157], v[208:211], v[66:69]
	v_mfma_f32_16x16x32_bf16 v[118:121], v[150:153], v[188:191], v[118:121]
	v_mfma_f32_16x16x32_bf16 v[114:117], v[158:161], v[188:191], v[114:117]
	v_mfma_f32_16x16x32_bf16 v[102:105], v[150:153], v[196:199], v[102:105]
	v_mfma_f32_16x16x32_bf16 v[98:101], v[158:161], v[196:199], v[98:101]
	v_mfma_f32_16x16x32_bf16 v[86:89], v[150:153], v[204:207], v[86:89]
	v_mfma_f32_16x16x32_bf16 v[82:85], v[158:161], v[204:207], v[82:85]
	v_mfma_f32_16x16x32_bf16 v[70:73], v[150:153], v[212:215], v[70:73]
	v_mfma_f32_16x16x32_bf16 v[66:69], v[158:161], v[212:215], v[66:69]
	s_setprio 0
	s_barrier
	s_add_i32 s0, s51, s29
	v_lshl_add_u64 v[178:179], v[178:179], 0, s[80:81]
	s_mov_b32 m0, s0
	ds_read_b128 v[174:177], v185 offset:49152
	ds_read_b128 v[188:191], v185 offset:50176
	ds_read_b128 v[192:195], v185 offset:51200
	ds_read_b128 v[196:199], v185 offset:52224
	ds_read_b128 v[200:203], v185 offset:53248
	ds_read_b128 v[204:207], v185 offset:54272
	ds_read_b128 v[208:211], v185 offset:55296
	ds_read_b128 v[212:215], v185 offset:56320
	global_load_lds_dwordx4 v[178:179], off
	s_add_i32 m0, s0, 0x2000
	s_add_u32 s0, s20, 0xb0080
	v_lshl_add_u64 v[178:179], v[216:217], 0, s[80:81]
	s_addc_u32 s1, s21, 0
	s_add_i32 s20, s52, s29
	global_load_lds_dwordx4 v[178:179], off
	v_lshl_add_u64 v[178:179], s[0:1], 0, v[0:1]
	s_mov_b32 m0, s20
	s_nop 0
	global_load_lds_dwordx4 v[178:179], off
	v_lshl_add_u64 v[178:179], s[0:1], 0, v[166:167]
	s_add_i32 m0, s20, 0x2000
	s_nop 0
	global_load_lds_dwordx4 v[178:179], off
	v_lshl_add_u64 v[178:179], v[218:219], 0, s[80:81]
	s_mov_b32 m0, s40
	s_nop 0
	global_load_lds_dwordx4 v[178:179], off
	v_lshl_add_u64 v[178:179], v[220:221], 0, s[80:81]
	s_mov_b32 m0, s41
	s_nop 0
	global_load_lds_dwordx4 v[178:179], off
	s_waitcnt vmcnt(8)
	s_waitcnt lgkmcnt(0)
	s_barrier
	s_setprio 1
	s_waitcnt lgkmcnt(0)
	v_mfma_f32_16x16x32_bf16 v[62:65], v[130:133], v[174:177], v[62:65]
	v_mfma_f32_16x16x32_bf16 v[58:61], v[138:141], v[174:177], v[58:61]
	v_mfma_f32_16x16x32_bf16 v[46:49], v[130:133], v[192:195], v[46:49]
	v_mfma_f32_16x16x32_bf16 v[42:45], v[138:141], v[192:195], v[42:45]
	v_mfma_f32_16x16x32_bf16 v[30:33], v[130:133], v[200:203], v[30:33]
	v_mfma_f32_16x16x32_bf16 v[26:29], v[138:141], v[200:203], v[26:29]
	v_mfma_f32_16x16x32_bf16 v[14:17], v[130:133], v[208:211], v[14:17]
	v_mfma_f32_16x16x32_bf16 v[10:13], v[138:141], v[208:211], v[10:13]
	v_mfma_f32_16x16x32_bf16 v[62:65], v[134:137], v[188:191], v[62:65]
	v_mfma_f32_16x16x32_bf16 v[58:61], v[142:145], v[188:191], v[58:61]
	v_mfma_f32_16x16x32_bf16 v[46:49], v[134:137], v[196:199], v[46:49]
	v_mfma_f32_16x16x32_bf16 v[42:45], v[142:145], v[196:199], v[42:45]
	v_mfma_f32_16x16x32_bf16 v[30:33], v[134:137], v[204:207], v[30:33]
	v_mfma_f32_16x16x32_bf16 v[26:29], v[142:145], v[204:207], v[26:29]
	v_mfma_f32_16x16x32_bf16 v[14:17], v[134:137], v[212:215], v[14:17]
	v_mfma_f32_16x16x32_bf16 v[10:13], v[142:145], v[212:215], v[10:13]
	s_setprio 0
	s_setprio 1
	v_mfma_f32_16x16x32_bf16 v[54:57], v[146:149], v[174:177], v[54:57]
	v_mfma_f32_16x16x32_bf16 v[50:53], v[154:157], v[174:177], v[50:53]
	v_mfma_f32_16x16x32_bf16 v[38:41], v[146:149], v[192:195], v[38:41]
	v_mfma_f32_16x16x32_bf16 v[34:37], v[154:157], v[192:195], v[34:37]
	v_mfma_f32_16x16x32_bf16 v[22:25], v[146:149], v[200:203], v[22:25]
	v_mfma_f32_16x16x32_bf16 v[18:21], v[154:157], v[200:203], v[18:21]
	v_mfma_f32_16x16x32_bf16 v[6:9], v[146:149], v[208:211], v[6:9]
	v_mfma_f32_16x16x32_bf16 v[2:5], v[154:157], v[208:211], v[2:5]
	v_mfma_f32_16x16x32_bf16 v[54:57], v[150:153], v[188:191], v[54:57]
	v_mfma_f32_16x16x32_bf16 v[50:53], v[158:161], v[188:191], v[50:53]
	v_mfma_f32_16x16x32_bf16 v[38:41], v[150:153], v[196:199], v[38:41]
	v_mfma_f32_16x16x32_bf16 v[34:37], v[158:161], v[196:199], v[34:37]
	v_mfma_f32_16x16x32_bf16 v[22:25], v[150:153], v[204:207], v[22:25]
	v_mfma_f32_16x16x32_bf16 v[18:21], v[158:161], v[204:207], v[18:21]
	v_mfma_f32_16x16x32_bf16 v[6:9], v[150:153], v[212:215], v[6:9]
	v_mfma_f32_16x16x32_bf16 v[2:5], v[158:161], v[212:215], v[2:5]
	s_setprio 0
	s_barrier
	s_add_i32 s50, s50, 2
	s_add_u32 s46, s46, 0x100
	s_addc_u32 s47, s47, 0
	s_cmp_gt_u32 s50, 41
	s_mov_b64 s[0:1], s[6:7]
	s_cbranch_scc0 .LBB0_889
	s_and_b64 vcc, exec, s[12:13]
	s_cbranch_vccnz .LBB0_895
	s_andn2_b64 vcc, exec, s[14:15]
	s_mov_b64 s[20:21], 0
	s_mov_b64 s[50:51], 0x10000
	s_cbranch_vccz .LBB0_896

.LBB0_1072:
	s_add_u32 s26, s4, 0xfffc0080
	s_addc_u32 s27, s5, -1
	s_add_i32 s34, 0, 0x10000
	s_cmp_eq_u32 s33, 12
	s_cselect_b32 s29, s1, s27
	s_cselect_b32 s28, s3, s26
	v_add_u32_e32 v0, s34, v178
	s_cselect_b32 s27, s17, s31
	s_cselect_b32 s26, s19, s30
	s_add_i32 s50, 0, 0x14000
	ds_read_b128 v[18:21], v0
	ds_read_b128 v[22:25], v0 offset:1024
	ds_read_b128 v[34:37], v0 offset:2048
	ds_read_b128 v[38:41], v0 offset:3072
	v_add_u32_e32 v0, s50, v178
	ds_read_b128 v[162:165], v0
	ds_read_b128 v[166:169], v0 offset:1024
	ds_read_b128 v[170:173], v0 offset:2048
	ds_read_b128 v[182:185], v0 offset:3072
	v_lshl_add_u64 v[174:175], s[4:5], 0, v[158:159]
	s_add_i32 m0, s43, 0xc000
	ds_read_b128 v[186:189], v179
	ds_read_b128 v[190:193], v179 offset:1024
	ds_read_b128 v[194:197], v179 offset:2048
	ds_read_b128 v[198:201], v179 offset:3072
	ds_read_b128 v[202:205], v179 offset:4096
	ds_read_b128 v[206:209], v179 offset:5120
	ds_read_b128 v[210:213], v179 offset:6144
	ds_read_b128 v[214:217], v179 offset:7168
	global_load_lds_dwordx4 v[174:175], off
	v_lshl_add_u64 v[174:175], s[4:5], 0, v[160:161]
	s_add_i32 m0, s43, 0xe000
	s_nop 0
	global_load_lds_dwordx4 v[174:175], off
	s_waitcnt vmcnt(8)
	s_waitcnt lgkmcnt(0)
	s_barrier
	s_setprio 1
	s_waitcnt lgkmcnt(0)
	v_mfma_f32_16x16x32_bf16 v[142:145], v[18:21], v[186:189], v[142:145]
	v_mfma_f32_16x16x32_bf16 v[138:141], v[34:37], v[186:189], v[138:141]
	v_mfma_f32_16x16x32_bf16 v[126:129], v[18:21], v[194:197], v[126:129]
	v_mfma_f32_16x16x32_bf16 v[122:125], v[34:37], v[194:197], v[122:125]
	v_mfma_f32_16x16x32_bf16 v[110:113], v[18:21], v[202:205], v[110:113]
	v_mfma_f32_16x16x32_bf16 v[106:109], v[34:37], v[202:205], v[106:109]
	v_mfma_f32_16x16x32_bf16 v[94:97], v[18:21], v[210:213], v[94:97]
	v_mfma_f32_16x16x32_bf16 v[90:93], v[34:37], v[210:213], v[90:93]
	v_mfma_f32_16x16x32_bf16 v[142:145], v[22:25], v[190:193], v[142:145]
	v_mfma_f32_16x16x32_bf16 v[138:141], v[38:41], v[190:193], v[138:141]
	v_mfma_f32_16x16x32_bf16 v[126:129], v[22:25], v[198:201], v[126:129]
	v_mfma_f32_16x16x32_bf16 v[122:125], v[38:41], v[198:201], v[122:125]
	v_mfma_f32_16x16x32_bf16 v[110:113], v[22:25], v[206:209], v[110:113]
	v_mfma_f32_16x16x32_bf16 v[106:109], v[38:41], v[206:209], v[106:109]
	v_mfma_f32_16x16x32_bf16 v[94:97], v[22:25], v[214:217], v[94:97]
	v_mfma_f32_16x16x32_bf16 v[90:93], v[38:41], v[214:217], v[90:93]
	s_setprio 0
	s_setprio 1
	v_mfma_f32_16x16x32_bf16 v[134:137], v[162:165], v[186:189], v[134:137]
	v_mfma_f32_16x16x32_bf16 v[130:133], v[170:173], v[186:189], v[130:133]
	v_mfma_f32_16x16x32_bf16 v[118:121], v[162:165], v[194:197], v[118:121]
	v_mfma_f32_16x16x32_bf16 v[114:117], v[170:173], v[194:197], v[114:117]
	v_mfma_f32_16x16x32_bf16 v[102:105], v[162:165], v[202:205], v[102:105]
	v_mfma_f32_16x16x32_bf16 v[98:101], v[170:173], v[202:205], v[98:101]
	v_mfma_f32_16x16x32_bf16 v[86:89], v[162:165], v[210:213], v[86:89]
	v_mfma_f32_16x16x32_bf16 v[82:85], v[170:173], v[210:213], v[82:85]
	v_mfma_f32_16x16x32_bf16 v[134:137], v[166:169], v[190:193], v[134:137]
	v_mfma_f32_16x16x32_bf16 v[130:133], v[182:185], v[190:193], v[130:133]
	v_mfma_f32_16x16x32_bf16 v[118:121], v[166:169], v[198:201], v[118:121]
	v_mfma_f32_16x16x32_bf16 v[114:117], v[182:185], v[198:201], v[114:117]
	v_mfma_f32_16x16x32_bf16 v[102:105], v[166:169], v[206:209], v[102:105]
	v_mfma_f32_16x16x32_bf16 v[98:101], v[182:185], v[206:209], v[98:101]
	v_mfma_f32_16x16x32_bf16 v[86:89], v[166:169], v[214:217], v[86:89]
	v_mfma_f32_16x16x32_bf16 v[82:85], v[182:185], v[214:217], v[82:85]
	s_setprio 0
	s_barrier
	s_add_i32 s34, s34, s42
	v_lshl_add_u64 v[174:175], s[26:27], 0, v[148:149]
	s_mov_b32 m0, s34
	ds_read_b128 v[186:189], v179 offset:16384
	ds_read_b128 v[190:193], v179 offset:17408
	ds_read_b128 v[194:197], v179 offset:18432
	ds_read_b128 v[198:201], v179 offset:19456
	ds_read_b128 v[202:205], v179 offset:20480
	ds_read_b128 v[206:209], v179 offset:21504
	ds_read_b128 v[210:213], v179 offset:22528
	ds_read_b128 v[214:217], v179 offset:23552
	global_load_lds_dwordx4 v[174:175], off
	s_add_i32 m0, s34, 0x2000
	s_add_u32 s34, s26, 0x40000
	v_lshl_add_u64 v[218:219], s[26:27], 0, v[152:153]
	s_addc_u32 s35, s27, 0
	s_add_i32 s50, s50, s42
	global_load_lds_dwordx4 v[218:219], off
	v_lshl_add_u64 v[220:221], s[34:35], 0, v[148:149]
	s_mov_b32 m0, s50
	v_lshl_add_u64 v[222:223], s[28:29], 0, v[150:151]
	global_load_lds_dwordx4 v[220:221], off
	v_lshl_add_u64 v[220:221], s[34:35], 0, v[152:153]
	s_add_i32 m0, s50, 0x2000
	s_nop 0
	global_load_lds_dwordx4 v[220:221], off
	s_waitcnt vmcnt(6)
	s_waitcnt lgkmcnt(0)
	s_barrier
	s_setprio 1
	s_waitcnt lgkmcnt(0)
	v_mfma_f32_16x16x32_bf16 v[78:81], v[18:21], v[186:189], v[78:81]
	v_mfma_f32_16x16x32_bf16 v[74:77], v[34:37], v[186:189], v[74:77]
	v_mfma_f32_16x16x32_bf16 v[62:65], v[18:21], v[194:197], v[62:65]
	v_mfma_f32_16x16x32_bf16 v[58:61], v[34:37], v[194:197], v[58:61]
	v_mfma_f32_16x16x32_bf16 v[46:49], v[18:21], v[202:205], v[46:49]
	v_mfma_f32_16x16x32_bf16 v[42:45], v[34:37], v[202:205], v[42:45]
	v_mfma_f32_16x16x32_bf16 v[14:17], v[18:21], v[210:213], v[14:17]
	v_mfma_f32_16x16x32_bf16 v[10:13], v[34:37], v[210:213], v[10:13]
	v_mfma_f32_16x16x32_bf16 v[78:81], v[22:25], v[190:193], v[78:81]
	v_mfma_f32_16x16x32_bf16 v[74:77], v[38:41], v[190:193], v[74:77]
	v_mfma_f32_16x16x32_bf16 v[62:65], v[22:25], v[198:201], v[62:65]
	v_mfma_f32_16x16x32_bf16 v[58:61], v[38:41], v[198:201], v[58:61]
	v_mfma_f32_16x16x32_bf16 v[46:49], v[22:25], v[206:209], v[46:49]
	v_mfma_f32_16x16x32_bf16 v[42:45], v[38:41], v[206:209], v[42:45]
	v_mfma_f32_16x16x32_bf16 v[14:17], v[22:25], v[214:217], v[14:17]
	v_mfma_f32_16x16x32_bf16 v[10:13], v[38:41], v[214:217], v[10:13]
	s_setprio 0
	s_setprio 1
	v_mfma_f32_16x16x32_bf16 v[30:33], v[162:165], v[202:205], v[30:33]
	v_mfma_f32_16x16x32_bf16 v[26:29], v[170:173], v[202:205], v[26:29]
	v_mfma_f32_16x16x32_bf16 v[6:9], v[162:165], v[210:213], v[6:9]
	v_mfma_f32_16x16x32_bf16 v[2:5], v[170:173], v[210:213], v[2:5]
	v_mfma_f32_16x16x32_bf16 v[18:21], v[162:165], v[186:189], v[70:73]
	v_mfma_f32_16x16x32_bf16 v[22:25], v[170:173], v[186:189], v[66:69]
	v_mfma_f32_16x16x32_bf16 v[34:37], v[162:165], v[194:197], v[54:57]
	v_mfma_f32_16x16x32_bf16 v[38:41], v[170:173], v[194:197], v[50:53]
	v_mfma_f32_16x16x32_bf16 v[30:33], v[166:169], v[206:209], v[30:33]
	v_mfma_f32_16x16x32_bf16 v[26:29], v[182:185], v[206:209], v[26:29]
	v_mfma_f32_16x16x32_bf16 v[6:9], v[166:169], v[214:217], v[6:9]
	v_mfma_f32_16x16x32_bf16 v[2:5], v[182:185], v[214:217], v[2:5]
	v_mfma_f32_16x16x32_bf16 v[18:21], v[166:169], v[190:193], v[18:21]
	v_mfma_f32_16x16x32_bf16 v[22:25], v[182:185], v[190:193], v[22:25]
	v_mfma_f32_16x16x32_bf16 v[34:37], v[166:169], v[198:201], v[34:37]
	v_mfma_f32_16x16x32_bf16 v[38:41], v[182:185], v[198:201], v[38:41]
	s_setprio 0
	s_barrier
	s_add_i32 s34, 0, 0x18000
	v_add_u32_e32 v0, s34, v178
	s_add_i32 s35, 0, 0x1c000
	ds_read_b128 v[50:53], v0
	ds_read_b128 v[54:57], v0 offset:1024
	ds_read_b128 v[66:69], v0 offset:2048
	ds_read_b128 v[70:73], v0 offset:3072
	v_add_u32_e32 v0, s35, v178
	ds_read_b128 v[162:165], v0
	ds_read_b128 v[166:169], v0 offset:1024
	ds_read_b128 v[170:173], v0 offset:2048
	ds_read_b128 v[182:185], v0 offset:3072
	v_lshl_add_u64 v[220:221], s[28:29], 0, v[146:147]
	s_mov_b32 m0, s43
	s_nop 0
	global_load_lds_dwordx4 v[220:221], off
	s_mov_b32 m0, s44
	s_nop 0
	global_load_lds_dwordx4 v[222:223], off
	s_add_u32 s28, s28, 0x40000
	s_addc_u32 s29, s29, 0
	s_mov_b32 m0, s45
	v_lshl_add_u64 v[224:225], s[28:29], 0, v[146:147]
	ds_read_b128 v[186:189], v179 offset:32768
	ds_read_b128 v[190:193], v179 offset:33792
	ds_read_b128 v[194:197], v179 offset:34816
	ds_read_b128 v[198:201], v179 offset:35840
	ds_read_b128 v[202:205], v179 offset:36864
	ds_read_b128 v[206:209], v179 offset:37888
	ds_read_b128 v[210:213], v179 offset:38912
	ds_read_b128 v[214:217], v179 offset:39936
	global_load_lds_dwordx4 v[224:225], off
	v_lshl_add_u64 v[224:225], s[28:29], 0, v[150:151]
	s_mov_b32 m0, s46
	s_nop 0
	global_load_lds_dwordx4 v[224:225], off
	s_waitcnt vmcnt(8)
	s_waitcnt lgkmcnt(0)
	s_barrier
	s_setprio 1
	s_waitcnt lgkmcnt(0)
	v_mfma_f32_16x16x32_bf16 v[142:145], v[50:53], v[186:189], v[142:145]
	v_mfma_f32_16x16x32_bf16 v[138:141], v[66:69], v[186:189], v[138:141]
	v_mfma_f32_16x16x32_bf16 v[126:129], v[50:53], v[194:197], v[126:129]
	v_mfma_f32_16x16x32_bf16 v[122:125], v[66:69], v[194:197], v[122:125]
	v_mfma_f32_16x16x32_bf16 v[110:113], v[50:53], v[202:205], v[110:113]
	v_mfma_f32_16x16x32_bf16 v[106:109], v[66:69], v[202:205], v[106:109]
	v_mfma_f32_16x16x32_bf16 v[94:97], v[50:53], v[210:213], v[94:97]
	v_mfma_f32_16x16x32_bf16 v[90:93], v[66:69], v[210:213], v[90:93]
	v_mfma_f32_16x16x32_bf16 v[142:145], v[54:57], v[190:193], v[142:145]
	v_mfma_f32_16x16x32_bf16 v[138:141], v[70:73], v[190:193], v[138:141]
	v_mfma_f32_16x16x32_bf16 v[126:129], v[54:57], v[198:201], v[126:129]
	v_mfma_f32_16x16x32_bf16 v[122:125], v[70:73], v[198:201], v[122:125]
	v_mfma_f32_16x16x32_bf16 v[110:113], v[54:57], v[206:209], v[110:113]
	v_mfma_f32_16x16x32_bf16 v[106:109], v[70:73], v[206:209], v[106:109]
	v_mfma_f32_16x16x32_bf16 v[94:97], v[54:57], v[214:217], v[94:97]
	v_mfma_f32_16x16x32_bf16 v[90:93], v[70:73], v[214:217], v[90:93]
	s_setprio 0
	s_setprio 1
	v_mfma_f32_16x16x32_bf16 v[134:137], v[162:165], v[186:189], v[134:137]
	v_mfma_f32_16x16x32_bf16 v[130:133], v[170:173], v[186:189], v[130:133]
	v_mfma_f32_16x16x32_bf16 v[118:121], v[162:165], v[194:197], v[118:121]
	v_mfma_f32_16x16x32_bf16 v[114:117], v[170:173], v[194:197], v[114:117]
	v_mfma_f32_16x16x32_bf16 v[102:105], v[162:165], v[202:205], v[102:105]
	v_mfma_f32_16x16x32_bf16 v[98:101], v[170:173], v[202:205], v[98:101]
	v_mfma_f32_16x16x32_bf16 v[86:89], v[162:165], v[210:213], v[86:89]
	v_mfma_f32_16x16x32_bf16 v[82:85], v[170:173], v[210:213], v[82:85]
	v_mfma_f32_16x16x32_bf16 v[134:137], v[166:169], v[190:193], v[134:137]
	v_mfma_f32_16x16x32_bf16 v[130:133], v[182:185], v[190:193], v[130:133]
	v_mfma_f32_16x16x32_bf16 v[118:121], v[166:169], v[198:201], v[118:121]
	v_mfma_f32_16x16x32_bf16 v[114:117], v[182:185], v[198:201], v[114:117]
	v_mfma_f32_16x16x32_bf16 v[102:105], v[166:169], v[206:209], v[102:105]
	v_mfma_f32_16x16x32_bf16 v[98:101], v[182:185], v[206:209], v[98:101]
	v_mfma_f32_16x16x32_bf16 v[86:89], v[166:169], v[214:217], v[86:89]
	v_mfma_f32_16x16x32_bf16 v[82:85], v[182:185], v[214:217], v[82:85]
	s_setprio 0
	s_barrier
	s_add_i32 s28, s34, s42
	v_lshl_add_u64 v[174:175], v[174:175], 0, s[80:81]
	s_mov_b32 m0, s28
	ds_read_b128 v[186:189], v179 offset:49152
	ds_read_b128 v[190:193], v179 offset:50176
	ds_read_b128 v[194:197], v179 offset:51200
	ds_read_b128 v[198:201], v179 offset:52224
	ds_read_b128 v[202:205], v179 offset:53248
	ds_read_b128 v[206:209], v179 offset:54272
	ds_read_b128 v[210:213], v179 offset:55296
	ds_read_b128 v[214:217], v179 offset:56320
	global_load_lds_dwordx4 v[174:175], off
	s_add_i32 m0, s28, 0x2000
	s_add_u32 s26, s26, 0x40080
	v_lshl_add_u64 v[174:175], v[218:219], 0, s[80:81]
	s_addc_u32 s27, s27, 0
	s_add_i32 s28, s35, s42
	global_load_lds_dwordx4 v[174:175], off
	v_lshl_add_u64 v[174:175], s[26:27], 0, v[148:149]
	s_mov_b32 m0, s28
	s_nop 0
	global_load_lds_dwordx4 v[174:175], off
	v_lshl_add_u64 v[174:175], s[26:27], 0, v[152:153]
	s_add_i32 m0, s28, 0x2000
	s_nop 0
	global_load_lds_dwordx4 v[174:175], off
	v_lshl_add_u64 v[174:175], v[220:221], 0, s[80:81]
	s_mov_b32 m0, s47
	s_nop 0
	global_load_lds_dwordx4 v[174:175], off
	v_lshl_add_u64 v[174:175], v[222:223], 0, s[80:81]
	s_mov_b32 m0, s48
	s_nop 0
	global_load_lds_dwordx4 v[174:175], off
	s_waitcnt vmcnt(8)
	s_waitcnt lgkmcnt(0)
	s_barrier
	s_setprio 1
	s_waitcnt lgkmcnt(0)
	v_mfma_f32_16x16x32_bf16 v[78:81], v[50:53], v[186:189], v[78:81]
	v_mfma_f32_16x16x32_bf16 v[74:77], v[66:69], v[186:189], v[74:77]
	v_mfma_f32_16x16x32_bf16 v[62:65], v[50:53], v[194:197], v[62:65]
	v_mfma_f32_16x16x32_bf16 v[58:61], v[66:69], v[194:197], v[58:61]
	v_mfma_f32_16x16x32_bf16 v[46:49], v[50:53], v[202:205], v[46:49]
	v_mfma_f32_16x16x32_bf16 v[42:45], v[66:69], v[202:205], v[42:45]
	v_mfma_f32_16x16x32_bf16 v[14:17], v[50:53], v[210:213], v[14:17]
	v_mfma_f32_16x16x32_bf16 v[10:13], v[66:69], v[210:213], v[10:13]
	v_mfma_f32_16x16x32_bf16 v[78:81], v[54:57], v[190:193], v[78:81]
	v_mfma_f32_16x16x32_bf16 v[74:77], v[70:73], v[190:193], v[74:77]
	v_mfma_f32_16x16x32_bf16 v[62:65], v[54:57], v[198:201], v[62:65]
	v_mfma_f32_16x16x32_bf16 v[58:61], v[70:73], v[198:201], v[58:61]
	v_mfma_f32_16x16x32_bf16 v[46:49], v[54:57], v[206:209], v[46:49]
	v_mfma_f32_16x16x32_bf16 v[42:45], v[70:73], v[206:209], v[42:45]
	v_mfma_f32_16x16x32_bf16 v[14:17], v[54:57], v[214:217], v[14:17]
	v_mfma_f32_16x16x32_bf16 v[10:13], v[70:73], v[214:217], v[10:13]
	s_setprio 0
	s_setprio 1
	v_mfma_f32_16x16x32_bf16 v[18:21], v[162:165], v[186:189], v[18:21]
	v_mfma_f32_16x16x32_bf16 v[70:73], v[166:169], v[190:193], v[18:21]
	v_mfma_f32_16x16x32_bf16 v[18:21], v[170:173], v[186:189], v[22:25]
	v_mfma_f32_16x16x32_bf16 v[66:69], v[182:185], v[190:193], v[18:21]
	v_mfma_f32_16x16x32_bf16 v[18:21], v[162:165], v[194:197], v[34:37]
	v_mfma_f32_16x16x32_bf16 v[54:57], v[166:169], v[198:201], v[18:21]
	v_mfma_f32_16x16x32_bf16 v[18:21], v[170:173], v[194:197], v[38:41]
	v_mfma_f32_16x16x32_bf16 v[50:53], v[182:185], v[198:201], v[18:21]
	v_mfma_f32_16x16x32_bf16 v[18:21], v[162:165], v[202:205], v[30:33]
	v_mfma_f32_16x16x32_bf16 v[30:33], v[166:169], v[206:209], v[18:21]
	v_mfma_f32_16x16x32_bf16 v[18:21], v[170:173], v[202:205], v[26:29]
	v_mfma_f32_16x16x32_bf16 v[6:9], v[162:165], v[210:213], v[6:9]
	v_mfma_f32_16x16x32_bf16 v[2:5], v[170:173], v[210:213], v[2:5]
	v_mfma_f32_16x16x32_bf16 v[26:29], v[182:185], v[206:209], v[18:21]
	v_mfma_f32_16x16x32_bf16 v[6:9], v[166:169], v[214:217], v[6:9]
	v_mfma_f32_16x16x32_bf16 v[2:5], v[182:185], v[214:217], v[2:5]
	s_setprio 0
	s_barrier
	s_add_i32 s33, s33, 2
	s_add_u32 s4, s4, 0x100
	s_addc_u32 s5, s5, 0
	s_add_u32 s30, s30, 0x100
	s_addc_u32 s31, s31, 0
	s_cmp_gt_u32 s33, 13
	s_cbranch_scc0 .LBB0_1072
	s_and_b64 vcc, exec, s[12:13]
	s_cbranch_vccz .LBB0_1075
	s_barrier

.LBB0_1817:
	s_add_u32 s26, s24, 0xfffc0080
	s_addc_u32 s27, s25, -1
	s_add_i32 s48, 0, 0x10000
	s_cmp_eq_u32 s47, 12
	s_cselect_b32 s29, s1, s27
	s_cselect_b32 s28, s13, s26
	v_add_u32_e32 v153, s48, v151
	s_cselect_b32 s27, s15, s46
	s_cselect_b32 s26, s44, s45
	s_add_i32 s50, 0, 0x14000
	ds_read_b128 v[130:133], v153
	ds_read_b128 v[146:149], v153 offset:1024
	ds_read_b128 v[154:157], v153 offset:2048
	ds_read_b128 v[158:161], v153 offset:3072
	v_add_u32_e32 v153, s50, v151
	ds_read_b128 v[162:165], v153
	ds_read_b128 v[166:169], v153 offset:1024
	ds_read_b128 v[170:173], v153 offset:2048
	ds_read_b128 v[174:177], v153 offset:3072
	v_lshl_add_u64 v[210:211], s[24:25], 0, v[142:143]
	s_add_i32 m0, s23, 0xc000
	ds_read_b128 v[178:181], v152
	ds_read_b128 v[182:185], v152 offset:1024
	ds_read_b128 v[186:189], v152 offset:2048
	ds_read_b128 v[190:193], v152 offset:3072
	ds_read_b128 v[194:197], v152 offset:4096
	ds_read_b128 v[198:201], v152 offset:5120
	ds_read_b128 v[202:205], v152 offset:6144
	ds_read_b128 v[206:209], v152 offset:7168
	global_load_lds_dwordx4 v[210:211], off
	v_lshl_add_u64 v[210:211], s[24:25], 0, v[144:145]
	s_add_i32 m0, s23, 0xe000
	s_nop 0
	global_load_lds_dwordx4 v[210:211], off
	s_waitcnt vmcnt(8)
	s_waitcnt lgkmcnt(0)
	s_barrier
	s_setprio 1
	s_waitcnt lgkmcnt(0)
	v_mfma_f32_16x16x32_bf16 v[126:129], v[130:133], v[178:181], v[126:129]
	v_mfma_f32_16x16x32_bf16 v[122:125], v[154:157], v[178:181], v[122:125]
	v_mfma_f32_16x16x32_bf16 v[110:113], v[130:133], v[186:189], v[110:113]
	v_mfma_f32_16x16x32_bf16 v[106:109], v[154:157], v[186:189], v[106:109]
	v_mfma_f32_16x16x32_bf16 v[94:97], v[130:133], v[194:197], v[94:97]
	v_mfma_f32_16x16x32_bf16 v[90:93], v[154:157], v[194:197], v[90:93]
	v_mfma_f32_16x16x32_bf16 v[78:81], v[130:133], v[202:205], v[78:81]
	v_mfma_f32_16x16x32_bf16 v[74:77], v[154:157], v[202:205], v[74:77]
	v_mfma_f32_16x16x32_bf16 v[126:129], v[146:149], v[182:185], v[126:129]
	v_mfma_f32_16x16x32_bf16 v[122:125], v[158:161], v[182:185], v[122:125]
	v_mfma_f32_16x16x32_bf16 v[110:113], v[146:149], v[190:193], v[110:113]
	v_mfma_f32_16x16x32_bf16 v[106:109], v[158:161], v[190:193], v[106:109]
	v_mfma_f32_16x16x32_bf16 v[94:97], v[146:149], v[198:201], v[94:97]
	v_mfma_f32_16x16x32_bf16 v[90:93], v[158:161], v[198:201], v[90:93]
	v_mfma_f32_16x16x32_bf16 v[78:81], v[146:149], v[206:209], v[78:81]
	v_mfma_f32_16x16x32_bf16 v[74:77], v[158:161], v[206:209], v[74:77]
	s_setprio 0
	s_setprio 1
	v_mfma_f32_16x16x32_bf16 v[118:121], v[162:165], v[178:181], v[118:121]
	v_mfma_f32_16x16x32_bf16 v[114:117], v[170:173], v[178:181], v[114:117]
	v_mfma_f32_16x16x32_bf16 v[102:105], v[162:165], v[186:189], v[102:105]
	v_mfma_f32_16x16x32_bf16 v[98:101], v[170:173], v[186:189], v[98:101]
	v_mfma_f32_16x16x32_bf16 v[86:89], v[162:165], v[194:197], v[86:89]
	v_mfma_f32_16x16x32_bf16 v[82:85], v[170:173], v[194:197], v[82:85]
	v_mfma_f32_16x16x32_bf16 v[70:73], v[162:165], v[202:205], v[70:73]
	v_mfma_f32_16x16x32_bf16 v[66:69], v[170:173], v[202:205], v[66:69]
	v_mfma_f32_16x16x32_bf16 v[118:121], v[166:169], v[182:185], v[118:121]
	v_mfma_f32_16x16x32_bf16 v[114:117], v[174:177], v[182:185], v[114:117]
	v_mfma_f32_16x16x32_bf16 v[102:105], v[166:169], v[190:193], v[102:105]
	v_mfma_f32_16x16x32_bf16 v[98:101], v[174:177], v[190:193], v[98:101]
	v_mfma_f32_16x16x32_bf16 v[86:89], v[166:169], v[198:201], v[86:89]
	v_mfma_f32_16x16x32_bf16 v[82:85], v[174:177], v[198:201], v[82:85]
	v_mfma_f32_16x16x32_bf16 v[70:73], v[166:169], v[206:209], v[70:73]
	v_mfma_f32_16x16x32_bf16 v[66:69], v[174:177], v[206:209], v[66:69]
	s_setprio 0
	s_barrier
	s_add_i32 s48, s48, s35
	v_lshl_add_u64 v[210:211], s[26:27], 0, v[0:1]
	s_mov_b32 m0, s48
	ds_read_b128 v[178:181], v152 offset:16384
	ds_read_b128 v[182:185], v152 offset:17408
	ds_read_b128 v[186:189], v152 offset:18432
	ds_read_b128 v[190:193], v152 offset:19456
	ds_read_b128 v[194:197], v152 offset:20480
	ds_read_b128 v[198:201], v152 offset:21504
	ds_read_b128 v[202:205], v152 offset:22528
	ds_read_b128 v[206:209], v152 offset:23552
	global_load_lds_dwordx4 v[210:211], off
	s_add_i32 m0, s48, 0x2000
	s_add_u32 s48, s26, 0x40000
	v_lshl_add_u64 v[212:213], s[26:27], 0, v[134:135]
	s_addc_u32 s49, s27, 0
	s_add_i32 s50, s50, s35
	global_load_lds_dwordx4 v[212:213], off
	v_lshl_add_u64 v[214:215], s[48:49], 0, v[0:1]
	s_mov_b32 m0, s50
	v_lshl_add_u64 v[216:217], s[28:29], 0, v[136:137]
	global_load_lds_dwordx4 v[214:215], off
	v_lshl_add_u64 v[214:215], s[48:49], 0, v[134:135]
	s_add_i32 m0, s50, 0x2000
	s_nop 0
	global_load_lds_dwordx4 v[214:215], off
	s_waitcnt vmcnt(6)
	s_waitcnt lgkmcnt(0)
	s_barrier
	s_setprio 1
	s_waitcnt lgkmcnt(0)
	v_mfma_f32_16x16x32_bf16 v[62:65], v[130:133], v[178:181], v[62:65]
	v_mfma_f32_16x16x32_bf16 v[58:61], v[154:157], v[178:181], v[58:61]
	v_mfma_f32_16x16x32_bf16 v[46:49], v[130:133], v[186:189], v[46:49]
	v_mfma_f32_16x16x32_bf16 v[42:45], v[154:157], v[186:189], v[42:45]
	v_mfma_f32_16x16x32_bf16 v[30:33], v[130:133], v[194:197], v[30:33]
	v_mfma_f32_16x16x32_bf16 v[26:29], v[154:157], v[194:197], v[26:29]
	v_mfma_f32_16x16x32_bf16 v[22:25], v[130:133], v[202:205], v[22:25]
	v_mfma_f32_16x16x32_bf16 v[18:21], v[154:157], v[202:205], v[18:21]
	v_mfma_f32_16x16x32_bf16 v[62:65], v[146:149], v[182:185], v[62:65]
	v_mfma_f32_16x16x32_bf16 v[58:61], v[158:161], v[182:185], v[58:61]
	v_mfma_f32_16x16x32_bf16 v[46:49], v[146:149], v[190:193], v[46:49]
	v_mfma_f32_16x16x32_bf16 v[42:45], v[158:161], v[190:193], v[42:45]
	v_mfma_f32_16x16x32_bf16 v[30:33], v[146:149], v[198:201], v[30:33]
	v_mfma_f32_16x16x32_bf16 v[26:29], v[158:161], v[198:201], v[26:29]
	v_mfma_f32_16x16x32_bf16 v[22:25], v[146:149], v[206:209], v[22:25]
	v_mfma_f32_16x16x32_bf16 v[18:21], v[158:161], v[206:209], v[18:21]
	s_setprio 0
	s_setprio 1
	v_mfma_f32_16x16x32_bf16 v[54:57], v[162:165], v[178:181], v[54:57]
	v_mfma_f32_16x16x32_bf16 v[50:53], v[170:173], v[178:181], v[50:53]
	v_mfma_f32_16x16x32_bf16 v[38:41], v[162:165], v[186:189], v[38:41]
	v_mfma_f32_16x16x32_bf16 v[34:37], v[170:173], v[186:189], v[34:37]
	v_mfma_f32_16x16x32_bf16 v[14:17], v[162:165], v[194:197], v[14:17]
	v_mfma_f32_16x16x32_bf16 v[10:13], v[170:173], v[194:197], v[10:13]
	v_mfma_f32_16x16x32_bf16 v[6:9], v[162:165], v[202:205], v[6:9]
	v_mfma_f32_16x16x32_bf16 v[2:5], v[170:173], v[202:205], v[2:5]
	v_mfma_f32_16x16x32_bf16 v[54:57], v[166:169], v[182:185], v[54:57]
	v_mfma_f32_16x16x32_bf16 v[50:53], v[174:177], v[182:185], v[50:53]
	v_mfma_f32_16x16x32_bf16 v[38:41], v[166:169], v[190:193], v[38:41]
	v_mfma_f32_16x16x32_bf16 v[34:37], v[174:177], v[190:193], v[34:37]
	v_mfma_f32_16x16x32_bf16 v[14:17], v[166:169], v[198:201], v[14:17]
	v_mfma_f32_16x16x32_bf16 v[10:13], v[174:177], v[198:201], v[10:13]
	v_mfma_f32_16x16x32_bf16 v[6:9], v[166:169], v[206:209], v[6:9]
	v_mfma_f32_16x16x32_bf16 v[2:5], v[174:177], v[206:209], v[2:5]
	s_setprio 0
	s_barrier
	s_add_i32 s48, 0, 0x18000
	v_add_u32_e32 v153, s48, v151
	s_add_i32 s49, 0, 0x1c000
	ds_read_b128 v[130:133], v153
	ds_read_b128 v[146:149], v153 offset:1024
	ds_read_b128 v[154:157], v153 offset:2048
	ds_read_b128 v[158:161], v153 offset:3072
	v_add_u32_e32 v153, s49, v151
	ds_read_b128 v[162:165], v153
	ds_read_b128 v[166:169], v153 offset:1024
	ds_read_b128 v[170:173], v153 offset:2048
	ds_read_b128 v[174:177], v153 offset:3072
	v_lshl_add_u64 v[214:215], s[28:29], 0, v[138:139]
	s_mov_b32 m0, s23
	s_nop 0
	global_load_lds_dwordx4 v[214:215], off
	s_mov_b32 m0, s38
	s_nop 0
	global_load_lds_dwordx4 v[216:217], off
	s_add_u32 s28, s28, 0x40000
	s_addc_u32 s29, s29, 0
	s_mov_b32 m0, s39
	v_lshl_add_u64 v[218:219], s[28:29], 0, v[138:139]
	ds_read_b128 v[178:181], v152 offset:32768
	ds_read_b128 v[182:185], v152 offset:33792
	ds_read_b128 v[186:189], v152 offset:34816
	ds_read_b128 v[190:193], v152 offset:35840
	ds_read_b128 v[194:197], v152 offset:36864
	ds_read_b128 v[198:201], v152 offset:37888
	ds_read_b128 v[202:205], v152 offset:38912
	ds_read_b128 v[206:209], v152 offset:39936
	global_load_lds_dwordx4 v[218:219], off
	v_lshl_add_u64 v[218:219], s[28:29], 0, v[136:137]
	s_mov_b32 m0, s40
	s_nop 0
	global_load_lds_dwordx4 v[218:219], off
	s_waitcnt vmcnt(8)
	s_waitcnt lgkmcnt(0)
	s_barrier
	s_setprio 1
	s_waitcnt lgkmcnt(0)
	v_mfma_f32_16x16x32_bf16 v[126:129], v[130:133], v[178:181], v[126:129]
	v_mfma_f32_16x16x32_bf16 v[122:125], v[154:157], v[178:181], v[122:125]
	v_mfma_f32_16x16x32_bf16 v[110:113], v[130:133], v[186:189], v[110:113]
	v_mfma_f32_16x16x32_bf16 v[106:109], v[154:157], v[186:189], v[106:109]
	v_mfma_f32_16x16x32_bf16 v[94:97], v[130:133], v[194:197], v[94:97]
	v_mfma_f32_16x16x32_bf16 v[90:93], v[154:157], v[194:197], v[90:93]
	v_mfma_f32_16x16x32_bf16 v[78:81], v[130:133], v[202:205], v[78:81]
	v_mfma_f32_16x16x32_bf16 v[74:77], v[154:157], v[202:205], v[74:77]
	v_mfma_f32_16x16x32_bf16 v[126:129], v[146:149], v[182:185], v[126:129]
	v_mfma_f32_16x16x32_bf16 v[122:125], v[158:161], v[182:185], v[122:125]
	v_mfma_f32_16x16x32_bf16 v[110:113], v[146:149], v[190:193], v[110:113]
	v_mfma_f32_16x16x32_bf16 v[106:109], v[158:161], v[190:193], v[106:109]
	v_mfma_f32_16x16x32_bf16 v[94:97], v[146:149], v[198:201], v[94:97]
	v_mfma_f32_16x16x32_bf16 v[90:93], v[158:161], v[198:201], v[90:93]
	v_mfma_f32_16x16x32_bf16 v[78:81], v[146:149], v[206:209], v[78:81]
	v_mfma_f32_16x16x32_bf16 v[74:77], v[158:161], v[206:209], v[74:77]
	s_setprio 0
	s_setprio 1
	v_mfma_f32_16x16x32_bf16 v[118:121], v[162:165], v[178:181], v[118:121]
	v_mfma_f32_16x16x32_bf16 v[114:117], v[170:173], v[178:181], v[114:117]
	v_mfma_f32_16x16x32_bf16 v[102:105], v[162:165], v[186:189], v[102:105]
	v_mfma_f32_16x16x32_bf16 v[98:101], v[170:173], v[186:189], v[98:101]
	v_mfma_f32_16x16x32_bf16 v[86:89], v[162:165], v[194:197], v[86:89]
	v_mfma_f32_16x16x32_bf16 v[82:85], v[170:173], v[194:197], v[82:85]
	v_mfma_f32_16x16x32_bf16 v[70:73], v[162:165], v[202:205], v[70:73]
	v_mfma_f32_16x16x32_bf16 v[66:69], v[170:173], v[202:205], v[66:69]
	v_mfma_f32_16x16x32_bf16 v[118:121], v[166:169], v[182:185], v[118:121]
	v_mfma_f32_16x16x32_bf16 v[114:117], v[174:177], v[182:185], v[114:117]
	v_mfma_f32_16x16x32_bf16 v[102:105], v[166:169], v[190:193], v[102:105]
	v_mfma_f32_16x16x32_bf16 v[98:101], v[174:177], v[190:193], v[98:101]
	v_mfma_f32_16x16x32_bf16 v[86:89], v[166:169], v[198:201], v[86:89]
	v_mfma_f32_16x16x32_bf16 v[82:85], v[174:177], v[198:201], v[82:85]
	v_mfma_f32_16x16x32_bf16 v[70:73], v[166:169], v[206:209], v[70:73]
	v_mfma_f32_16x16x32_bf16 v[66:69], v[174:177], v[206:209], v[66:69]
	s_setprio 0
	s_barrier
	s_add_i32 s28, s48, s35
	v_lshl_add_u64 v[210:211], v[210:211], 0, s[80:81]
	s_mov_b32 m0, s28
	ds_read_b128 v[178:181], v152 offset:49152
	ds_read_b128 v[182:185], v152 offset:50176
	ds_read_b128 v[186:189], v152 offset:51200
	ds_read_b128 v[190:193], v152 offset:52224
	ds_read_b128 v[194:197], v152 offset:53248
	ds_read_b128 v[198:201], v152 offset:54272
	ds_read_b128 v[202:205], v152 offset:55296
	ds_read_b128 v[206:209], v152 offset:56320
	global_load_lds_dwordx4 v[210:211], off
	s_add_i32 m0, s28, 0x2000
	s_add_u32 s26, s26, 0x40080
	v_lshl_add_u64 v[210:211], v[212:213], 0, s[80:81]
	s_addc_u32 s27, s27, 0
	s_add_i32 s28, s49, s35
	global_load_lds_dwordx4 v[210:211], off
	v_lshl_add_u64 v[210:211], s[26:27], 0, v[0:1]
	s_mov_b32 m0, s28
	s_nop 0
	global_load_lds_dwordx4 v[210:211], off
	v_lshl_add_u64 v[210:211], s[26:27], 0, v[134:135]
	s_add_i32 m0, s28, 0x2000
	s_nop 0
	global_load_lds_dwordx4 v[210:211], off
	v_lshl_add_u64 v[210:211], v[214:215], 0, s[80:81]
	s_mov_b32 m0, s41
	s_nop 0
	global_load_lds_dwordx4 v[210:211], off
	v_lshl_add_u64 v[210:211], v[216:217], 0, s[80:81]
	s_mov_b32 m0, s42
	s_nop 0
	global_load_lds_dwordx4 v[210:211], off
	s_waitcnt vmcnt(8)
	s_waitcnt lgkmcnt(0)
	s_barrier
	s_setprio 1
	s_waitcnt lgkmcnt(0)
	v_mfma_f32_16x16x32_bf16 v[62:65], v[130:133], v[178:181], v[62:65]
	v_mfma_f32_16x16x32_bf16 v[58:61], v[154:157], v[178:181], v[58:61]
	v_mfma_f32_16x16x32_bf16 v[46:49], v[130:133], v[186:189], v[46:49]
	v_mfma_f32_16x16x32_bf16 v[42:45], v[154:157], v[186:189], v[42:45]
	v_mfma_f32_16x16x32_bf16 v[30:33], v[130:133], v[194:197], v[30:33]
	v_mfma_f32_16x16x32_bf16 v[26:29], v[154:157], v[194:197], v[26:29]
	v_mfma_f32_16x16x32_bf16 v[22:25], v[130:133], v[202:205], v[22:25]
	v_mfma_f32_16x16x32_bf16 v[18:21], v[154:157], v[202:205], v[18:21]
	v_mfma_f32_16x16x32_bf16 v[62:65], v[146:149], v[182:185], v[62:65]
	v_mfma_f32_16x16x32_bf16 v[58:61], v[158:161], v[182:185], v[58:61]
	v_mfma_f32_16x16x32_bf16 v[46:49], v[146:149], v[190:193], v[46:49]
	v_mfma_f32_16x16x32_bf16 v[42:45], v[158:161], v[190:193], v[42:45]
	v_mfma_f32_16x16x32_bf16 v[30:33], v[146:149], v[198:201], v[30:33]
	v_mfma_f32_16x16x32_bf16 v[26:29], v[158:161], v[198:201], v[26:29]
	v_mfma_f32_16x16x32_bf16 v[22:25], v[146:149], v[206:209], v[22:25]
	v_mfma_f32_16x16x32_bf16 v[18:21], v[158:161], v[206:209], v[18:21]
	s_setprio 0
	s_setprio 1
	v_mfma_f32_16x16x32_bf16 v[54:57], v[162:165], v[178:181], v[54:57]
	v_mfma_f32_16x16x32_bf16 v[50:53], v[170:173], v[178:181], v[50:53]
	v_mfma_f32_16x16x32_bf16 v[38:41], v[162:165], v[186:189], v[38:41]
	v_mfma_f32_16x16x32_bf16 v[34:37], v[170:173], v[186:189], v[34:37]
	v_mfma_f32_16x16x32_bf16 v[14:17], v[162:165], v[194:197], v[14:17]
	v_mfma_f32_16x16x32_bf16 v[10:13], v[170:173], v[194:197], v[10:13]
	v_mfma_f32_16x16x32_bf16 v[6:9], v[162:165], v[202:205], v[6:9]
	v_mfma_f32_16x16x32_bf16 v[2:5], v[170:173], v[202:205], v[2:5]
	v_mfma_f32_16x16x32_bf16 v[54:57], v[166:169], v[182:185], v[54:57]
	v_mfma_f32_16x16x32_bf16 v[50:53], v[174:177], v[182:185], v[50:53]
	v_mfma_f32_16x16x32_bf16 v[38:41], v[166:169], v[190:193], v[38:41]
	v_mfma_f32_16x16x32_bf16 v[34:37], v[174:177], v[190:193], v[34:37]
	v_mfma_f32_16x16x32_bf16 v[14:17], v[166:169], v[198:201], v[14:17]
	v_mfma_f32_16x16x32_bf16 v[10:13], v[174:177], v[198:201], v[10:13]
	v_mfma_f32_16x16x32_bf16 v[6:9], v[166:169], v[206:209], v[6:9]
	v_mfma_f32_16x16x32_bf16 v[2:5], v[174:177], v[206:209], v[2:5]
	s_setprio 0
	s_barrier
	s_add_i32 s47, s47, 2
	s_add_u32 s24, s24, 0x100
	s_addc_u32 s25, s25, 0
	s_add_u32 s45, s45, 0x100
	s_addc_u32 s46, s46, 0
	s_cmp_gt_u32 s47, 13
	s_cbranch_scc0 .LBB0_1817
	s_and_b64 vcc, exec, s[10:11]
	s_cbranch_vccz .LBB0_1820
	s_barrier

.LBB0_1847:
	s_add_u32 s28, s26, 0xfffc0080
	s_addc_u32 s29, s27, -1
	s_add_i32 s50, 0, 0x10000
	s_cmp_eq_u32 s49, 12
	s_cselect_b32 s31, s13, s29
	s_cselect_b32 s30, s23, s28
	s_cselect_b32 s29, s15, s48
	s_cselect_b32 s28, s46, s47
	s_add_i32 s52, 0, 0x14000
	v_add_u32_e32 v142, s50, v166
	v_add_u32_e32 v162, s52, v166
	ds_read_b128 v[130:133], v142
	ds_read_b128 v[134:137], v142 offset:1024
	ds_read_b128 v[138:141], v142 offset:2048
	ds_read_b128 v[142:145], v142 offset:3072
	ds_read_b128 v[158:161], v162
	ds_read_b128 v[168:171], v162 offset:1024
	ds_read_b128 v[172:175], v162 offset:2048
	ds_read_b128 v[176:179], v162 offset:3072
	v_lshl_add_u64 v[162:163], s[26:27], 0, v[154:155]
	s_add_i32 m0, s25, 0xc000
	ds_read_b128 v[180:183], v167
	ds_read_b128 v[184:187], v167 offset:1024
	ds_read_b128 v[188:191], v167 offset:2048
	ds_read_b128 v[192:195], v167 offset:3072
	ds_read_b128 v[196:199], v167 offset:4096
	ds_read_b128 v[200:203], v167 offset:5120
	ds_read_b128 v[204:207], v167 offset:6144
	ds_read_b128 v[208:211], v167 offset:7168
	global_load_lds_dwordx4 v[162:163], off
	v_lshl_add_u64 v[162:163], s[26:27], 0, v[156:157]
	s_add_i32 m0, s25, 0xe000
	s_nop 0
	global_load_lds_dwordx4 v[162:163], off
	s_waitcnt vmcnt(8)
	s_waitcnt lgkmcnt(0)
	s_barrier
	s_setprio 1
	s_waitcnt lgkmcnt(0)
	v_mfma_f32_16x16x32_bf16 v[126:129], v[130:133], v[180:183], v[126:129]
	v_mfma_f32_16x16x32_bf16 v[122:125], v[138:141], v[180:183], v[122:125]
	v_mfma_f32_16x16x32_bf16 v[110:113], v[130:133], v[188:191], v[110:113]
	v_mfma_f32_16x16x32_bf16 v[106:109], v[138:141], v[188:191], v[106:109]
	v_mfma_f32_16x16x32_bf16 v[94:97], v[130:133], v[196:199], v[94:97]
	v_mfma_f32_16x16x32_bf16 v[90:93], v[138:141], v[196:199], v[90:93]
	v_mfma_f32_16x16x32_bf16 v[78:81], v[130:133], v[204:207], v[78:81]
	v_mfma_f32_16x16x32_bf16 v[74:77], v[138:141], v[204:207], v[74:77]
	v_mfma_f32_16x16x32_bf16 v[126:129], v[134:137], v[184:187], v[126:129]
	v_mfma_f32_16x16x32_bf16 v[122:125], v[142:145], v[184:187], v[122:125]
	v_mfma_f32_16x16x32_bf16 v[110:113], v[134:137], v[192:195], v[110:113]
	v_mfma_f32_16x16x32_bf16 v[106:109], v[142:145], v[192:195], v[106:109]
	v_mfma_f32_16x16x32_bf16 v[94:97], v[134:137], v[200:203], v[94:97]
	v_mfma_f32_16x16x32_bf16 v[90:93], v[142:145], v[200:203], v[90:93]
	v_mfma_f32_16x16x32_bf16 v[78:81], v[134:137], v[208:211], v[78:81]
	v_mfma_f32_16x16x32_bf16 v[74:77], v[142:145], v[208:211], v[74:77]
	s_setprio 0
	s_setprio 1
	v_mfma_f32_16x16x32_bf16 v[118:121], v[158:161], v[180:183], v[118:121]
	v_mfma_f32_16x16x32_bf16 v[114:117], v[172:175], v[180:183], v[114:117]
	v_mfma_f32_16x16x32_bf16 v[102:105], v[158:161], v[188:191], v[102:105]
	v_mfma_f32_16x16x32_bf16 v[98:101], v[172:175], v[188:191], v[98:101]
	v_mfma_f32_16x16x32_bf16 v[86:89], v[158:161], v[196:199], v[86:89]
	v_mfma_f32_16x16x32_bf16 v[82:85], v[172:175], v[196:199], v[82:85]
	v_mfma_f32_16x16x32_bf16 v[70:73], v[158:161], v[204:207], v[70:73]
	v_mfma_f32_16x16x32_bf16 v[66:69], v[172:175], v[204:207], v[66:69]
	v_mfma_f32_16x16x32_bf16 v[118:121], v[168:171], v[184:187], v[118:121]
	v_mfma_f32_16x16x32_bf16 v[114:117], v[176:179], v[184:187], v[114:117]
	v_mfma_f32_16x16x32_bf16 v[102:105], v[168:171], v[192:195], v[102:105]
	v_mfma_f32_16x16x32_bf16 v[98:101], v[176:179], v[192:195], v[98:101]
	v_mfma_f32_16x16x32_bf16 v[86:89], v[168:171], v[200:203], v[86:89]
	v_mfma_f32_16x16x32_bf16 v[82:85], v[176:179], v[200:203], v[82:85]
	v_mfma_f32_16x16x32_bf16 v[70:73], v[168:171], v[208:211], v[70:73]
	v_mfma_f32_16x16x32_bf16 v[66:69], v[176:179], v[208:211], v[66:69]
	s_setprio 0
	s_barrier
	s_add_i32 s50, s50, s39
	v_lshl_add_u64 v[162:163], s[28:29], 0, v[0:1]
	s_mov_b32 m0, s50
	ds_read_b128 v[180:183], v167 offset:16384
	ds_read_b128 v[184:187], v167 offset:17408
	ds_read_b128 v[188:191], v167 offset:18432
	ds_read_b128 v[192:195], v167 offset:19456
	ds_read_b128 v[196:199], v167 offset:20480
	ds_read_b128 v[200:203], v167 offset:21504
	ds_read_b128 v[204:207], v167 offset:22528
	ds_read_b128 v[208:211], v167 offset:23552
	global_load_lds_dwordx4 v[162:163], off
	s_add_i32 m0, s50, 0x2000
	s_add_u32 s50, s28, 0x40000
	v_lshl_add_u64 v[212:213], s[28:29], 0, v[146:147]
	s_addc_u32 s51, s29, 0
	s_add_i32 s52, s52, s39
	global_load_lds_dwordx4 v[212:213], off
	v_lshl_add_u64 v[214:215], s[50:51], 0, v[0:1]
	s_mov_b32 m0, s52
	v_lshl_add_u64 v[216:217], s[30:31], 0, v[148:149]
	global_load_lds_dwordx4 v[214:215], off
	v_lshl_add_u64 v[214:215], s[50:51], 0, v[146:147]
	s_add_i32 m0, s52, 0x2000
	s_nop 0
	global_load_lds_dwordx4 v[214:215], off
	s_waitcnt vmcnt(6)
	s_waitcnt lgkmcnt(0)
	s_barrier
	s_setprio 1
	s_waitcnt lgkmcnt(0)
	v_mfma_f32_16x16x32_bf16 v[62:65], v[130:133], v[180:183], v[62:65]
	v_mfma_f32_16x16x32_bf16 v[58:61], v[138:141], v[180:183], v[58:61]
	v_mfma_f32_16x16x32_bf16 v[46:49], v[130:133], v[188:191], v[46:49]
	v_mfma_f32_16x16x32_bf16 v[42:45], v[138:141], v[188:191], v[42:45]
	v_mfma_f32_16x16x32_bf16 v[30:33], v[130:133], v[196:199], v[30:33]
	v_mfma_f32_16x16x32_bf16 v[26:29], v[138:141], v[196:199], v[26:29]
	v_mfma_f32_16x16x32_bf16 v[14:17], v[130:133], v[204:207], v[14:17]
	v_mfma_f32_16x16x32_bf16 v[10:13], v[138:141], v[204:207], v[10:13]
	v_mfma_f32_16x16x32_bf16 v[62:65], v[134:137], v[184:187], v[62:65]
	v_mfma_f32_16x16x32_bf16 v[58:61], v[142:145], v[184:187], v[58:61]
	v_mfma_f32_16x16x32_bf16 v[46:49], v[134:137], v[192:195], v[46:49]
	v_mfma_f32_16x16x32_bf16 v[42:45], v[142:145], v[192:195], v[42:45]
	v_mfma_f32_16x16x32_bf16 v[30:33], v[134:137], v[200:203], v[30:33]
	v_mfma_f32_16x16x32_bf16 v[26:29], v[142:145], v[200:203], v[26:29]
	v_mfma_f32_16x16x32_bf16 v[14:17], v[134:137], v[208:211], v[14:17]
	v_mfma_f32_16x16x32_bf16 v[10:13], v[142:145], v[208:211], v[10:13]
	s_setprio 0
	s_setprio 1
	v_mfma_f32_16x16x32_bf16 v[54:57], v[158:161], v[180:183], v[54:57]
	v_mfma_f32_16x16x32_bf16 v[50:53], v[172:175], v[180:183], v[50:53]
	v_mfma_f32_16x16x32_bf16 v[38:41], v[158:161], v[188:191], v[38:41]
	v_mfma_f32_16x16x32_bf16 v[34:37], v[172:175], v[188:191], v[34:37]
	v_mfma_f32_16x16x32_bf16 v[22:25], v[158:161], v[196:199], v[22:25]
	v_mfma_f32_16x16x32_bf16 v[18:21], v[172:175], v[196:199], v[18:21]
	v_mfma_f32_16x16x32_bf16 v[6:9], v[158:161], v[204:207], v[6:9]
	v_mfma_f32_16x16x32_bf16 v[2:5], v[172:175], v[204:207], v[2:5]
	v_mfma_f32_16x16x32_bf16 v[54:57], v[168:171], v[184:187], v[54:57]
	v_mfma_f32_16x16x32_bf16 v[50:53], v[176:179], v[184:187], v[50:53]
	v_mfma_f32_16x16x32_bf16 v[38:41], v[168:171], v[192:195], v[38:41]
	v_mfma_f32_16x16x32_bf16 v[34:37], v[176:179], v[192:195], v[34:37]
	v_mfma_f32_16x16x32_bf16 v[22:25], v[168:171], v[200:203], v[22:25]
	v_mfma_f32_16x16x32_bf16 v[18:21], v[176:179], v[200:203], v[18:21]
	v_mfma_f32_16x16x32_bf16 v[6:9], v[168:171], v[208:211], v[6:9]
	v_mfma_f32_16x16x32_bf16 v[2:5], v[176:179], v[208:211], v[2:5]
	s_setprio 0
	s_barrier
	s_add_i32 s50, 0, 0x18000
	s_add_i32 s51, 0, 0x1c000
	v_add_u32_e32 v142, s50, v166
	v_add_u32_e32 v176, s51, v166
	ds_read_b128 v[130:133], v142
	ds_read_b128 v[134:137], v142 offset:1024
	ds_read_b128 v[138:141], v142 offset:2048
	ds_read_b128 v[142:145], v142 offset:3072
	ds_read_b128 v[158:161], v176
	ds_read_b128 v[168:171], v176 offset:1024
	ds_read_b128 v[172:175], v176 offset:2048
	ds_read_b128 v[176:179], v176 offset:3072
	v_lshl_add_u64 v[214:215], s[30:31], 0, v[150:151]
	s_mov_b32 m0, s25
	s_nop 0
	global_load_lds_dwordx4 v[214:215], off
	s_mov_b32 m0, s40
	s_nop 0
	global_load_lds_dwordx4 v[216:217], off
	s_add_u32 s30, s30, 0x40000
	s_addc_u32 s31, s31, 0
	s_mov_b32 m0, s41
	v_lshl_add_u64 v[218:219], s[30:31], 0, v[150:151]
	ds_read_b128 v[180:183], v167 offset:32768
	ds_read_b128 v[184:187], v167 offset:33792
	ds_read_b128 v[188:191], v167 offset:34816
	ds_read_b128 v[192:195], v167 offset:35840
	ds_read_b128 v[196:199], v167 offset:36864
	ds_read_b128 v[200:203], v167 offset:37888
	ds_read_b128 v[204:207], v167 offset:38912
	ds_read_b128 v[208:211], v167 offset:39936
	global_load_lds_dwordx4 v[218:219], off
	v_lshl_add_u64 v[218:219], s[30:31], 0, v[148:149]
	s_mov_b32 m0, s42
	s_nop 0
	global_load_lds_dwordx4 v[218:219], off
	s_waitcnt vmcnt(8)
	s_waitcnt lgkmcnt(0)
	s_barrier
	s_setprio 1
	s_waitcnt lgkmcnt(0)
	v_mfma_f32_16x16x32_bf16 v[126:129], v[130:133], v[180:183], v[126:129]
	v_mfma_f32_16x16x32_bf16 v[122:125], v[138:141], v[180:183], v[122:125]
	v_mfma_f32_16x16x32_bf16 v[110:113], v[130:133], v[188:191], v[110:113]
	v_mfma_f32_16x16x32_bf16 v[106:109], v[138:141], v[188:191], v[106:109]
	v_mfma_f32_16x16x32_bf16 v[94:97], v[130:133], v[196:199], v[94:97]
	v_mfma_f32_16x16x32_bf16 v[90:93], v[138:141], v[196:199], v[90:93]
	v_mfma_f32_16x16x32_bf16 v[78:81], v[130:133], v[204:207], v[78:81]
	v_mfma_f32_16x16x32_bf16 v[74:77], v[138:141], v[204:207], v[74:77]
	v_mfma_f32_16x16x32_bf16 v[126:129], v[134:137], v[184:187], v[126:129]
	v_mfma_f32_16x16x32_bf16 v[122:125], v[142:145], v[184:187], v[122:125]
	v_mfma_f32_16x16x32_bf16 v[110:113], v[134:137], v[192:195], v[110:113]
	v_mfma_f32_16x16x32_bf16 v[106:109], v[142:145], v[192:195], v[106:109]
	v_mfma_f32_16x16x32_bf16 v[94:97], v[134:137], v[200:203], v[94:97]
	v_mfma_f32_16x16x32_bf16 v[90:93], v[142:145], v[200:203], v[90:93]
	v_mfma_f32_16x16x32_bf16 v[78:81], v[134:137], v[208:211], v[78:81]
	v_mfma_f32_16x16x32_bf16 v[74:77], v[142:145], v[208:211], v[74:77]
	s_setprio 0
	s_setprio 1
	v_mfma_f32_16x16x32_bf16 v[118:121], v[158:161], v[180:183], v[118:121]
	v_mfma_f32_16x16x32_bf16 v[114:117], v[172:175], v[180:183], v[114:117]
	v_mfma_f32_16x16x32_bf16 v[102:105], v[158:161], v[188:191], v[102:105]
	v_mfma_f32_16x16x32_bf16 v[98:101], v[172:175], v[188:191], v[98:101]
	v_mfma_f32_16x16x32_bf16 v[86:89], v[158:161], v[196:199], v[86:89]
	v_mfma_f32_16x16x32_bf16 v[82:85], v[172:175], v[196:199], v[82:85]
	v_mfma_f32_16x16x32_bf16 v[70:73], v[158:161], v[204:207], v[70:73]
	v_mfma_f32_16x16x32_bf16 v[66:69], v[172:175], v[204:207], v[66:69]
	v_mfma_f32_16x16x32_bf16 v[118:121], v[168:171], v[184:187], v[118:121]
	v_mfma_f32_16x16x32_bf16 v[114:117], v[176:179], v[184:187], v[114:117]
	v_mfma_f32_16x16x32_bf16 v[102:105], v[168:171], v[192:195], v[102:105]
	v_mfma_f32_16x16x32_bf16 v[98:101], v[176:179], v[192:195], v[98:101]
	v_mfma_f32_16x16x32_bf16 v[86:89], v[168:171], v[200:203], v[86:89]
	v_mfma_f32_16x16x32_bf16 v[82:85], v[176:179], v[200:203], v[82:85]
	v_mfma_f32_16x16x32_bf16 v[70:73], v[168:171], v[208:211], v[70:73]
	v_mfma_f32_16x16x32_bf16 v[66:69], v[176:179], v[208:211], v[66:69]
	s_setprio 0
	s_barrier
	s_add_i32 s30, s50, s39
	v_lshl_add_u64 v[162:163], v[162:163], 0, s[80:81]
	s_mov_b32 m0, s30
	ds_read_b128 v[180:183], v167 offset:49152
	ds_read_b128 v[184:187], v167 offset:50176
	ds_read_b128 v[188:191], v167 offset:51200
	ds_read_b128 v[192:195], v167 offset:52224
	ds_read_b128 v[196:199], v167 offset:53248
	ds_read_b128 v[200:203], v167 offset:54272
	ds_read_b128 v[204:207], v167 offset:55296
	ds_read_b128 v[208:211], v167 offset:56320
	global_load_lds_dwordx4 v[162:163], off
	s_add_i32 m0, s30, 0x2000
	s_add_u32 s28, s28, 0x40080
	v_lshl_add_u64 v[162:163], v[212:213], 0, s[80:81]
	s_addc_u32 s29, s29, 0
	s_add_i32 s30, s51, s39
	global_load_lds_dwordx4 v[162:163], off
	v_lshl_add_u64 v[162:163], s[28:29], 0, v[0:1]
	s_mov_b32 m0, s30
	s_nop 0
	global_load_lds_dwordx4 v[162:163], off
	v_lshl_add_u64 v[162:163], s[28:29], 0, v[146:147]
	s_add_i32 m0, s30, 0x2000
	s_nop 0
	global_load_lds_dwordx4 v[162:163], off
	v_lshl_add_u64 v[162:163], v[214:215], 0, s[80:81]
	s_mov_b32 m0, s43
	s_nop 0
	global_load_lds_dwordx4 v[162:163], off
	v_lshl_add_u64 v[162:163], v[216:217], 0, s[80:81]
	s_mov_b32 m0, s44
	s_nop 0
	global_load_lds_dwordx4 v[162:163], off
	s_waitcnt vmcnt(8)
	s_waitcnt lgkmcnt(0)
	s_barrier
	s_setprio 1
	s_waitcnt lgkmcnt(0)
	v_mfma_f32_16x16x32_bf16 v[62:65], v[130:133], v[180:183], v[62:65]
	v_mfma_f32_16x16x32_bf16 v[58:61], v[138:141], v[180:183], v[58:61]
	v_mfma_f32_16x16x32_bf16 v[46:49], v[130:133], v[188:191], v[46:49]
	v_mfma_f32_16x16x32_bf16 v[42:45], v[138:141], v[188:191], v[42:45]
	v_mfma_f32_16x16x32_bf16 v[30:33], v[130:133], v[196:199], v[30:33]
	v_mfma_f32_16x16x32_bf16 v[26:29], v[138:141], v[196:199], v[26:29]
	v_mfma_f32_16x16x32_bf16 v[14:17], v[130:133], v[204:207], v[14:17]
	v_mfma_f32_16x16x32_bf16 v[10:13], v[138:141], v[204:207], v[10:13]
	v_mfma_f32_16x16x32_bf16 v[62:65], v[134:137], v[184:187], v[62:65]
	v_mfma_f32_16x16x32_bf16 v[58:61], v[142:145], v[184:187], v[58:61]
	v_mfma_f32_16x16x32_bf16 v[46:49], v[134:137], v[192:195], v[46:49]
	v_mfma_f32_16x16x32_bf16 v[42:45], v[142:145], v[192:195], v[42:45]
	v_mfma_f32_16x16x32_bf16 v[30:33], v[134:137], v[200:203], v[30:33]
	v_mfma_f32_16x16x32_bf16 v[26:29], v[142:145], v[200:203], v[26:29]
	v_mfma_f32_16x16x32_bf16 v[14:17], v[134:137], v[208:211], v[14:17]
	v_mfma_f32_16x16x32_bf16 v[10:13], v[142:145], v[208:211], v[10:13]
	s_setprio 0
	s_setprio 1
	v_mfma_f32_16x16x32_bf16 v[54:57], v[158:161], v[180:183], v[54:57]
	v_mfma_f32_16x16x32_bf16 v[50:53], v[172:175], v[180:183], v[50:53]
	v_mfma_f32_16x16x32_bf16 v[38:41], v[158:161], v[188:191], v[38:41]
	v_mfma_f32_16x16x32_bf16 v[34:37], v[172:175], v[188:191], v[34:37]
	v_mfma_f32_16x16x32_bf16 v[22:25], v[158:161], v[196:199], v[22:25]
	v_mfma_f32_16x16x32_bf16 v[18:21], v[172:175], v[196:199], v[18:21]
	v_mfma_f32_16x16x32_bf16 v[6:9], v[158:161], v[204:207], v[6:9]
	v_mfma_f32_16x16x32_bf16 v[2:5], v[172:175], v[204:207], v[2:5]
	v_mfma_f32_16x16x32_bf16 v[54:57], v[168:171], v[184:187], v[54:57]
	v_mfma_f32_16x16x32_bf16 v[50:53], v[176:179], v[184:187], v[50:53]
	v_mfma_f32_16x16x32_bf16 v[38:41], v[168:171], v[192:195], v[38:41]
	v_mfma_f32_16x16x32_bf16 v[34:37], v[176:179], v[192:195], v[34:37]
	v_mfma_f32_16x16x32_bf16 v[22:25], v[168:171], v[200:203], v[22:25]
	v_mfma_f32_16x16x32_bf16 v[18:21], v[176:179], v[200:203], v[18:21]
	v_mfma_f32_16x16x32_bf16 v[6:9], v[168:171], v[208:211], v[6:9]
	v_mfma_f32_16x16x32_bf16 v[2:5], v[176:179], v[208:211], v[2:5]
	s_setprio 0
	s_barrier
	s_add_i32 s49, s49, 2
	s_add_u32 s26, s26, 0x100
	s_addc_u32 s27, s27, 0
	s_add_u32 s47, s47, 0x100
	s_addc_u32 s48, s48, 0
	s_cmp_gt_u32 s49, 13
	s_cbranch_scc0 .LBB0_1847
	s_and_b64 vcc, exec, s[10:11]
	s_cbranch_vccz .LBB0_1850
	s_barrier

.LBB0_1877:
	s_add_u32 s26, s24, 0xfffc0080
	s_addc_u32 s27, s25, -1
	s_add_i32 s50, 0, 0x10000
	s_cmp_eq_u32 s49, 12
	s_cselect_b32 s29, s1, s27
	s_cselect_b32 s28, s13, s26
	v_add_u32_e32 v0, s50, v171
	s_cselect_b32 s27, s15, s48
	s_cselect_b32 s26, s46, s47
	s_add_i32 s52, 0, 0x14000
	ds_read_b128 v[98:101], v0
	ds_read_b128 v[102:105], v0 offset:1024
	ds_read_b128 v[106:109], v0 offset:2048
	ds_read_b128 v[110:113], v0 offset:3072
	v_add_u32_e32 v0, s52, v171
	ds_read_b128 v[146:149], v0
	ds_read_b128 v[164:167], v0 offset:1024
	ds_read_b128 v[174:177], v0 offset:2048
	ds_read_b128 v[178:181], v0 offset:3072
	v_lshl_add_u64 v[214:215], s[24:25], 0, v[160:161]
	s_add_i32 m0, s23, 0xc000
	ds_read_b128 v[182:185], v173
	ds_read_b128 v[186:189], v173 offset:1024
	ds_read_b128 v[190:193], v173 offset:2048
	ds_read_b128 v[194:197], v173 offset:3072
	ds_read_b128 v[198:201], v173 offset:4096
	ds_read_b128 v[202:205], v173 offset:5120
	ds_read_b128 v[206:209], v173 offset:6144
	ds_read_b128 v[210:213], v173 offset:7168
	global_load_lds_dwordx4 v[214:215], off
	v_lshl_add_u64 v[214:215], s[24:25], 0, v[162:163]
	s_add_i32 m0, s23, 0xe000
	s_nop 0
	global_load_lds_dwordx4 v[214:215], off
	s_waitcnt vmcnt(8)
	s_waitcnt lgkmcnt(0)
	s_barrier
	s_setprio 1
	s_waitcnt lgkmcnt(0)
	v_mfma_f32_16x16x32_bf16 v[142:145], v[98:101], v[182:185], v[142:145]
	v_mfma_f32_16x16x32_bf16 v[138:141], v[106:109], v[182:185], v[138:141]
	v_mfma_f32_16x16x32_bf16 v[126:129], v[98:101], v[190:193], v[126:129]
	v_mfma_f32_16x16x32_bf16 v[122:125], v[106:109], v[190:193], v[122:125]
	v_mfma_f32_16x16x32_bf16 v[94:97], v[98:101], v[198:201], v[94:97]
	v_mfma_f32_16x16x32_bf16 v[90:93], v[106:109], v[198:201], v[90:93]
	v_mfma_f32_16x16x32_bf16 v[78:81], v[98:101], v[206:209], v[78:81]
	v_mfma_f32_16x16x32_bf16 v[74:77], v[106:109], v[206:209], v[74:77]
	v_mfma_f32_16x16x32_bf16 v[142:145], v[102:105], v[186:189], v[142:145]
	v_mfma_f32_16x16x32_bf16 v[138:141], v[110:113], v[186:189], v[138:141]
	v_mfma_f32_16x16x32_bf16 v[126:129], v[102:105], v[194:197], v[126:129]
	v_mfma_f32_16x16x32_bf16 v[122:125], v[110:113], v[194:197], v[122:125]
	v_mfma_f32_16x16x32_bf16 v[94:97], v[102:105], v[202:205], v[94:97]
	v_mfma_f32_16x16x32_bf16 v[90:93], v[110:113], v[202:205], v[90:93]
	v_mfma_f32_16x16x32_bf16 v[78:81], v[102:105], v[210:213], v[78:81]
	v_mfma_f32_16x16x32_bf16 v[74:77], v[110:113], v[210:213], v[74:77]
	s_setprio 0
	s_setprio 1
	v_mfma_f32_16x16x32_bf16 v[134:137], v[146:149], v[182:185], v[134:137]
	v_mfma_f32_16x16x32_bf16 v[130:133], v[174:177], v[182:185], v[130:133]
	v_mfma_f32_16x16x32_bf16 v[118:121], v[146:149], v[190:193], v[118:121]
	v_mfma_f32_16x16x32_bf16 v[114:117], v[174:177], v[190:193], v[114:117]
	v_mfma_f32_16x16x32_bf16 v[86:89], v[146:149], v[198:201], v[86:89]
	v_mfma_f32_16x16x32_bf16 v[82:85], v[174:177], v[198:201], v[82:85]
	v_mfma_f32_16x16x32_bf16 v[70:73], v[146:149], v[206:209], v[70:73]
	v_mfma_f32_16x16x32_bf16 v[66:69], v[174:177], v[206:209], v[66:69]
	v_mfma_f32_16x16x32_bf16 v[134:137], v[164:167], v[186:189], v[134:137]
	v_mfma_f32_16x16x32_bf16 v[130:133], v[178:181], v[186:189], v[130:133]
	v_mfma_f32_16x16x32_bf16 v[118:121], v[164:167], v[194:197], v[118:121]
	v_mfma_f32_16x16x32_bf16 v[114:117], v[178:181], v[194:197], v[114:117]
	v_mfma_f32_16x16x32_bf16 v[86:89], v[164:167], v[202:205], v[86:89]
	v_mfma_f32_16x16x32_bf16 v[82:85], v[178:181], v[202:205], v[82:85]
	v_mfma_f32_16x16x32_bf16 v[70:73], v[164:167], v[210:213], v[70:73]
	v_mfma_f32_16x16x32_bf16 v[66:69], v[178:181], v[210:213], v[66:69]
	s_setprio 0
	s_barrier
	s_add_i32 s50, s50, s35
	v_lshl_add_u64 v[214:215], s[26:27], 0, v[154:155]
	s_mov_b32 m0, s50
	ds_read_b128 v[182:185], v173 offset:16384
	ds_read_b128 v[186:189], v173 offset:17408
	ds_read_b128 v[190:193], v173 offset:18432
	ds_read_b128 v[194:197], v173 offset:19456
	ds_read_b128 v[198:201], v173 offset:20480
	ds_read_b128 v[202:205], v173 offset:21504
	ds_read_b128 v[206:209], v173 offset:22528
	ds_read_b128 v[210:213], v173 offset:23552
	global_load_lds_dwordx4 v[214:215], off
	s_add_i32 m0, s50, 0x2000
	s_add_u32 s50, s26, 0x40000
	v_lshl_add_u64 v[216:217], s[26:27], 0, v[150:151]
	s_addc_u32 s51, s27, 0
	s_add_i32 s52, s52, s35
	global_load_lds_dwordx4 v[216:217], off
	v_lshl_add_u64 v[218:219], s[50:51], 0, v[154:155]
	s_mov_b32 m0, s52
	v_lshl_add_u64 v[220:221], s[28:29], 0, v[152:153]
	global_load_lds_dwordx4 v[218:219], off
	v_lshl_add_u64 v[218:219], s[50:51], 0, v[150:151]
	s_add_i32 m0, s52, 0x2000
	s_nop 0
	global_load_lds_dwordx4 v[218:219], off
	s_waitcnt vmcnt(6)
	s_waitcnt lgkmcnt(0)
	s_barrier
	s_setprio 1
	s_waitcnt lgkmcnt(0)
	v_mfma_f32_16x16x32_bf16 v[62:65], v[98:101], v[182:185], v[62:65]
	v_mfma_f32_16x16x32_bf16 v[58:61], v[106:109], v[182:185], v[58:61]
	v_mfma_f32_16x16x32_bf16 v[46:49], v[98:101], v[190:193], v[46:49]
	v_mfma_f32_16x16x32_bf16 v[42:45], v[106:109], v[190:193], v[42:45]
	v_mfma_f32_16x16x32_bf16 v[30:33], v[98:101], v[198:201], v[30:33]
	v_mfma_f32_16x16x32_bf16 v[26:29], v[106:109], v[198:201], v[26:29]
	v_mfma_f32_16x16x32_bf16 v[14:17], v[98:101], v[206:209], v[14:17]
	v_mfma_f32_16x16x32_bf16 v[10:13], v[106:109], v[206:209], v[10:13]
	v_mfma_f32_16x16x32_bf16 v[62:65], v[102:105], v[186:189], v[62:65]
	v_mfma_f32_16x16x32_bf16 v[58:61], v[110:113], v[186:189], v[58:61]
	v_mfma_f32_16x16x32_bf16 v[46:49], v[102:105], v[194:197], v[46:49]
	v_mfma_f32_16x16x32_bf16 v[42:45], v[110:113], v[194:197], v[42:45]
	v_mfma_f32_16x16x32_bf16 v[30:33], v[102:105], v[202:205], v[30:33]
	v_mfma_f32_16x16x32_bf16 v[26:29], v[110:113], v[202:205], v[26:29]
	v_mfma_f32_16x16x32_bf16 v[14:17], v[102:105], v[210:213], v[14:17]
	v_mfma_f32_16x16x32_bf16 v[10:13], v[110:113], v[210:213], v[10:13]
	s_setprio 0
	s_setprio 1
	v_mfma_f32_16x16x32_bf16 v[54:57], v[146:149], v[182:185], v[54:57]
	v_mfma_f32_16x16x32_bf16 v[50:53], v[174:177], v[182:185], v[50:53]
	v_mfma_f32_16x16x32_bf16 v[38:41], v[146:149], v[190:193], v[38:41]
	v_mfma_f32_16x16x32_bf16 v[34:37], v[174:177], v[190:193], v[34:37]
	v_mfma_f32_16x16x32_bf16 v[22:25], v[146:149], v[198:201], v[22:25]
	v_mfma_f32_16x16x32_bf16 v[18:21], v[174:177], v[198:201], v[18:21]
	v_mfma_f32_16x16x32_bf16 v[6:9], v[146:149], v[206:209], v[6:9]
	v_mfma_f32_16x16x32_bf16 v[2:5], v[174:177], v[206:209], v[2:5]
	v_mfma_f32_16x16x32_bf16 v[54:57], v[164:167], v[186:189], v[54:57]
	v_mfma_f32_16x16x32_bf16 v[50:53], v[178:181], v[186:189], v[50:53]
	v_mfma_f32_16x16x32_bf16 v[38:41], v[164:167], v[194:197], v[38:41]
	v_mfma_f32_16x16x32_bf16 v[34:37], v[178:181], v[194:197], v[34:37]
	v_mfma_f32_16x16x32_bf16 v[22:25], v[164:167], v[202:205], v[22:25]
	v_mfma_f32_16x16x32_bf16 v[18:21], v[178:181], v[202:205], v[18:21]
	v_mfma_f32_16x16x32_bf16 v[6:9], v[164:167], v[210:213], v[6:9]
	v_mfma_f32_16x16x32_bf16 v[2:5], v[178:181], v[210:213], v[2:5]
	s_setprio 0
	s_barrier
	s_add_i32 s50, 0, 0x18000
	v_add_u32_e32 v0, s50, v171
	s_add_i32 s51, 0, 0x1c000
	ds_read_b128 v[98:101], v0
	ds_read_b128 v[102:105], v0 offset:1024
	ds_read_b128 v[106:109], v0 offset:2048
	ds_read_b128 v[110:113], v0 offset:3072
	v_add_u32_e32 v0, s51, v171
	ds_read_b128 v[146:149], v0
	ds_read_b128 v[164:167], v0 offset:1024
	ds_read_b128 v[174:177], v0 offset:2048
	ds_read_b128 v[178:181], v0 offset:3072
	v_lshl_add_u64 v[218:219], s[28:29], 0, v[156:157]
	s_mov_b32 m0, s23
	s_nop 0
	global_load_lds_dwordx4 v[218:219], off
	s_mov_b32 m0, s38
	s_nop 0
	global_load_lds_dwordx4 v[220:221], off
	s_add_u32 s28, s28, 0x40000
	s_addc_u32 s29, s29, 0
	s_mov_b32 m0, s39
	v_lshl_add_u64 v[222:223], s[28:29], 0, v[156:157]
	ds_read_b128 v[182:185], v173 offset:32768
	ds_read_b128 v[186:189], v173 offset:33792
	ds_read_b128 v[190:193], v173 offset:34816
	ds_read_b128 v[194:197], v173 offset:35840
	ds_read_b128 v[198:201], v173 offset:36864
	ds_read_b128 v[202:205], v173 offset:37888
	ds_read_b128 v[206:209], v173 offset:38912
	ds_read_b128 v[210:213], v173 offset:39936
	global_load_lds_dwordx4 v[222:223], off
	v_lshl_add_u64 v[222:223], s[28:29], 0, v[152:153]
	s_mov_b32 m0, s40
	s_nop 0
	global_load_lds_dwordx4 v[222:223], off
	s_waitcnt vmcnt(8)
	s_waitcnt lgkmcnt(0)
	s_barrier
	s_setprio 1
	s_waitcnt lgkmcnt(0)
	v_mfma_f32_16x16x32_bf16 v[142:145], v[98:101], v[182:185], v[142:145]
	v_mfma_f32_16x16x32_bf16 v[138:141], v[106:109], v[182:185], v[138:141]
	v_mfma_f32_16x16x32_bf16 v[126:129], v[98:101], v[190:193], v[126:129]
	v_mfma_f32_16x16x32_bf16 v[122:125], v[106:109], v[190:193], v[122:125]
	v_mfma_f32_16x16x32_bf16 v[94:97], v[98:101], v[198:201], v[94:97]
	v_mfma_f32_16x16x32_bf16 v[90:93], v[106:109], v[198:201], v[90:93]
	v_mfma_f32_16x16x32_bf16 v[78:81], v[98:101], v[206:209], v[78:81]
	v_mfma_f32_16x16x32_bf16 v[74:77], v[106:109], v[206:209], v[74:77]
	v_mfma_f32_16x16x32_bf16 v[142:145], v[102:105], v[186:189], v[142:145]
	v_mfma_f32_16x16x32_bf16 v[138:141], v[110:113], v[186:189], v[138:141]
	v_mfma_f32_16x16x32_bf16 v[126:129], v[102:105], v[194:197], v[126:129]
	v_mfma_f32_16x16x32_bf16 v[122:125], v[110:113], v[194:197], v[122:125]
	v_mfma_f32_16x16x32_bf16 v[94:97], v[102:105], v[202:205], v[94:97]
	v_mfma_f32_16x16x32_bf16 v[90:93], v[110:113], v[202:205], v[90:93]
	v_mfma_f32_16x16x32_bf16 v[78:81], v[102:105], v[210:213], v[78:81]
	v_mfma_f32_16x16x32_bf16 v[74:77], v[110:113], v[210:213], v[74:77]
	s_setprio 0
	s_setprio 1
	v_mfma_f32_16x16x32_bf16 v[134:137], v[146:149], v[182:185], v[134:137]
	v_mfma_f32_16x16x32_bf16 v[130:133], v[174:177], v[182:185], v[130:133]
	v_mfma_f32_16x16x32_bf16 v[118:121], v[146:149], v[190:193], v[118:121]
	v_mfma_f32_16x16x32_bf16 v[114:117], v[174:177], v[190:193], v[114:117]
	v_mfma_f32_16x16x32_bf16 v[86:89], v[146:149], v[198:201], v[86:89]
	v_mfma_f32_16x16x32_bf16 v[82:85], v[174:177], v[198:201], v[82:85]
	v_mfma_f32_16x16x32_bf16 v[70:73], v[146:149], v[206:209], v[70:73]
	v_mfma_f32_16x16x32_bf16 v[66:69], v[174:177], v[206:209], v[66:69]
	v_mfma_f32_16x16x32_bf16 v[134:137], v[164:167], v[186:189], v[134:137]
	v_mfma_f32_16x16x32_bf16 v[130:133], v[178:181], v[186:189], v[130:133]
	v_mfma_f32_16x16x32_bf16 v[118:121], v[164:167], v[194:197], v[118:121]
	v_mfma_f32_16x16x32_bf16 v[114:117], v[178:181], v[194:197], v[114:117]
	v_mfma_f32_16x16x32_bf16 v[86:89], v[164:167], v[202:205], v[86:89]
	v_mfma_f32_16x16x32_bf16 v[82:85], v[178:181], v[202:205], v[82:85]
	v_mfma_f32_16x16x32_bf16 v[70:73], v[164:167], v[210:213], v[70:73]
	v_mfma_f32_16x16x32_bf16 v[66:69], v[178:181], v[210:213], v[66:69]
	s_setprio 0
	s_barrier
	s_add_i32 s28, s50, s35
	v_lshl_add_u64 v[214:215], v[214:215], 0, s[80:81]
	s_mov_b32 m0, s28
	ds_read_b128 v[182:185], v173 offset:49152
	ds_read_b128 v[186:189], v173 offset:50176
	ds_read_b128 v[190:193], v173 offset:51200
	ds_read_b128 v[194:197], v173 offset:52224
	ds_read_b128 v[198:201], v173 offset:53248
	ds_read_b128 v[202:205], v173 offset:54272
	ds_read_b128 v[206:209], v173 offset:55296
	ds_read_b128 v[210:213], v173 offset:56320
	global_load_lds_dwordx4 v[214:215], off
	s_add_i32 m0, s28, 0x2000
	s_add_u32 s26, s26, 0x40080
	v_lshl_add_u64 v[214:215], v[216:217], 0, s[80:81]
	s_addc_u32 s27, s27, 0
	s_add_i32 s28, s51, s35
	global_load_lds_dwordx4 v[214:215], off
	v_lshl_add_u64 v[214:215], s[26:27], 0, v[154:155]
	s_mov_b32 m0, s28
	s_nop 0
	global_load_lds_dwordx4 v[214:215], off
	v_lshl_add_u64 v[214:215], s[26:27], 0, v[150:151]
	s_add_i32 m0, s28, 0x2000
	s_nop 0
	global_load_lds_dwordx4 v[214:215], off
	v_lshl_add_u64 v[214:215], v[218:219], 0, s[80:81]
	s_mov_b32 m0, s43
	s_nop 0
	global_load_lds_dwordx4 v[214:215], off
	v_lshl_add_u64 v[214:215], v[220:221], 0, s[80:81]
	s_mov_b32 m0, s44
	s_nop 0
	global_load_lds_dwordx4 v[214:215], off
	s_waitcnt vmcnt(8)
	s_waitcnt lgkmcnt(0)
	s_barrier
	s_setprio 1
	s_waitcnt lgkmcnt(0)
	v_mfma_f32_16x16x32_bf16 v[62:65], v[98:101], v[182:185], v[62:65]
	v_mfma_f32_16x16x32_bf16 v[58:61], v[106:109], v[182:185], v[58:61]
	v_mfma_f32_16x16x32_bf16 v[46:49], v[98:101], v[190:193], v[46:49]
	v_mfma_f32_16x16x32_bf16 v[42:45], v[106:109], v[190:193], v[42:45]
	v_mfma_f32_16x16x32_bf16 v[30:33], v[98:101], v[198:201], v[30:33]
	v_mfma_f32_16x16x32_bf16 v[26:29], v[106:109], v[198:201], v[26:29]
	v_mfma_f32_16x16x32_bf16 v[14:17], v[98:101], v[206:209], v[14:17]
	v_mfma_f32_16x16x32_bf16 v[10:13], v[106:109], v[206:209], v[10:13]
	v_mfma_f32_16x16x32_bf16 v[62:65], v[102:105], v[186:189], v[62:65]
	v_mfma_f32_16x16x32_bf16 v[58:61], v[110:113], v[186:189], v[58:61]
	v_mfma_f32_16x16x32_bf16 v[46:49], v[102:105], v[194:197], v[46:49]
	v_mfma_f32_16x16x32_bf16 v[42:45], v[110:113], v[194:197], v[42:45]
	v_mfma_f32_16x16x32_bf16 v[30:33], v[102:105], v[202:205], v[30:33]
	v_mfma_f32_16x16x32_bf16 v[26:29], v[110:113], v[202:205], v[26:29]
	v_mfma_f32_16x16x32_bf16 v[14:17], v[102:105], v[210:213], v[14:17]
	v_mfma_f32_16x16x32_bf16 v[10:13], v[110:113], v[210:213], v[10:13]
	s_setprio 0
	s_setprio 1
	v_mfma_f32_16x16x32_bf16 v[54:57], v[146:149], v[182:185], v[54:57]
	v_mfma_f32_16x16x32_bf16 v[50:53], v[174:177], v[182:185], v[50:53]
	v_mfma_f32_16x16x32_bf16 v[38:41], v[146:149], v[190:193], v[38:41]
	v_mfma_f32_16x16x32_bf16 v[34:37], v[174:177], v[190:193], v[34:37]
	v_mfma_f32_16x16x32_bf16 v[22:25], v[146:149], v[198:201], v[22:25]
	v_mfma_f32_16x16x32_bf16 v[18:21], v[174:177], v[198:201], v[18:21]
	v_mfma_f32_16x16x32_bf16 v[6:9], v[146:149], v[206:209], v[6:9]
	v_mfma_f32_16x16x32_bf16 v[2:5], v[174:177], v[206:209], v[2:5]
	v_mfma_f32_16x16x32_bf16 v[54:57], v[164:167], v[186:189], v[54:57]
	v_mfma_f32_16x16x32_bf16 v[50:53], v[178:181], v[186:189], v[50:53]
	v_mfma_f32_16x16x32_bf16 v[38:41], v[164:167], v[194:197], v[38:41]
	v_mfma_f32_16x16x32_bf16 v[34:37], v[178:181], v[194:197], v[34:37]
	v_mfma_f32_16x16x32_bf16 v[22:25], v[164:167], v[202:205], v[22:25]
	v_mfma_f32_16x16x32_bf16 v[18:21], v[178:181], v[202:205], v[18:21]
	v_mfma_f32_16x16x32_bf16 v[6:9], v[164:167], v[210:213], v[6:9]
	v_mfma_f32_16x16x32_bf16 v[2:5], v[178:181], v[210:213], v[2:5]
	s_setprio 0
	s_barrier
	s_add_i32 s49, s49, 2
	s_add_u32 s24, s24, 0x100
	s_addc_u32 s25, s25, 0
	s_add_u32 s47, s47, 0x100
	s_addc_u32 s48, s48, 0
	s_cmp_gt_u32 s49, 13
	s_cbranch_scc0 .LBB0_1877
	s_and_b64 vcc, exec, s[10:11]
	s_cbranch_vccnz .LBB0_1882
	s_cmpk_lt_i32 s0, 0x80
	s_mov_b64 s[24:25], -1
	s_cbranch_scc0 .LBB0_1883

.LBB0_1927:
	s_add_u32 s24, s22, 0xfffc0080
	s_addc_u32 s25, s23, -1
	s_add_i32 s46, 0, 0x10000
	s_cmp_eq_u32 s45, 12
	s_cselect_b32 s27, s9, s25
	s_cselect_b32 s26, s19, s24
	s_cselect_b32 s25, s11, s44
	s_cselect_b32 s24, s42, s43
	s_add_i32 s48, 0, 0x14000
	v_add_u32_e32 v158, s46, v143
	v_add_u32_e32 v174, s48, v143
	ds_read_b128 v[146:149], v158
	ds_read_b128 v[150:153], v158 offset:1024
	ds_read_b128 v[154:157], v158 offset:2048
	ds_read_b128 v[158:161], v158 offset:3072
	ds_read_b128 v[162:165], v174
	ds_read_b128 v[166:169], v174 offset:1024
	ds_read_b128 v[170:173], v174 offset:2048
	ds_read_b128 v[174:177], v174 offset:3072
	v_lshl_add_u64 v[210:211], s[22:23], 0, v[136:137]
	s_add_i32 m0, s21, 0xc000
	ds_read_b128 v[178:181], v145
	ds_read_b128 v[182:185], v145 offset:1024
	ds_read_b128 v[186:189], v145 offset:2048
	ds_read_b128 v[190:193], v145 offset:3072
	ds_read_b128 v[194:197], v145 offset:4096
	ds_read_b128 v[198:201], v145 offset:5120
	ds_read_b128 v[202:205], v145 offset:6144
	ds_read_b128 v[206:209], v145 offset:7168
	global_load_lds_dwordx4 v[210:211], off
	v_lshl_add_u64 v[210:211], s[22:23], 0, v[138:139]
	s_add_i32 m0, s21, 0xe000
	s_nop 0
	global_load_lds_dwordx4 v[210:211], off
	s_waitcnt vmcnt(8)
	s_waitcnt lgkmcnt(0)
	s_barrier
	s_setprio 1
	s_waitcnt lgkmcnt(0)
	v_mfma_f32_16x16x32_bf16 v[126:129], v[146:149], v[178:181], v[126:129]
	v_mfma_f32_16x16x32_bf16 v[118:121], v[154:157], v[178:181], v[118:121]
	v_mfma_f32_16x16x32_bf16 v[110:113], v[146:149], v[186:189], v[110:113]
	v_mfma_f32_16x16x32_bf16 v[102:105], v[154:157], v[186:189], v[102:105]
	v_mfma_f32_16x16x32_bf16 v[94:97], v[146:149], v[194:197], v[94:97]
	v_mfma_f32_16x16x32_bf16 v[86:89], v[154:157], v[194:197], v[86:89]
	v_mfma_f32_16x16x32_bf16 v[78:81], v[146:149], v[202:205], v[78:81]
	v_mfma_f32_16x16x32_bf16 v[70:73], v[154:157], v[202:205], v[70:73]
	v_mfma_f32_16x16x32_bf16 v[126:129], v[150:153], v[182:185], v[126:129]
	v_mfma_f32_16x16x32_bf16 v[118:121], v[158:161], v[182:185], v[118:121]
	v_mfma_f32_16x16x32_bf16 v[110:113], v[150:153], v[190:193], v[110:113]
	v_mfma_f32_16x16x32_bf16 v[102:105], v[158:161], v[190:193], v[102:105]
	v_mfma_f32_16x16x32_bf16 v[94:97], v[150:153], v[198:201], v[94:97]
	v_mfma_f32_16x16x32_bf16 v[86:89], v[158:161], v[198:201], v[86:89]
	v_mfma_f32_16x16x32_bf16 v[78:81], v[150:153], v[206:209], v[78:81]
	v_mfma_f32_16x16x32_bf16 v[70:73], v[158:161], v[206:209], v[70:73]
	s_setprio 0
	s_setprio 1
	v_mfma_f32_16x16x32_bf16 v[122:125], v[162:165], v[178:181], v[122:125]
	v_mfma_f32_16x16x32_bf16 v[114:117], v[170:173], v[178:181], v[114:117]
	v_mfma_f32_16x16x32_bf16 v[106:109], v[162:165], v[186:189], v[106:109]
	v_mfma_f32_16x16x32_bf16 v[98:101], v[170:173], v[186:189], v[98:101]
	v_mfma_f32_16x16x32_bf16 v[90:93], v[162:165], v[194:197], v[90:93]
	v_mfma_f32_16x16x32_bf16 v[82:85], v[170:173], v[194:197], v[82:85]
	v_mfma_f32_16x16x32_bf16 v[74:77], v[162:165], v[202:205], v[74:77]
	v_mfma_f32_16x16x32_bf16 v[66:69], v[170:173], v[202:205], v[66:69]
	v_mfma_f32_16x16x32_bf16 v[122:125], v[166:169], v[182:185], v[122:125]
	v_mfma_f32_16x16x32_bf16 v[114:117], v[174:177], v[182:185], v[114:117]
	v_mfma_f32_16x16x32_bf16 v[106:109], v[166:169], v[190:193], v[106:109]
	v_mfma_f32_16x16x32_bf16 v[98:101], v[174:177], v[190:193], v[98:101]
	v_mfma_f32_16x16x32_bf16 v[90:93], v[166:169], v[198:201], v[90:93]
	v_mfma_f32_16x16x32_bf16 v[82:85], v[174:177], v[198:201], v[82:85]
	v_mfma_f32_16x16x32_bf16 v[74:77], v[166:169], v[206:209], v[74:77]
	v_mfma_f32_16x16x32_bf16 v[66:69], v[174:177], v[206:209], v[66:69]
	s_setprio 0
	s_barrier
	s_add_i32 s46, s46, s33
	v_lshl_add_u64 v[210:211], s[24:25], 0, v[0:1]
	s_mov_b32 m0, s46
	ds_read_b128 v[178:181], v145 offset:16384
	ds_read_b128 v[182:185], v145 offset:17408
	ds_read_b128 v[186:189], v145 offset:18432
	ds_read_b128 v[190:193], v145 offset:19456
	ds_read_b128 v[194:197], v145 offset:20480
	ds_read_b128 v[198:201], v145 offset:21504
	ds_read_b128 v[202:205], v145 offset:22528
	ds_read_b128 v[206:209], v145 offset:23552
	global_load_lds_dwordx4 v[210:211], off
	s_add_i32 m0, s46, 0x2000
	s_add_u32 s46, s24, 0x40000
	v_lshl_add_u64 v[212:213], s[24:25], 0, v[130:131]
	s_addc_u32 s47, s25, 0
	s_add_i32 s48, s48, s33
	global_load_lds_dwordx4 v[212:213], off
	v_lshl_add_u64 v[214:215], s[46:47], 0, v[0:1]
	s_mov_b32 m0, s48
	v_lshl_add_u64 v[216:217], s[26:27], 0, v[132:133]
	global_load_lds_dwordx4 v[214:215], off
	v_lshl_add_u64 v[214:215], s[46:47], 0, v[130:131]
	s_add_i32 m0, s48, 0x2000
	s_nop 0
	global_load_lds_dwordx4 v[214:215], off
	s_waitcnt vmcnt(6)
	s_waitcnt lgkmcnt(0)
	s_barrier
	s_setprio 1
	s_waitcnt lgkmcnt(0)
	v_mfma_f32_16x16x32_bf16 v[62:65], v[146:149], v[178:181], v[62:65]
	v_mfma_f32_16x16x32_bf16 v[54:57], v[154:157], v[178:181], v[54:57]
	v_mfma_f32_16x16x32_bf16 v[46:49], v[146:149], v[186:189], v[46:49]
	v_mfma_f32_16x16x32_bf16 v[38:41], v[154:157], v[186:189], v[38:41]
	v_mfma_f32_16x16x32_bf16 v[30:33], v[146:149], v[194:197], v[30:33]
	v_mfma_f32_16x16x32_bf16 v[22:25], v[154:157], v[194:197], v[22:25]
	v_mfma_f32_16x16x32_bf16 v[14:17], v[146:149], v[202:205], v[14:17]
	v_mfma_f32_16x16x32_bf16 v[6:9], v[154:157], v[202:205], v[6:9]
	v_mfma_f32_16x16x32_bf16 v[62:65], v[150:153], v[182:185], v[62:65]
	v_mfma_f32_16x16x32_bf16 v[54:57], v[158:161], v[182:185], v[54:57]
	v_mfma_f32_16x16x32_bf16 v[46:49], v[150:153], v[190:193], v[46:49]
	v_mfma_f32_16x16x32_bf16 v[38:41], v[158:161], v[190:193], v[38:41]
	v_mfma_f32_16x16x32_bf16 v[30:33], v[150:153], v[198:201], v[30:33]
	v_mfma_f32_16x16x32_bf16 v[22:25], v[158:161], v[198:201], v[22:25]
	v_mfma_f32_16x16x32_bf16 v[14:17], v[150:153], v[206:209], v[14:17]
	v_mfma_f32_16x16x32_bf16 v[6:9], v[158:161], v[206:209], v[6:9]
	s_setprio 0
	s_setprio 1
	v_mfma_f32_16x16x32_bf16 v[58:61], v[162:165], v[178:181], v[58:61]
	v_mfma_f32_16x16x32_bf16 v[50:53], v[170:173], v[178:181], v[50:53]
	v_mfma_f32_16x16x32_bf16 v[42:45], v[162:165], v[186:189], v[42:45]
	v_mfma_f32_16x16x32_bf16 v[34:37], v[170:173], v[186:189], v[34:37]
	v_mfma_f32_16x16x32_bf16 v[26:29], v[162:165], v[194:197], v[26:29]
	v_mfma_f32_16x16x32_bf16 v[18:21], v[170:173], v[194:197], v[18:21]
	v_mfma_f32_16x16x32_bf16 v[10:13], v[162:165], v[202:205], v[10:13]
	v_mfma_f32_16x16x32_bf16 v[2:5], v[170:173], v[202:205], v[2:5]
	v_mfma_f32_16x16x32_bf16 v[58:61], v[166:169], v[182:185], v[58:61]
	v_mfma_f32_16x16x32_bf16 v[50:53], v[174:177], v[182:185], v[50:53]
	v_mfma_f32_16x16x32_bf16 v[42:45], v[166:169], v[190:193], v[42:45]
	v_mfma_f32_16x16x32_bf16 v[34:37], v[174:177], v[190:193], v[34:37]
	v_mfma_f32_16x16x32_bf16 v[26:29], v[166:169], v[198:201], v[26:29]
	v_mfma_f32_16x16x32_bf16 v[18:21], v[174:177], v[198:201], v[18:21]
	v_mfma_f32_16x16x32_bf16 v[10:13], v[166:169], v[206:209], v[10:13]
	v_mfma_f32_16x16x32_bf16 v[2:5], v[174:177], v[206:209], v[2:5]
	s_setprio 0
	s_barrier
	s_add_i32 s46, 0, 0x18000
	s_add_i32 s47, 0, 0x1c000
	v_add_u32_e32 v158, s46, v143
	v_add_u32_e32 v174, s47, v143
	ds_read_b128 v[146:149], v158
	ds_read_b128 v[150:153], v158 offset:1024
	ds_read_b128 v[154:157], v158 offset:2048
	ds_read_b128 v[158:161], v158 offset:3072
	ds_read_b128 v[162:165], v174
	ds_read_b128 v[166:169], v174 offset:1024
	ds_read_b128 v[170:173], v174 offset:2048
	ds_read_b128 v[174:177], v174 offset:3072
	v_lshl_add_u64 v[214:215], s[26:27], 0, v[134:135]
	s_mov_b32 m0, s21
	s_nop 0
	global_load_lds_dwordx4 v[214:215], off
	s_mov_b32 m0, s34
	s_nop 0
	global_load_lds_dwordx4 v[216:217], off
	s_add_u32 s26, s26, 0x40000
	s_addc_u32 s27, s27, 0
	s_mov_b32 m0, s35
	v_lshl_add_u64 v[218:219], s[26:27], 0, v[134:135]
	ds_read_b128 v[178:181], v145 offset:32768
	ds_read_b128 v[182:185], v145 offset:33792
	ds_read_b128 v[186:189], v145 offset:34816
	ds_read_b128 v[190:193], v145 offset:35840
	ds_read_b128 v[194:197], v145 offset:36864
	ds_read_b128 v[198:201], v145 offset:37888
	ds_read_b128 v[202:205], v145 offset:38912
	ds_read_b128 v[206:209], v145 offset:39936
	global_load_lds_dwordx4 v[218:219], off
	v_lshl_add_u64 v[218:219], s[26:27], 0, v[132:133]
	s_mov_b32 m0, s38
	s_nop 0
	global_load_lds_dwordx4 v[218:219], off
	s_waitcnt vmcnt(8)
	s_waitcnt lgkmcnt(0)
	s_barrier
	s_setprio 1
	s_waitcnt lgkmcnt(0)
	v_mfma_f32_16x16x32_bf16 v[126:129], v[146:149], v[178:181], v[126:129]
	v_mfma_f32_16x16x32_bf16 v[118:121], v[154:157], v[178:181], v[118:121]
	v_mfma_f32_16x16x32_bf16 v[110:113], v[146:149], v[186:189], v[110:113]
	v_mfma_f32_16x16x32_bf16 v[102:105], v[154:157], v[186:189], v[102:105]
	v_mfma_f32_16x16x32_bf16 v[94:97], v[146:149], v[194:197], v[94:97]
	v_mfma_f32_16x16x32_bf16 v[86:89], v[154:157], v[194:197], v[86:89]
	v_mfma_f32_16x16x32_bf16 v[78:81], v[146:149], v[202:205], v[78:81]
	v_mfma_f32_16x16x32_bf16 v[70:73], v[154:157], v[202:205], v[70:73]
	v_mfma_f32_16x16x32_bf16 v[126:129], v[150:153], v[182:185], v[126:129]
	v_mfma_f32_16x16x32_bf16 v[118:121], v[158:161], v[182:185], v[118:121]
	v_mfma_f32_16x16x32_bf16 v[110:113], v[150:153], v[190:193], v[110:113]
	v_mfma_f32_16x16x32_bf16 v[102:105], v[158:161], v[190:193], v[102:105]
	v_mfma_f32_16x16x32_bf16 v[94:97], v[150:153], v[198:201], v[94:97]
	v_mfma_f32_16x16x32_bf16 v[86:89], v[158:161], v[198:201], v[86:89]
	v_mfma_f32_16x16x32_bf16 v[78:81], v[150:153], v[206:209], v[78:81]
	v_mfma_f32_16x16x32_bf16 v[70:73], v[158:161], v[206:209], v[70:73]
	s_setprio 0
	s_setprio 1
	v_mfma_f32_16x16x32_bf16 v[122:125], v[162:165], v[178:181], v[122:125]
	v_mfma_f32_16x16x32_bf16 v[114:117], v[170:173], v[178:181], v[114:117]
	v_mfma_f32_16x16x32_bf16 v[106:109], v[162:165], v[186:189], v[106:109]
	v_mfma_f32_16x16x32_bf16 v[98:101], v[170:173], v[186:189], v[98:101]
	v_mfma_f32_16x16x32_bf16 v[90:93], v[162:165], v[194:197], v[90:93]
	v_mfma_f32_16x16x32_bf16 v[82:85], v[170:173], v[194:197], v[82:85]
	v_mfma_f32_16x16x32_bf16 v[74:77], v[162:165], v[202:205], v[74:77]
	v_mfma_f32_16x16x32_bf16 v[66:69], v[170:173], v[202:205], v[66:69]
	v_mfma_f32_16x16x32_bf16 v[122:125], v[166:169], v[182:185], v[122:125]
	v_mfma_f32_16x16x32_bf16 v[114:117], v[174:177], v[182:185], v[114:117]
	v_mfma_f32_16x16x32_bf16 v[106:109], v[166:169], v[190:193], v[106:109]
	v_mfma_f32_16x16x32_bf16 v[98:101], v[174:177], v[190:193], v[98:101]
	v_mfma_f32_16x16x32_bf16 v[90:93], v[166:169], v[198:201], v[90:93]
	v_mfma_f32_16x16x32_bf16 v[82:85], v[174:177], v[198:201], v[82:85]
	v_mfma_f32_16x16x32_bf16 v[74:77], v[166:169], v[206:209], v[74:77]
	v_mfma_f32_16x16x32_bf16 v[66:69], v[174:177], v[206:209], v[66:69]
	s_setprio 0
	s_barrier
	s_add_i32 s26, s46, s33
	v_lshl_add_u64 v[210:211], v[210:211], 0, s[80:81]
	s_mov_b32 m0, s26
	ds_read_b128 v[178:181], v145 offset:49152
	ds_read_b128 v[182:185], v145 offset:50176
	ds_read_b128 v[186:189], v145 offset:51200
	ds_read_b128 v[190:193], v145 offset:52224
	ds_read_b128 v[194:197], v145 offset:53248
	ds_read_b128 v[198:201], v145 offset:54272
	ds_read_b128 v[202:205], v145 offset:55296
	ds_read_b128 v[206:209], v145 offset:56320
	global_load_lds_dwordx4 v[210:211], off
	s_add_i32 m0, s26, 0x2000
	s_add_u32 s24, s24, 0x40080
	v_lshl_add_u64 v[210:211], v[212:213], 0, s[80:81]
	s_addc_u32 s25, s25, 0
	s_add_i32 s26, s47, s33
	global_load_lds_dwordx4 v[210:211], off
	v_lshl_add_u64 v[210:211], s[24:25], 0, v[0:1]
	s_mov_b32 m0, s26
	s_nop 0
	global_load_lds_dwordx4 v[210:211], off
	v_lshl_add_u64 v[210:211], s[24:25], 0, v[130:131]
	s_add_i32 m0, s26, 0x2000
	s_nop 0
	global_load_lds_dwordx4 v[210:211], off
	v_lshl_add_u64 v[210:211], v[214:215], 0, s[80:81]
	s_mov_b32 m0, s39
	s_nop 0
	global_load_lds_dwordx4 v[210:211], off
	v_lshl_add_u64 v[210:211], v[216:217], 0, s[80:81]
	s_mov_b32 m0, s40
	s_nop 0
	global_load_lds_dwordx4 v[210:211], off
	s_waitcnt vmcnt(8)
	s_waitcnt lgkmcnt(0)
	s_barrier
	s_setprio 1
	s_waitcnt lgkmcnt(0)
	v_mfma_f32_16x16x32_bf16 v[62:65], v[146:149], v[178:181], v[62:65]
	v_mfma_f32_16x16x32_bf16 v[54:57], v[154:157], v[178:181], v[54:57]
	v_mfma_f32_16x16x32_bf16 v[46:49], v[146:149], v[186:189], v[46:49]
	v_mfma_f32_16x16x32_bf16 v[38:41], v[154:157], v[186:189], v[38:41]
	v_mfma_f32_16x16x32_bf16 v[30:33], v[146:149], v[194:197], v[30:33]
	v_mfma_f32_16x16x32_bf16 v[22:25], v[154:157], v[194:197], v[22:25]
	v_mfma_f32_16x16x32_bf16 v[14:17], v[146:149], v[202:205], v[14:17]
	v_mfma_f32_16x16x32_bf16 v[6:9], v[154:157], v[202:205], v[6:9]
	v_mfma_f32_16x16x32_bf16 v[62:65], v[150:153], v[182:185], v[62:65]
	v_mfma_f32_16x16x32_bf16 v[54:57], v[158:161], v[182:185], v[54:57]
	v_mfma_f32_16x16x32_bf16 v[46:49], v[150:153], v[190:193], v[46:49]
	v_mfma_f32_16x16x32_bf16 v[38:41], v[158:161], v[190:193], v[38:41]
	v_mfma_f32_16x16x32_bf16 v[30:33], v[150:153], v[198:201], v[30:33]
	v_mfma_f32_16x16x32_bf16 v[22:25], v[158:161], v[198:201], v[22:25]
	v_mfma_f32_16x16x32_bf16 v[14:17], v[150:153], v[206:209], v[14:17]
	v_mfma_f32_16x16x32_bf16 v[6:9], v[158:161], v[206:209], v[6:9]
	s_setprio 0
	s_setprio 1
	v_mfma_f32_16x16x32_bf16 v[58:61], v[162:165], v[178:181], v[58:61]
	v_mfma_f32_16x16x32_bf16 v[50:53], v[170:173], v[178:181], v[50:53]
	v_mfma_f32_16x16x32_bf16 v[42:45], v[162:165], v[186:189], v[42:45]
	v_mfma_f32_16x16x32_bf16 v[34:37], v[170:173], v[186:189], v[34:37]
	v_mfma_f32_16x16x32_bf16 v[26:29], v[162:165], v[194:197], v[26:29]
	v_mfma_f32_16x16x32_bf16 v[18:21], v[170:173], v[194:197], v[18:21]
	v_mfma_f32_16x16x32_bf16 v[10:13], v[162:165], v[202:205], v[10:13]
	v_mfma_f32_16x16x32_bf16 v[2:5], v[170:173], v[202:205], v[2:5]
	v_mfma_f32_16x16x32_bf16 v[58:61], v[166:169], v[182:185], v[58:61]
	v_mfma_f32_16x16x32_bf16 v[50:53], v[174:177], v[182:185], v[50:53]
	v_mfma_f32_16x16x32_bf16 v[42:45], v[166:169], v[190:193], v[42:45]
	v_mfma_f32_16x16x32_bf16 v[34:37], v[174:177], v[190:193], v[34:37]
	v_mfma_f32_16x16x32_bf16 v[26:29], v[166:169], v[198:201], v[26:29]
	v_mfma_f32_16x16x32_bf16 v[18:21], v[174:177], v[198:201], v[18:21]
	v_mfma_f32_16x16x32_bf16 v[10:13], v[166:169], v[206:209], v[10:13]
	v_mfma_f32_16x16x32_bf16 v[2:5], v[174:177], v[206:209], v[2:5]
	s_setprio 0
	s_barrier
	s_add_i32 s45, s45, 2
	s_add_u32 s22, s22, 0x100
	s_addc_u32 s23, s23, 0
	s_add_u32 s43, s43, 0x100
	s_addc_u32 s44, s44, 0
	s_cmp_gt_u32 s45, 13
	s_cbranch_scc0 .LBB0_1927
	s_and_b64 vcc, exec, s[6:7]
	s_cbranch_vccz .LBB0_1930
	s_barrier

.LBB0_1961:
	s_add_u32 s16, s0, 0x100
	s_addc_u32 s17, s1, 0
	s_add_i32 s46, 0, 0x10000
	s_cmp_eq_u32 s45, 40
	s_cselect_b32 s21, s13, s17
	s_cselect_b32 s20, s12, s16
	v_add_u32_e32 v0, s46, v169
	s_cselect_b32 s19, s15, s44
	s_cselect_b32 s18, s14, s43
	s_add_i32 s47, 0, 0x14000
	ds_read_b128 v[130:133], v0
	ds_read_b128 v[148:151], v0 offset:1024
	ds_read_b128 v[152:155], v0 offset:2048
	ds_read_b128 v[156:159], v0 offset:3072
	v_add_u32_e32 v0, s47, v169
	ds_read_b128 v[160:163], v0
	ds_read_b128 v[164:167], v0 offset:1024
	ds_read_b128 v[172:175], v0 offset:2048
	ds_read_b128 v[176:179], v0 offset:3072
	v_lshl_add_u64 v[212:213], s[0:1], 0, v[144:145]
	s_add_i32 m0, s27, 0xc000
	ds_read_b128 v[180:183], v171
	ds_read_b128 v[184:187], v171 offset:1024
	ds_read_b128 v[188:191], v171 offset:2048
	ds_read_b128 v[192:195], v171 offset:3072
	ds_read_b128 v[196:199], v171 offset:4096
	ds_read_b128 v[200:203], v171 offset:5120
	ds_read_b128 v[204:207], v171 offset:6144
	ds_read_b128 v[208:211], v171 offset:7168
	global_load_lds_dwordx4 v[212:213], off
	v_lshl_add_u64 v[212:213], s[0:1], 0, v[146:147]
	s_add_i32 m0, s27, 0xe000
	s_nop 0
	global_load_lds_dwordx4 v[212:213], off
	s_waitcnt vmcnt(8)
	s_waitcnt lgkmcnt(0)
	s_barrier
	s_setprio 1
	s_waitcnt lgkmcnt(0)
	v_mfma_f32_16x16x32_bf16 v[126:129], v[130:133], v[180:183], v[126:129]
	v_mfma_f32_16x16x32_bf16 v[122:125], v[152:155], v[180:183], v[122:125]
	v_mfma_f32_16x16x32_bf16 v[110:113], v[130:133], v[188:191], v[110:113]
	v_mfma_f32_16x16x32_bf16 v[106:109], v[152:155], v[188:191], v[106:109]
	v_mfma_f32_16x16x32_bf16 v[94:97], v[130:133], v[196:199], v[94:97]
	v_mfma_f32_16x16x32_bf16 v[90:93], v[152:155], v[196:199], v[90:93]
	v_mfma_f32_16x16x32_bf16 v[78:81], v[130:133], v[204:207], v[78:81]
	v_mfma_f32_16x16x32_bf16 v[74:77], v[152:155], v[204:207], v[74:77]
	v_mfma_f32_16x16x32_bf16 v[126:129], v[148:151], v[184:187], v[126:129]
	v_mfma_f32_16x16x32_bf16 v[122:125], v[156:159], v[184:187], v[122:125]
	v_mfma_f32_16x16x32_bf16 v[110:113], v[148:151], v[192:195], v[110:113]
	v_mfma_f32_16x16x32_bf16 v[106:109], v[156:159], v[192:195], v[106:109]
	v_mfma_f32_16x16x32_bf16 v[94:97], v[148:151], v[200:203], v[94:97]
	v_mfma_f32_16x16x32_bf16 v[90:93], v[156:159], v[200:203], v[90:93]
	v_mfma_f32_16x16x32_bf16 v[78:81], v[148:151], v[208:211], v[78:81]
	v_mfma_f32_16x16x32_bf16 v[74:77], v[156:159], v[208:211], v[74:77]
	s_setprio 0
	s_setprio 1
	v_mfma_f32_16x16x32_bf16 v[118:121], v[160:163], v[180:183], v[118:121]
	v_mfma_f32_16x16x32_bf16 v[114:117], v[172:175], v[180:183], v[114:117]
	v_mfma_f32_16x16x32_bf16 v[102:105], v[160:163], v[188:191], v[102:105]
	v_mfma_f32_16x16x32_bf16 v[98:101], v[172:175], v[188:191], v[98:101]
	v_mfma_f32_16x16x32_bf16 v[86:89], v[160:163], v[196:199], v[86:89]
	v_mfma_f32_16x16x32_bf16 v[82:85], v[172:175], v[196:199], v[82:85]
	v_mfma_f32_16x16x32_bf16 v[70:73], v[160:163], v[204:207], v[70:73]
	v_mfma_f32_16x16x32_bf16 v[66:69], v[172:175], v[204:207], v[66:69]
	v_mfma_f32_16x16x32_bf16 v[118:121], v[164:167], v[184:187], v[118:121]
	v_mfma_f32_16x16x32_bf16 v[114:117], v[176:179], v[184:187], v[114:117]
	v_mfma_f32_16x16x32_bf16 v[102:105], v[164:167], v[192:195], v[102:105]
	v_mfma_f32_16x16x32_bf16 v[98:101], v[176:179], v[192:195], v[98:101]
	v_mfma_f32_16x16x32_bf16 v[86:89], v[164:167], v[200:203], v[86:89]
	v_mfma_f32_16x16x32_bf16 v[82:85], v[176:179], v[200:203], v[82:85]
	v_mfma_f32_16x16x32_bf16 v[70:73], v[164:167], v[208:211], v[70:73]
	v_mfma_f32_16x16x32_bf16 v[66:69], v[176:179], v[208:211], v[66:69]
	s_setprio 0
	s_barrier
	s_add_i32 s0, s46, s26
	v_lshl_add_u64 v[212:213], s[18:19], 0, v[138:139]
	s_mov_b32 m0, s0
	ds_read_b128 v[180:183], v171 offset:16384
	ds_read_b128 v[184:187], v171 offset:17408
	ds_read_b128 v[188:191], v171 offset:18432
	ds_read_b128 v[192:195], v171 offset:19456
	ds_read_b128 v[196:199], v171 offset:20480
	ds_read_b128 v[200:203], v171 offset:21504
	ds_read_b128 v[204:207], v171 offset:22528
	ds_read_b128 v[208:211], v171 offset:23552
	global_load_lds_dwordx4 v[212:213], off
	s_add_i32 m0, s0, 0x2000
	s_add_u32 s0, s18, 0xb0000
	v_lshl_add_u64 v[214:215], s[18:19], 0, v[134:135]
	s_addc_u32 s1, s19, 0
	s_add_i32 s46, s47, s26
	global_load_lds_dwordx4 v[214:215], off
	v_lshl_add_u64 v[216:217], s[0:1], 0, v[138:139]
	s_mov_b32 m0, s46
	v_lshl_add_u64 v[218:219], s[20:21], 0, v[136:137]
	global_load_lds_dwordx4 v[216:217], off
	v_lshl_add_u64 v[216:217], s[0:1], 0, v[134:135]
	s_add_i32 m0, s46, 0x2000
	s_nop 0
	global_load_lds_dwordx4 v[216:217], off
	s_waitcnt vmcnt(6)
	s_waitcnt lgkmcnt(0)
	s_barrier
	s_setprio 1
	s_waitcnt lgkmcnt(0)
	v_mfma_f32_16x16x32_bf16 v[62:65], v[130:133], v[180:183], v[62:65]
	v_mfma_f32_16x16x32_bf16 v[58:61], v[152:155], v[180:183], v[58:61]
	v_mfma_f32_16x16x32_bf16 v[46:49], v[130:133], v[188:191], v[46:49]
	v_mfma_f32_16x16x32_bf16 v[42:45], v[152:155], v[188:191], v[42:45]
	v_mfma_f32_16x16x32_bf16 v[30:33], v[130:133], v[196:199], v[30:33]
	v_mfma_f32_16x16x32_bf16 v[26:29], v[152:155], v[196:199], v[26:29]
	v_mfma_f32_16x16x32_bf16 v[14:17], v[130:133], v[204:207], v[14:17]
	v_mfma_f32_16x16x32_bf16 v[10:13], v[152:155], v[204:207], v[10:13]
	v_mfma_f32_16x16x32_bf16 v[62:65], v[148:151], v[184:187], v[62:65]
	v_mfma_f32_16x16x32_bf16 v[58:61], v[156:159], v[184:187], v[58:61]
	v_mfma_f32_16x16x32_bf16 v[46:49], v[148:151], v[192:195], v[46:49]
	v_mfma_f32_16x16x32_bf16 v[42:45], v[156:159], v[192:195], v[42:45]
	v_mfma_f32_16x16x32_bf16 v[30:33], v[148:151], v[200:203], v[30:33]
	v_mfma_f32_16x16x32_bf16 v[26:29], v[156:159], v[200:203], v[26:29]
	v_mfma_f32_16x16x32_bf16 v[14:17], v[148:151], v[208:211], v[14:17]
	v_mfma_f32_16x16x32_bf16 v[10:13], v[156:159], v[208:211], v[10:13]
	s_setprio 0
	s_setprio 1
	v_mfma_f32_16x16x32_bf16 v[54:57], v[160:163], v[180:183], v[54:57]
	v_mfma_f32_16x16x32_bf16 v[50:53], v[172:175], v[180:183], v[50:53]
	v_mfma_f32_16x16x32_bf16 v[38:41], v[160:163], v[188:191], v[38:41]
	v_mfma_f32_16x16x32_bf16 v[34:37], v[172:175], v[188:191], v[34:37]
	v_mfma_f32_16x16x32_bf16 v[22:25], v[160:163], v[196:199], v[22:25]
	v_mfma_f32_16x16x32_bf16 v[18:21], v[172:175], v[196:199], v[18:21]
	v_mfma_f32_16x16x32_bf16 v[6:9], v[160:163], v[204:207], v[6:9]
	v_mfma_f32_16x16x32_bf16 v[2:5], v[172:175], v[204:207], v[2:5]
	v_mfma_f32_16x16x32_bf16 v[54:57], v[164:167], v[184:187], v[54:57]
	v_mfma_f32_16x16x32_bf16 v[50:53], v[176:179], v[184:187], v[50:53]
	v_mfma_f32_16x16x32_bf16 v[38:41], v[164:167], v[192:195], v[38:41]
	v_mfma_f32_16x16x32_bf16 v[34:37], v[176:179], v[192:195], v[34:37]
	v_mfma_f32_16x16x32_bf16 v[22:25], v[164:167], v[200:203], v[22:25]
	v_mfma_f32_16x16x32_bf16 v[18:21], v[176:179], v[200:203], v[18:21]
	v_mfma_f32_16x16x32_bf16 v[6:9], v[164:167], v[208:211], v[6:9]
	v_mfma_f32_16x16x32_bf16 v[2:5], v[176:179], v[208:211], v[2:5]
	s_setprio 0
	s_barrier
	s_add_i32 s46, 0, 0x18000
	v_add_u32_e32 v0, s46, v169
	s_add_i32 s47, 0, 0x1c000
	ds_read_b128 v[130:133], v0
	ds_read_b128 v[148:151], v0 offset:1024
	ds_read_b128 v[152:155], v0 offset:2048
	ds_read_b128 v[156:159], v0 offset:3072
	v_add_u32_e32 v0, s47, v169
	ds_read_b128 v[160:163], v0
	ds_read_b128 v[164:167], v0 offset:1024
	ds_read_b128 v[172:175], v0 offset:2048
	ds_read_b128 v[176:179], v0 offset:3072
	s_add_u32 s0, s20, 0xb0000
	s_addc_u32 s1, s21, 0
	v_lshl_add_u64 v[216:217], s[20:21], 0, v[140:141]
	s_mov_b32 m0, s27
	s_nop 0
	global_load_lds_dwordx4 v[216:217], off
	s_mov_b32 m0, s28
	s_nop 0
	global_load_lds_dwordx4 v[218:219], off
	s_mov_b32 m0, s29
	v_lshl_add_u64 v[220:221], s[0:1], 0, v[140:141]
	ds_read_b128 v[180:183], v171 offset:32768
	ds_read_b128 v[184:187], v171 offset:33792
	ds_read_b128 v[188:191], v171 offset:34816
	ds_read_b128 v[192:195], v171 offset:35840
	ds_read_b128 v[196:199], v171 offset:36864
	ds_read_b128 v[200:203], v171 offset:37888
	ds_read_b128 v[204:207], v171 offset:38912
	ds_read_b128 v[208:211], v171 offset:39936
	global_load_lds_dwordx4 v[220:221], off
	v_lshl_add_u64 v[220:221], s[0:1], 0, v[136:137]
	s_mov_b32 m0, s30
	s_nop 0
	global_load_lds_dwordx4 v[220:221], off
	s_waitcnt vmcnt(8)
	s_waitcnt lgkmcnt(0)
	s_barrier
	s_setprio 1
	s_waitcnt lgkmcnt(0)
	v_mfma_f32_16x16x32_bf16 v[126:129], v[130:133], v[180:183], v[126:129]
	v_mfma_f32_16x16x32_bf16 v[122:125], v[152:155], v[180:183], v[122:125]
	v_mfma_f32_16x16x32_bf16 v[110:113], v[130:133], v[188:191], v[110:113]
	v_mfma_f32_16x16x32_bf16 v[106:109], v[152:155], v[188:191], v[106:109]
	v_mfma_f32_16x16x32_bf16 v[94:97], v[130:133], v[196:199], v[94:97]
	v_mfma_f32_16x16x32_bf16 v[90:93], v[152:155], v[196:199], v[90:93]
	v_mfma_f32_16x16x32_bf16 v[78:81], v[130:133], v[204:207], v[78:81]
	v_mfma_f32_16x16x32_bf16 v[74:77], v[152:155], v[204:207], v[74:77]
	v_mfma_f32_16x16x32_bf16 v[126:129], v[148:151], v[184:187], v[126:129]
	v_mfma_f32_16x16x32_bf16 v[122:125], v[156:159], v[184:187], v[122:125]
	v_mfma_f32_16x16x32_bf16 v[110:113], v[148:151], v[192:195], v[110:113]
	v_mfma_f32_16x16x32_bf16 v[106:109], v[156:159], v[192:195], v[106:109]
	v_mfma_f32_16x16x32_bf16 v[94:97], v[148:151], v[200:203], v[94:97]
	v_mfma_f32_16x16x32_bf16 v[90:93], v[156:159], v[200:203], v[90:93]
	v_mfma_f32_16x16x32_bf16 v[78:81], v[148:151], v[208:211], v[78:81]
	v_mfma_f32_16x16x32_bf16 v[74:77], v[156:159], v[208:211], v[74:77]
	s_setprio 0
	s_setprio 1
	v_mfma_f32_16x16x32_bf16 v[118:121], v[160:163], v[180:183], v[118:121]
	v_mfma_f32_16x16x32_bf16 v[114:117], v[172:175], v[180:183], v[114:117]
	v_mfma_f32_16x16x32_bf16 v[102:105], v[160:163], v[188:191], v[102:105]
	v_mfma_f32_16x16x32_bf16 v[98:101], v[172:175], v[188:191], v[98:101]
	v_mfma_f32_16x16x32_bf16 v[86:89], v[160:163], v[196:199], v[86:89]
	v_mfma_f32_16x16x32_bf16 v[82:85], v[172:175], v[196:199], v[82:85]
	v_mfma_f32_16x16x32_bf16 v[70:73], v[160:163], v[204:207], v[70:73]
	v_mfma_f32_16x16x32_bf16 v[66:69], v[172:175], v[204:207], v[66:69]
	v_mfma_f32_16x16x32_bf16 v[118:121], v[164:167], v[184:187], v[118:121]
	v_mfma_f32_16x16x32_bf16 v[114:117], v[176:179], v[184:187], v[114:117]
	v_mfma_f32_16x16x32_bf16 v[102:105], v[164:167], v[192:195], v[102:105]
	v_mfma_f32_16x16x32_bf16 v[98:101], v[176:179], v[192:195], v[98:101]
	v_mfma_f32_16x16x32_bf16 v[86:89], v[164:167], v[200:203], v[86:89]
	v_mfma_f32_16x16x32_bf16 v[82:85], v[176:179], v[200:203], v[82:85]
	v_mfma_f32_16x16x32_bf16 v[70:73], v[164:167], v[208:211], v[70:73]
	v_mfma_f32_16x16x32_bf16 v[66:69], v[176:179], v[208:211], v[66:69]
	s_setprio 0
	s_barrier
	s_add_i32 s0, s46, s26
	v_lshl_add_u64 v[212:213], v[212:213], 0, s[80:81]
	s_mov_b32 m0, s0
	ds_read_b128 v[180:183], v171 offset:49152
	ds_read_b128 v[184:187], v171 offset:50176
	ds_read_b128 v[188:191], v171 offset:51200
	ds_read_b128 v[192:195], v171 offset:52224
	ds_read_b128 v[196:199], v171 offset:53248
	ds_read_b128 v[200:203], v171 offset:54272
	ds_read_b128 v[204:207], v171 offset:55296
	ds_read_b128 v[208:211], v171 offset:56320
	global_load_lds_dwordx4 v[212:213], off
	s_add_i32 m0, s0, 0x2000
	s_add_u32 s0, s18, 0xb0080
	v_lshl_add_u64 v[212:213], v[214:215], 0, s[80:81]
	s_addc_u32 s1, s19, 0
	s_add_i32 s18, s47, s26
	global_load_lds_dwordx4 v[212:213], off
	v_lshl_add_u64 v[212:213], s[0:1], 0, v[138:139]
	s_mov_b32 m0, s18
	s_nop 0
	global_load_lds_dwordx4 v[212:213], off
	v_lshl_add_u64 v[212:213], s[0:1], 0, v[134:135]
	s_add_i32 m0, s18, 0x2000
	s_nop 0
	global_load_lds_dwordx4 v[212:213], off
	v_lshl_add_u64 v[212:213], v[216:217], 0, s[80:81]
	s_mov_b32 m0, s34
	s_nop 0
	global_load_lds_dwordx4 v[212:213], off
	v_lshl_add_u64 v[212:213], v[218:219], 0, s[80:81]
	s_mov_b32 m0, s35
	s_nop 0
	global_load_lds_dwordx4 v[212:213], off
	s_waitcnt vmcnt(8)
	s_waitcnt lgkmcnt(0)
	s_barrier
	s_setprio 1
	s_waitcnt lgkmcnt(0)
	v_mfma_f32_16x16x32_bf16 v[62:65], v[130:133], v[180:183], v[62:65]
	v_mfma_f32_16x16x32_bf16 v[58:61], v[152:155], v[180:183], v[58:61]
	v_mfma_f32_16x16x32_bf16 v[46:49], v[130:133], v[188:191], v[46:49]
	v_mfma_f32_16x16x32_bf16 v[42:45], v[152:155], v[188:191], v[42:45]
	v_mfma_f32_16x16x32_bf16 v[30:33], v[130:133], v[196:199], v[30:33]
	v_mfma_f32_16x16x32_bf16 v[26:29], v[152:155], v[196:199], v[26:29]
	v_mfma_f32_16x16x32_bf16 v[14:17], v[130:133], v[204:207], v[14:17]
	v_mfma_f32_16x16x32_bf16 v[10:13], v[152:155], v[204:207], v[10:13]
	v_mfma_f32_16x16x32_bf16 v[62:65], v[148:151], v[184:187], v[62:65]
	v_mfma_f32_16x16x32_bf16 v[58:61], v[156:159], v[184:187], v[58:61]
	v_mfma_f32_16x16x32_bf16 v[46:49], v[148:151], v[192:195], v[46:49]
	v_mfma_f32_16x16x32_bf16 v[42:45], v[156:159], v[192:195], v[42:45]
	v_mfma_f32_16x16x32_bf16 v[30:33], v[148:151], v[200:203], v[30:33]
	v_mfma_f32_16x16x32_bf16 v[26:29], v[156:159], v[200:203], v[26:29]
	v_mfma_f32_16x16x32_bf16 v[14:17], v[148:151], v[208:211], v[14:17]
	v_mfma_f32_16x16x32_bf16 v[10:13], v[156:159], v[208:211], v[10:13]
	s_setprio 0
	s_setprio 1
	v_mfma_f32_16x16x32_bf16 v[54:57], v[160:163], v[180:183], v[54:57]
	v_mfma_f32_16x16x32_bf16 v[50:53], v[172:175], v[180:183], v[50:53]
	v_mfma_f32_16x16x32_bf16 v[38:41], v[160:163], v[188:191], v[38:41]
	v_mfma_f32_16x16x32_bf16 v[34:37], v[172:175], v[188:191], v[34:37]
	v_mfma_f32_16x16x32_bf16 v[22:25], v[160:163], v[196:199], v[22:25]
	v_mfma_f32_16x16x32_bf16 v[18:21], v[172:175], v[196:199], v[18:21]
	v_mfma_f32_16x16x32_bf16 v[6:9], v[160:163], v[204:207], v[6:9]
	v_mfma_f32_16x16x32_bf16 v[2:5], v[172:175], v[204:207], v[2:5]
	v_mfma_f32_16x16x32_bf16 v[54:57], v[164:167], v[184:187], v[54:57]
	v_mfma_f32_16x16x32_bf16 v[50:53], v[176:179], v[184:187], v[50:53]
	v_mfma_f32_16x16x32_bf16 v[38:41], v[164:167], v[192:195], v[38:41]
	v_mfma_f32_16x16x32_bf16 v[34:37], v[176:179], v[192:195], v[34:37]
	v_mfma_f32_16x16x32_bf16 v[22:25], v[164:167], v[200:203], v[22:25]
	v_mfma_f32_16x16x32_bf16 v[18:21], v[176:179], v[200:203], v[18:21]
	v_mfma_f32_16x16x32_bf16 v[6:9], v[164:167], v[208:211], v[6:9]
	v_mfma_f32_16x16x32_bf16 v[2:5], v[176:179], v[208:211], v[2:5]
	s_setprio 0
	s_barrier
	s_add_i32 s45, s45, 2
	s_add_u32 s43, s43, 0x100
	s_addc_u32 s44, s44, 0
	s_cmp_gt_u32 s45, 41
	s_mov_b64 s[0:1], s[16:17]
	s_cbranch_scc0 .LBB0_1961
	s_and_b64 vcc, exec, s[10:11]
	s_cbranch_vccnz .LBB0_1966
	s_cmpk_lt_i32 s41, 0x80
	s_mov_b64 s[0:1], -1
	s_cbranch_scc0 .LBB0_1967

.LBB0_2199:
	s_add_u32 s24, s22, 0xfffc0080
	s_addc_u32 s25, s23, -1
	s_add_i32 s47, 0, 0x10000
	s_cmp_eq_u32 s46, 12
	s_cselect_b32 s27, s11, s25
	s_cselect_b32 s26, s42, s24
	s_cselect_b32 s25, s15, s45
	s_cselect_b32 s24, s43, s44
	s_add_i32 s50, 0, 0x14000
	v_add_u32_e32 v156, s47, v150
	v_add_u32_e32 v172, s50, v150
	ds_read_b128 v[130:133], v156
	ds_read_b128 v[146:149], v156 offset:1024
	ds_read_b128 v[152:155], v156 offset:2048
	ds_read_b128 v[156:159], v156 offset:3072
	ds_read_b128 v[160:163], v172
	ds_read_b128 v[164:167], v172 offset:1024
	ds_read_b128 v[168:171], v172 offset:2048
	ds_read_b128 v[172:175], v172 offset:3072
	v_lshl_add_u64 v[208:209], s[22:23], 0, v[142:143]
	s_add_i32 m0, s35, 0xc000
	ds_read_b128 v[176:179], v151
	ds_read_b128 v[180:183], v151 offset:1024
	ds_read_b128 v[184:187], v151 offset:2048
	ds_read_b128 v[188:191], v151 offset:3072
	ds_read_b128 v[192:195], v151 offset:4096
	ds_read_b128 v[196:199], v151 offset:5120
	ds_read_b128 v[200:203], v151 offset:6144
	ds_read_b128 v[204:207], v151 offset:7168
	global_load_lds_dwordx4 v[208:209], off
	v_lshl_add_u64 v[208:209], s[22:23], 0, v[144:145]
	s_add_i32 m0, s35, 0xe000
	s_nop 0
	global_load_lds_dwordx4 v[208:209], off
	s_waitcnt vmcnt(8)
	s_waitcnt lgkmcnt(0)
	s_barrier
	s_setprio 1
	s_waitcnt lgkmcnt(0)
	v_mfma_f32_16x16x32_bf16 v[126:129], v[130:133], v[176:179], v[126:129]
	v_mfma_f32_16x16x32_bf16 v[122:125], v[152:155], v[176:179], v[122:125]
	v_mfma_f32_16x16x32_bf16 v[110:113], v[130:133], v[184:187], v[110:113]
	v_mfma_f32_16x16x32_bf16 v[106:109], v[152:155], v[184:187], v[106:109]
	v_mfma_f32_16x16x32_bf16 v[94:97], v[130:133], v[192:195], v[94:97]
	v_mfma_f32_16x16x32_bf16 v[90:93], v[152:155], v[192:195], v[90:93]
	v_mfma_f32_16x16x32_bf16 v[78:81], v[130:133], v[200:203], v[78:81]
	v_mfma_f32_16x16x32_bf16 v[74:77], v[152:155], v[200:203], v[74:77]
	v_mfma_f32_16x16x32_bf16 v[126:129], v[146:149], v[180:183], v[126:129]
	v_mfma_f32_16x16x32_bf16 v[122:125], v[156:159], v[180:183], v[122:125]
	v_mfma_f32_16x16x32_bf16 v[110:113], v[146:149], v[188:191], v[110:113]
	v_mfma_f32_16x16x32_bf16 v[106:109], v[156:159], v[188:191], v[106:109]
	v_mfma_f32_16x16x32_bf16 v[94:97], v[146:149], v[196:199], v[94:97]
	v_mfma_f32_16x16x32_bf16 v[90:93], v[156:159], v[196:199], v[90:93]
	v_mfma_f32_16x16x32_bf16 v[78:81], v[146:149], v[204:207], v[78:81]
	v_mfma_f32_16x16x32_bf16 v[74:77], v[156:159], v[204:207], v[74:77]
	s_setprio 0
	s_setprio 1
	v_mfma_f32_16x16x32_bf16 v[118:121], v[160:163], v[176:179], v[118:121]
	v_mfma_f32_16x16x32_bf16 v[114:117], v[168:171], v[176:179], v[114:117]
	v_mfma_f32_16x16x32_bf16 v[102:105], v[160:163], v[184:187], v[102:105]
	v_mfma_f32_16x16x32_bf16 v[98:101], v[168:171], v[184:187], v[98:101]
	v_mfma_f32_16x16x32_bf16 v[86:89], v[160:163], v[192:195], v[86:89]
	v_mfma_f32_16x16x32_bf16 v[82:85], v[168:171], v[192:195], v[82:85]
	v_mfma_f32_16x16x32_bf16 v[70:73], v[160:163], v[200:203], v[70:73]
	v_mfma_f32_16x16x32_bf16 v[66:69], v[168:171], v[200:203], v[66:69]
	v_mfma_f32_16x16x32_bf16 v[118:121], v[164:167], v[180:183], v[118:121]
	v_mfma_f32_16x16x32_bf16 v[114:117], v[172:175], v[180:183], v[114:117]
	v_mfma_f32_16x16x32_bf16 v[102:105], v[164:167], v[188:191], v[102:105]
	v_mfma_f32_16x16x32_bf16 v[98:101], v[172:175], v[188:191], v[98:101]
	v_mfma_f32_16x16x32_bf16 v[86:89], v[164:167], v[196:199], v[86:89]
	v_mfma_f32_16x16x32_bf16 v[82:85], v[172:175], v[196:199], v[82:85]
	v_mfma_f32_16x16x32_bf16 v[70:73], v[164:167], v[204:207], v[70:73]
	v_mfma_f32_16x16x32_bf16 v[66:69], v[172:175], v[204:207], v[66:69]
	s_setprio 0
	s_barrier
	s_add_i32 s47, s47, s34
	v_lshl_add_u64 v[208:209], s[24:25], 0, v[0:1]
	s_mov_b32 m0, s47
	ds_read_b128 v[176:179], v151 offset:16384
	ds_read_b128 v[180:183], v151 offset:17408
	ds_read_b128 v[184:187], v151 offset:18432
	ds_read_b128 v[188:191], v151 offset:19456
	ds_read_b128 v[192:195], v151 offset:20480
	ds_read_b128 v[196:199], v151 offset:21504
	ds_read_b128 v[200:203], v151 offset:22528
	ds_read_b128 v[204:207], v151 offset:23552
	global_load_lds_dwordx4 v[208:209], off
	s_add_i32 m0, s47, 0x2000
	s_add_u32 s48, s24, 0x40000
	v_lshl_add_u64 v[210:211], s[24:25], 0, v[138:139]
	s_addc_u32 s49, s25, 0
	s_add_i32 s47, s50, s34
	global_load_lds_dwordx4 v[210:211], off
	v_lshl_add_u64 v[212:213], s[48:49], 0, v[0:1]
	s_mov_b32 m0, s47
	v_lshl_add_u64 v[214:215], s[26:27], 0, v[136:137]
	global_load_lds_dwordx4 v[212:213], off
	v_lshl_add_u64 v[212:213], s[48:49], 0, v[138:139]
	s_add_i32 m0, s47, 0x2000
	s_nop 0
	global_load_lds_dwordx4 v[212:213], off
	s_waitcnt vmcnt(6)
	s_waitcnt lgkmcnt(0)
	s_barrier
	s_setprio 1
	s_waitcnt lgkmcnt(0)
	v_mfma_f32_16x16x32_bf16 v[62:65], v[130:133], v[176:179], v[62:65]
	v_mfma_f32_16x16x32_bf16 v[58:61], v[152:155], v[176:179], v[58:61]
	v_mfma_f32_16x16x32_bf16 v[46:49], v[130:133], v[184:187], v[46:49]
	v_mfma_f32_16x16x32_bf16 v[42:45], v[152:155], v[184:187], v[42:45]
	v_mfma_f32_16x16x32_bf16 v[30:33], v[130:133], v[192:195], v[30:33]
	v_mfma_f32_16x16x32_bf16 v[26:29], v[152:155], v[192:195], v[26:29]
	v_mfma_f32_16x16x32_bf16 v[22:25], v[130:133], v[200:203], v[22:25]
	v_mfma_f32_16x16x32_bf16 v[18:21], v[152:155], v[200:203], v[18:21]
	v_mfma_f32_16x16x32_bf16 v[62:65], v[146:149], v[180:183], v[62:65]
	v_mfma_f32_16x16x32_bf16 v[58:61], v[156:159], v[180:183], v[58:61]
	v_mfma_f32_16x16x32_bf16 v[46:49], v[146:149], v[188:191], v[46:49]
	v_mfma_f32_16x16x32_bf16 v[42:45], v[156:159], v[188:191], v[42:45]
	v_mfma_f32_16x16x32_bf16 v[30:33], v[146:149], v[196:199], v[30:33]
	v_mfma_f32_16x16x32_bf16 v[26:29], v[156:159], v[196:199], v[26:29]
	v_mfma_f32_16x16x32_bf16 v[22:25], v[146:149], v[204:207], v[22:25]
	v_mfma_f32_16x16x32_bf16 v[18:21], v[156:159], v[204:207], v[18:21]
	s_setprio 0
	s_setprio 1
	v_mfma_f32_16x16x32_bf16 v[54:57], v[160:163], v[176:179], v[54:57]
	v_mfma_f32_16x16x32_bf16 v[50:53], v[168:171], v[176:179], v[50:53]
	v_mfma_f32_16x16x32_bf16 v[38:41], v[160:163], v[184:187], v[38:41]
	v_mfma_f32_16x16x32_bf16 v[34:37], v[168:171], v[184:187], v[34:37]
	v_mfma_f32_16x16x32_bf16 v[14:17], v[160:163], v[192:195], v[14:17]
	v_mfma_f32_16x16x32_bf16 v[10:13], v[168:171], v[192:195], v[10:13]
	v_mfma_f32_16x16x32_bf16 v[6:9], v[160:163], v[200:203], v[6:9]
	v_mfma_f32_16x16x32_bf16 v[2:5], v[168:171], v[200:203], v[2:5]
	v_mfma_f32_16x16x32_bf16 v[54:57], v[164:167], v[180:183], v[54:57]
	v_mfma_f32_16x16x32_bf16 v[50:53], v[172:175], v[180:183], v[50:53]
	v_mfma_f32_16x16x32_bf16 v[38:41], v[164:167], v[188:191], v[38:41]
	v_mfma_f32_16x16x32_bf16 v[34:37], v[172:175], v[188:191], v[34:37]
	v_mfma_f32_16x16x32_bf16 v[14:17], v[164:167], v[196:199], v[14:17]
	v_mfma_f32_16x16x32_bf16 v[10:13], v[172:175], v[196:199], v[10:13]
	v_mfma_f32_16x16x32_bf16 v[6:9], v[164:167], v[204:207], v[6:9]
	v_mfma_f32_16x16x32_bf16 v[2:5], v[172:175], v[204:207], v[2:5]
	s_setprio 0
	s_barrier
	s_add_i32 s47, 0, 0x18000
	s_add_i32 s48, 0, 0x1c000
	v_add_u32_e32 v156, s47, v150
	v_add_u32_e32 v172, s48, v150
	ds_read_b128 v[130:133], v156
	ds_read_b128 v[146:149], v156 offset:1024
	ds_read_b128 v[152:155], v156 offset:2048
	ds_read_b128 v[156:159], v156 offset:3072
	ds_read_b128 v[160:163], v172
	ds_read_b128 v[164:167], v172 offset:1024
	ds_read_b128 v[168:171], v172 offset:2048
	ds_read_b128 v[172:175], v172 offset:3072
	v_lshl_add_u64 v[212:213], s[26:27], 0, v[134:135]
	s_mov_b32 m0, s35
	s_nop 0
	global_load_lds_dwordx4 v[212:213], off
	s_mov_b32 m0, s36
	s_nop 0
	global_load_lds_dwordx4 v[214:215], off
	s_add_u32 s26, s26, 0x40000
	s_addc_u32 s27, s27, 0
	s_mov_b32 m0, s37
	v_lshl_add_u64 v[216:217], s[26:27], 0, v[134:135]
	ds_read_b128 v[176:179], v151 offset:32768
	ds_read_b128 v[180:183], v151 offset:33792
	ds_read_b128 v[184:187], v151 offset:34816
	ds_read_b128 v[188:191], v151 offset:35840
	ds_read_b128 v[192:195], v151 offset:36864
	ds_read_b128 v[196:199], v151 offset:37888
	ds_read_b128 v[200:203], v151 offset:38912
	ds_read_b128 v[204:207], v151 offset:39936
	global_load_lds_dwordx4 v[216:217], off
	v_lshl_add_u64 v[216:217], s[26:27], 0, v[136:137]
	s_mov_b32 m0, s38
	s_nop 0
	global_load_lds_dwordx4 v[216:217], off
	s_waitcnt vmcnt(8)
	s_waitcnt lgkmcnt(0)
	s_barrier
	s_setprio 1
	s_waitcnt lgkmcnt(0)
	v_mfma_f32_16x16x32_bf16 v[126:129], v[130:133], v[176:179], v[126:129]
	v_mfma_f32_16x16x32_bf16 v[122:125], v[152:155], v[176:179], v[122:125]
	v_mfma_f32_16x16x32_bf16 v[110:113], v[130:133], v[184:187], v[110:113]
	v_mfma_f32_16x16x32_bf16 v[106:109], v[152:155], v[184:187], v[106:109]
	v_mfma_f32_16x16x32_bf16 v[94:97], v[130:133], v[192:195], v[94:97]
	v_mfma_f32_16x16x32_bf16 v[90:93], v[152:155], v[192:195], v[90:93]
	v_mfma_f32_16x16x32_bf16 v[78:81], v[130:133], v[200:203], v[78:81]
	v_mfma_f32_16x16x32_bf16 v[74:77], v[152:155], v[200:203], v[74:77]
	v_mfma_f32_16x16x32_bf16 v[126:129], v[146:149], v[180:183], v[126:129]
	v_mfma_f32_16x16x32_bf16 v[122:125], v[156:159], v[180:183], v[122:125]
	v_mfma_f32_16x16x32_bf16 v[110:113], v[146:149], v[188:191], v[110:113]
	v_mfma_f32_16x16x32_bf16 v[106:109], v[156:159], v[188:191], v[106:109]
	v_mfma_f32_16x16x32_bf16 v[94:97], v[146:149], v[196:199], v[94:97]
	v_mfma_f32_16x16x32_bf16 v[90:93], v[156:159], v[196:199], v[90:93]
	v_mfma_f32_16x16x32_bf16 v[78:81], v[146:149], v[204:207], v[78:81]
	v_mfma_f32_16x16x32_bf16 v[74:77], v[156:159], v[204:207], v[74:77]
	s_setprio 0
	s_setprio 1
	v_mfma_f32_16x16x32_bf16 v[118:121], v[160:163], v[176:179], v[118:121]
	v_mfma_f32_16x16x32_bf16 v[114:117], v[168:171], v[176:179], v[114:117]
	v_mfma_f32_16x16x32_bf16 v[102:105], v[160:163], v[184:187], v[102:105]
	v_mfma_f32_16x16x32_bf16 v[98:101], v[168:171], v[184:187], v[98:101]
	v_mfma_f32_16x16x32_bf16 v[86:89], v[160:163], v[192:195], v[86:89]
	v_mfma_f32_16x16x32_bf16 v[82:85], v[168:171], v[192:195], v[82:85]
	v_mfma_f32_16x16x32_bf16 v[70:73], v[160:163], v[200:203], v[70:73]
	v_mfma_f32_16x16x32_bf16 v[66:69], v[168:171], v[200:203], v[66:69]
	v_mfma_f32_16x16x32_bf16 v[118:121], v[164:167], v[180:183], v[118:121]
	v_mfma_f32_16x16x32_bf16 v[114:117], v[172:175], v[180:183], v[114:117]
	v_mfma_f32_16x16x32_bf16 v[102:105], v[164:167], v[188:191], v[102:105]
	v_mfma_f32_16x16x32_bf16 v[98:101], v[172:175], v[188:191], v[98:101]
	v_mfma_f32_16x16x32_bf16 v[86:89], v[164:167], v[196:199], v[86:89]
	v_mfma_f32_16x16x32_bf16 v[82:85], v[172:175], v[196:199], v[82:85]
	v_mfma_f32_16x16x32_bf16 v[70:73], v[164:167], v[204:207], v[70:73]
	v_mfma_f32_16x16x32_bf16 v[66:69], v[172:175], v[204:207], v[66:69]
	s_setprio 0
	s_barrier
	s_add_i32 s26, s47, s34
	v_lshl_add_u64 v[208:209], v[208:209], 0, s[80:81]
	s_mov_b32 m0, s26
	ds_read_b128 v[176:179], v151 offset:49152
	ds_read_b128 v[180:183], v151 offset:50176
	ds_read_b128 v[184:187], v151 offset:51200
	ds_read_b128 v[188:191], v151 offset:52224
	ds_read_b128 v[192:195], v151 offset:53248
	ds_read_b128 v[196:199], v151 offset:54272
	ds_read_b128 v[200:203], v151 offset:55296
	ds_read_b128 v[204:207], v151 offset:56320
	global_load_lds_dwordx4 v[208:209], off
	s_add_i32 m0, s26, 0x2000
	s_add_u32 s24, s24, 0x40080
	v_lshl_add_u64 v[208:209], v[210:211], 0, s[80:81]
	s_addc_u32 s25, s25, 0
	s_add_i32 s26, s48, s34
	global_load_lds_dwordx4 v[208:209], off
	v_lshl_add_u64 v[208:209], s[24:25], 0, v[0:1]
	s_mov_b32 m0, s26
	s_nop 0
	global_load_lds_dwordx4 v[208:209], off
	v_lshl_add_u64 v[208:209], s[24:25], 0, v[138:139]
	s_add_i32 m0, s26, 0x2000
	s_nop 0
	global_load_lds_dwordx4 v[208:209], off
	v_lshl_add_u64 v[208:209], v[212:213], 0, s[80:81]
	s_mov_b32 m0, s39
	s_nop 0
	global_load_lds_dwordx4 v[208:209], off
	v_lshl_add_u64 v[208:209], v[214:215], 0, s[80:81]
	s_mov_b32 m0, s40
	s_nop 0
	global_load_lds_dwordx4 v[208:209], off
	s_waitcnt vmcnt(8)
	s_waitcnt lgkmcnt(0)
	s_barrier
	s_setprio 1
	s_waitcnt lgkmcnt(0)
	v_mfma_f32_16x16x32_bf16 v[62:65], v[130:133], v[176:179], v[62:65]
	v_mfma_f32_16x16x32_bf16 v[58:61], v[152:155], v[176:179], v[58:61]
	v_mfma_f32_16x16x32_bf16 v[46:49], v[130:133], v[184:187], v[46:49]
	v_mfma_f32_16x16x32_bf16 v[42:45], v[152:155], v[184:187], v[42:45]
	v_mfma_f32_16x16x32_bf16 v[30:33], v[130:133], v[192:195], v[30:33]
	v_mfma_f32_16x16x32_bf16 v[26:29], v[152:155], v[192:195], v[26:29]
	v_mfma_f32_16x16x32_bf16 v[22:25], v[130:133], v[200:203], v[22:25]
	v_mfma_f32_16x16x32_bf16 v[18:21], v[152:155], v[200:203], v[18:21]
	v_mfma_f32_16x16x32_bf16 v[62:65], v[146:149], v[180:183], v[62:65]
	v_mfma_f32_16x16x32_bf16 v[58:61], v[156:159], v[180:183], v[58:61]
	v_mfma_f32_16x16x32_bf16 v[46:49], v[146:149], v[188:191], v[46:49]
	v_mfma_f32_16x16x32_bf16 v[42:45], v[156:159], v[188:191], v[42:45]
	v_mfma_f32_16x16x32_bf16 v[30:33], v[146:149], v[196:199], v[30:33]
	v_mfma_f32_16x16x32_bf16 v[26:29], v[156:159], v[196:199], v[26:29]
	v_mfma_f32_16x16x32_bf16 v[22:25], v[146:149], v[204:207], v[22:25]
	v_mfma_f32_16x16x32_bf16 v[18:21], v[156:159], v[204:207], v[18:21]
	s_setprio 0
	s_setprio 1
	v_mfma_f32_16x16x32_bf16 v[54:57], v[160:163], v[176:179], v[54:57]
	v_mfma_f32_16x16x32_bf16 v[50:53], v[168:171], v[176:179], v[50:53]
	v_mfma_f32_16x16x32_bf16 v[38:41], v[160:163], v[184:187], v[38:41]
	v_mfma_f32_16x16x32_bf16 v[34:37], v[168:171], v[184:187], v[34:37]
	v_mfma_f32_16x16x32_bf16 v[14:17], v[160:163], v[192:195], v[14:17]
	v_mfma_f32_16x16x32_bf16 v[10:13], v[168:171], v[192:195], v[10:13]
	v_mfma_f32_16x16x32_bf16 v[6:9], v[160:163], v[200:203], v[6:9]
	v_mfma_f32_16x16x32_bf16 v[2:5], v[168:171], v[200:203], v[2:5]
	v_mfma_f32_16x16x32_bf16 v[54:57], v[164:167], v[180:183], v[54:57]
	v_mfma_f32_16x16x32_bf16 v[50:53], v[172:175], v[180:183], v[50:53]
	v_mfma_f32_16x16x32_bf16 v[38:41], v[164:167], v[188:191], v[38:41]
	v_mfma_f32_16x16x32_bf16 v[34:37], v[172:175], v[188:191], v[34:37]
	v_mfma_f32_16x16x32_bf16 v[14:17], v[164:167], v[196:199], v[14:17]
	v_mfma_f32_16x16x32_bf16 v[10:13], v[172:175], v[196:199], v[10:13]
	v_mfma_f32_16x16x32_bf16 v[6:9], v[164:167], v[204:207], v[6:9]
	v_mfma_f32_16x16x32_bf16 v[2:5], v[172:175], v[204:207], v[2:5]
	s_setprio 0
	s_barrier
	s_add_i32 s46, s46, 2
	s_add_u32 s22, s22, 0x100
	s_addc_u32 s23, s23, 0
	s_add_u32 s44, s44, 0x100
	s_addc_u32 s45, s45, 0
	s_cmp_gt_u32 s46, 13
	s_cbranch_scc0 .LBB0_2199
	s_and_b64 vcc, exec, s[8:9]
	s_cbranch_vccz .LBB0_2202
	s_barrier

.LBB0_2277:
	s_add_u32 s26, s24, 0xfffc0080
	s_addc_u32 s27, s25, -1
	s_add_i32 s49, 0, 0x10000
	s_cmp_eq_u32 s48, 12
	s_cselect_b32 s29, s11, s27
	s_cselect_b32 s28, s44, s26
	s_cselect_b32 s27, s15, s47
	s_cselect_b32 s26, s45, s46
	s_add_i32 s52, 0, 0x14000
	v_add_u32_e32 v142, s49, v164
	v_add_u32_e32 v162, s52, v164
	ds_read_b128 v[130:133], v142
	ds_read_b128 v[134:137], v142 offset:1024
	ds_read_b128 v[138:141], v142 offset:2048
	ds_read_b128 v[142:145], v142 offset:3072
	ds_read_b128 v[158:161], v162
	ds_read_b128 v[166:169], v162 offset:1024
	ds_read_b128 v[170:173], v162 offset:2048
	ds_read_b128 v[174:177], v162 offset:3072
	v_lshl_add_u64 v[162:163], s[24:25], 0, v[154:155]
	s_add_i32 m0, s37, 0xc000
	ds_read_b128 v[178:181], v165
	ds_read_b128 v[182:185], v165 offset:1024
	ds_read_b128 v[186:189], v165 offset:2048
	ds_read_b128 v[190:193], v165 offset:3072
	ds_read_b128 v[194:197], v165 offset:4096
	ds_read_b128 v[198:201], v165 offset:5120
	ds_read_b128 v[202:205], v165 offset:6144
	ds_read_b128 v[206:209], v165 offset:7168
	global_load_lds_dwordx4 v[162:163], off
	v_lshl_add_u64 v[162:163], s[24:25], 0, v[156:157]
	s_add_i32 m0, s37, 0xe000
	s_nop 0
	global_load_lds_dwordx4 v[162:163], off
	s_waitcnt vmcnt(8)
	s_waitcnt lgkmcnt(0)
	s_barrier
	s_setprio 1
	s_waitcnt lgkmcnt(0)
	v_mfma_f32_16x16x32_bf16 v[126:129], v[130:133], v[178:181], v[126:129]
	v_mfma_f32_16x16x32_bf16 v[122:125], v[138:141], v[178:181], v[122:125]
	v_mfma_f32_16x16x32_bf16 v[110:113], v[130:133], v[186:189], v[110:113]
	v_mfma_f32_16x16x32_bf16 v[106:109], v[138:141], v[186:189], v[106:109]
	v_mfma_f32_16x16x32_bf16 v[94:97], v[130:133], v[194:197], v[94:97]
	v_mfma_f32_16x16x32_bf16 v[90:93], v[138:141], v[194:197], v[90:93]
	v_mfma_f32_16x16x32_bf16 v[78:81], v[130:133], v[202:205], v[78:81]
	v_mfma_f32_16x16x32_bf16 v[74:77], v[138:141], v[202:205], v[74:77]
	v_mfma_f32_16x16x32_bf16 v[126:129], v[134:137], v[182:185], v[126:129]
	v_mfma_f32_16x16x32_bf16 v[122:125], v[142:145], v[182:185], v[122:125]
	v_mfma_f32_16x16x32_bf16 v[110:113], v[134:137], v[190:193], v[110:113]
	v_mfma_f32_16x16x32_bf16 v[106:109], v[142:145], v[190:193], v[106:109]
	v_mfma_f32_16x16x32_bf16 v[94:97], v[134:137], v[198:201], v[94:97]
	v_mfma_f32_16x16x32_bf16 v[90:93], v[142:145], v[198:201], v[90:93]
	v_mfma_f32_16x16x32_bf16 v[78:81], v[134:137], v[206:209], v[78:81]
	v_mfma_f32_16x16x32_bf16 v[74:77], v[142:145], v[206:209], v[74:77]
	s_setprio 0
	s_setprio 1
	v_mfma_f32_16x16x32_bf16 v[118:121], v[158:161], v[178:181], v[118:121]
	v_mfma_f32_16x16x32_bf16 v[114:117], v[170:173], v[178:181], v[114:117]
	v_mfma_f32_16x16x32_bf16 v[102:105], v[158:161], v[186:189], v[102:105]
	v_mfma_f32_16x16x32_bf16 v[98:101], v[170:173], v[186:189], v[98:101]
	v_mfma_f32_16x16x32_bf16 v[86:89], v[158:161], v[194:197], v[86:89]
	v_mfma_f32_16x16x32_bf16 v[82:85], v[170:173], v[194:197], v[82:85]
	v_mfma_f32_16x16x32_bf16 v[70:73], v[158:161], v[202:205], v[70:73]
	v_mfma_f32_16x16x32_bf16 v[66:69], v[170:173], v[202:205], v[66:69]
	v_mfma_f32_16x16x32_bf16 v[118:121], v[166:169], v[182:185], v[118:121]
	v_mfma_f32_16x16x32_bf16 v[114:117], v[174:177], v[182:185], v[114:117]
	v_mfma_f32_16x16x32_bf16 v[102:105], v[166:169], v[190:193], v[102:105]
	v_mfma_f32_16x16x32_bf16 v[98:101], v[174:177], v[190:193], v[98:101]
	v_mfma_f32_16x16x32_bf16 v[86:89], v[166:169], v[198:201], v[86:89]
	v_mfma_f32_16x16x32_bf16 v[82:85], v[174:177], v[198:201], v[82:85]
	v_mfma_f32_16x16x32_bf16 v[70:73], v[166:169], v[206:209], v[70:73]
	v_mfma_f32_16x16x32_bf16 v[66:69], v[174:177], v[206:209], v[66:69]
	s_setprio 0
	s_barrier
	s_add_i32 s49, s49, s36
	v_lshl_add_u64 v[162:163], s[26:27], 0, v[0:1]
	s_mov_b32 m0, s49
	ds_read_b128 v[178:181], v165 offset:16384
	ds_read_b128 v[182:185], v165 offset:17408
	ds_read_b128 v[186:189], v165 offset:18432
	ds_read_b128 v[190:193], v165 offset:19456
	ds_read_b128 v[194:197], v165 offset:20480
	ds_read_b128 v[198:201], v165 offset:21504
	ds_read_b128 v[202:205], v165 offset:22528
	ds_read_b128 v[206:209], v165 offset:23552
	global_load_lds_dwordx4 v[162:163], off
	s_add_i32 m0, s49, 0x2000
	s_add_u32 s50, s26, 0x40000
	v_lshl_add_u64 v[210:211], s[26:27], 0, v[150:151]
	s_addc_u32 s51, s27, 0
	s_add_i32 s49, s52, s36
	global_load_lds_dwordx4 v[210:211], off
	v_lshl_add_u64 v[212:213], s[50:51], 0, v[0:1]
	s_mov_b32 m0, s49
	v_lshl_add_u64 v[214:215], s[28:29], 0, v[148:149]
	global_load_lds_dwordx4 v[212:213], off
	v_lshl_add_u64 v[212:213], s[50:51], 0, v[150:151]
	s_add_i32 m0, s49, 0x2000
	s_nop 0
	global_load_lds_dwordx4 v[212:213], off
	s_waitcnt vmcnt(6)
	s_waitcnt lgkmcnt(0)
	s_barrier
	s_setprio 1
	s_waitcnt lgkmcnt(0)
	v_mfma_f32_16x16x32_bf16 v[62:65], v[130:133], v[178:181], v[62:65]
	v_mfma_f32_16x16x32_bf16 v[58:61], v[138:141], v[178:181], v[58:61]
	v_mfma_f32_16x16x32_bf16 v[46:49], v[130:133], v[186:189], v[46:49]
	v_mfma_f32_16x16x32_bf16 v[42:45], v[138:141], v[186:189], v[42:45]
	v_mfma_f32_16x16x32_bf16 v[30:33], v[130:133], v[194:197], v[30:33]
	v_mfma_f32_16x16x32_bf16 v[26:29], v[138:141], v[194:197], v[26:29]
	v_mfma_f32_16x16x32_bf16 v[14:17], v[130:133], v[202:205], v[14:17]
	v_mfma_f32_16x16x32_bf16 v[10:13], v[138:141], v[202:205], v[10:13]
	v_mfma_f32_16x16x32_bf16 v[62:65], v[134:137], v[182:185], v[62:65]
	v_mfma_f32_16x16x32_bf16 v[58:61], v[142:145], v[182:185], v[58:61]
	v_mfma_f32_16x16x32_bf16 v[46:49], v[134:137], v[190:193], v[46:49]
	v_mfma_f32_16x16x32_bf16 v[42:45], v[142:145], v[190:193], v[42:45]
	v_mfma_f32_16x16x32_bf16 v[30:33], v[134:137], v[198:201], v[30:33]
	v_mfma_f32_16x16x32_bf16 v[26:29], v[142:145], v[198:201], v[26:29]
	v_mfma_f32_16x16x32_bf16 v[14:17], v[134:137], v[206:209], v[14:17]
	v_mfma_f32_16x16x32_bf16 v[10:13], v[142:145], v[206:209], v[10:13]
	s_setprio 0
	s_setprio 1
	v_mfma_f32_16x16x32_bf16 v[54:57], v[158:161], v[178:181], v[54:57]
	v_mfma_f32_16x16x32_bf16 v[50:53], v[170:173], v[178:181], v[50:53]
	v_mfma_f32_16x16x32_bf16 v[38:41], v[158:161], v[186:189], v[38:41]
	v_mfma_f32_16x16x32_bf16 v[34:37], v[170:173], v[186:189], v[34:37]
	v_mfma_f32_16x16x32_bf16 v[22:25], v[158:161], v[194:197], v[22:25]
	v_mfma_f32_16x16x32_bf16 v[18:21], v[170:173], v[194:197], v[18:21]
	v_mfma_f32_16x16x32_bf16 v[6:9], v[158:161], v[202:205], v[6:9]
	v_mfma_f32_16x16x32_bf16 v[2:5], v[170:173], v[202:205], v[2:5]
	v_mfma_f32_16x16x32_bf16 v[54:57], v[166:169], v[182:185], v[54:57]
	v_mfma_f32_16x16x32_bf16 v[50:53], v[174:177], v[182:185], v[50:53]
	v_mfma_f32_16x16x32_bf16 v[38:41], v[166:169], v[190:193], v[38:41]
	v_mfma_f32_16x16x32_bf16 v[34:37], v[174:177], v[190:193], v[34:37]
	v_mfma_f32_16x16x32_bf16 v[22:25], v[166:169], v[198:201], v[22:25]
	v_mfma_f32_16x16x32_bf16 v[18:21], v[174:177], v[198:201], v[18:21]
	v_mfma_f32_16x16x32_bf16 v[6:9], v[166:169], v[206:209], v[6:9]
	v_mfma_f32_16x16x32_bf16 v[2:5], v[174:177], v[206:209], v[2:5]
	s_setprio 0
	s_barrier
	s_add_i32 s49, 0, 0x18000
	s_add_i32 s50, 0, 0x1c000
	v_add_u32_e32 v142, s49, v164
	v_add_u32_e32 v174, s50, v164
	ds_read_b128 v[130:133], v142
	ds_read_b128 v[134:137], v142 offset:1024
	ds_read_b128 v[138:141], v142 offset:2048
	ds_read_b128 v[142:145], v142 offset:3072
	ds_read_b128 v[158:161], v174
	ds_read_b128 v[166:169], v174 offset:1024
	ds_read_b128 v[170:173], v174 offset:2048
	ds_read_b128 v[174:177], v174 offset:3072
	v_lshl_add_u64 v[212:213], s[28:29], 0, v[146:147]
	s_mov_b32 m0, s37
	s_nop 0
	global_load_lds_dwordx4 v[212:213], off
	s_mov_b32 m0, s38
	s_nop 0
	global_load_lds_dwordx4 v[214:215], off
	s_add_u32 s28, s28, 0x40000
	s_addc_u32 s29, s29, 0
	s_mov_b32 m0, s39
	v_lshl_add_u64 v[216:217], s[28:29], 0, v[146:147]
	ds_read_b128 v[178:181], v165 offset:32768
	ds_read_b128 v[182:185], v165 offset:33792
	ds_read_b128 v[186:189], v165 offset:34816
	ds_read_b128 v[190:193], v165 offset:35840
	ds_read_b128 v[194:197], v165 offset:36864
	ds_read_b128 v[198:201], v165 offset:37888
	ds_read_b128 v[202:205], v165 offset:38912
	ds_read_b128 v[206:209], v165 offset:39936
	global_load_lds_dwordx4 v[216:217], off
	v_lshl_add_u64 v[216:217], s[28:29], 0, v[148:149]
	s_mov_b32 m0, s40
	s_nop 0
	global_load_lds_dwordx4 v[216:217], off
	s_waitcnt vmcnt(8)
	s_waitcnt lgkmcnt(0)
	s_barrier
	s_setprio 1
	s_waitcnt lgkmcnt(0)
	v_mfma_f32_16x16x32_bf16 v[126:129], v[130:133], v[178:181], v[126:129]
	v_mfma_f32_16x16x32_bf16 v[122:125], v[138:141], v[178:181], v[122:125]
	v_mfma_f32_16x16x32_bf16 v[110:113], v[130:133], v[186:189], v[110:113]
	v_mfma_f32_16x16x32_bf16 v[106:109], v[138:141], v[186:189], v[106:109]
	v_mfma_f32_16x16x32_bf16 v[94:97], v[130:133], v[194:197], v[94:97]
	v_mfma_f32_16x16x32_bf16 v[90:93], v[138:141], v[194:197], v[90:93]
	v_mfma_f32_16x16x32_bf16 v[78:81], v[130:133], v[202:205], v[78:81]
	v_mfma_f32_16x16x32_bf16 v[74:77], v[138:141], v[202:205], v[74:77]
	v_mfma_f32_16x16x32_bf16 v[126:129], v[134:137], v[182:185], v[126:129]
	v_mfma_f32_16x16x32_bf16 v[122:125], v[142:145], v[182:185], v[122:125]
	v_mfma_f32_16x16x32_bf16 v[110:113], v[134:137], v[190:193], v[110:113]
	v_mfma_f32_16x16x32_bf16 v[106:109], v[142:145], v[190:193], v[106:109]
	v_mfma_f32_16x16x32_bf16 v[94:97], v[134:137], v[198:201], v[94:97]
	v_mfma_f32_16x16x32_bf16 v[90:93], v[142:145], v[198:201], v[90:93]
	v_mfma_f32_16x16x32_bf16 v[78:81], v[134:137], v[206:209], v[78:81]
	v_mfma_f32_16x16x32_bf16 v[74:77], v[142:145], v[206:209], v[74:77]
	s_setprio 0
	s_setprio 1
	v_mfma_f32_16x16x32_bf16 v[118:121], v[158:161], v[178:181], v[118:121]
	v_mfma_f32_16x16x32_bf16 v[114:117], v[170:173], v[178:181], v[114:117]
	v_mfma_f32_16x16x32_bf16 v[102:105], v[158:161], v[186:189], v[102:105]
	v_mfma_f32_16x16x32_bf16 v[98:101], v[170:173], v[186:189], v[98:101]
	v_mfma_f32_16x16x32_bf16 v[86:89], v[158:161], v[194:197], v[86:89]
	v_mfma_f32_16x16x32_bf16 v[82:85], v[170:173], v[194:197], v[82:85]
	v_mfma_f32_16x16x32_bf16 v[70:73], v[158:161], v[202:205], v[70:73]
	v_mfma_f32_16x16x32_bf16 v[66:69], v[170:173], v[202:205], v[66:69]
	v_mfma_f32_16x16x32_bf16 v[118:121], v[166:169], v[182:185], v[118:121]
	v_mfma_f32_16x16x32_bf16 v[114:117], v[174:177], v[182:185], v[114:117]
	v_mfma_f32_16x16x32_bf16 v[102:105], v[166:169], v[190:193], v[102:105]
	v_mfma_f32_16x16x32_bf16 v[98:101], v[174:177], v[190:193], v[98:101]
	v_mfma_f32_16x16x32_bf16 v[86:89], v[166:169], v[198:201], v[86:89]
	v_mfma_f32_16x16x32_bf16 v[82:85], v[174:177], v[198:201], v[82:85]
	v_mfma_f32_16x16x32_bf16 v[70:73], v[166:169], v[206:209], v[70:73]
	v_mfma_f32_16x16x32_bf16 v[66:69], v[174:177], v[206:209], v[66:69]
	s_setprio 0
	s_barrier
	s_add_i32 s28, s49, s36
	v_lshl_add_u64 v[162:163], v[162:163], 0, s[80:81]
	s_mov_b32 m0, s28
	ds_read_b128 v[178:181], v165 offset:49152
	ds_read_b128 v[182:185], v165 offset:50176
	ds_read_b128 v[186:189], v165 offset:51200
	ds_read_b128 v[190:193], v165 offset:52224
	ds_read_b128 v[194:197], v165 offset:53248
	ds_read_b128 v[198:201], v165 offset:54272
	ds_read_b128 v[202:205], v165 offset:55296
	ds_read_b128 v[206:209], v165 offset:56320
	global_load_lds_dwordx4 v[162:163], off
	s_add_i32 m0, s28, 0x2000
	s_add_u32 s26, s26, 0x40080
	v_lshl_add_u64 v[162:163], v[210:211], 0, s[80:81]
	s_addc_u32 s27, s27, 0
	s_add_i32 s28, s50, s36
	global_load_lds_dwordx4 v[162:163], off
	v_lshl_add_u64 v[162:163], s[26:27], 0, v[0:1]
	s_mov_b32 m0, s28
	s_nop 0
	global_load_lds_dwordx4 v[162:163], off
	v_lshl_add_u64 v[162:163], s[26:27], 0, v[150:151]
	s_add_i32 m0, s28, 0x2000
	s_nop 0
	global_load_lds_dwordx4 v[162:163], off
	v_lshl_add_u64 v[162:163], v[212:213], 0, s[80:81]
	s_mov_b32 m0, s41
	s_nop 0
	global_load_lds_dwordx4 v[162:163], off
	v_lshl_add_u64 v[162:163], v[214:215], 0, s[80:81]
	s_mov_b32 m0, s42
	s_nop 0
	global_load_lds_dwordx4 v[162:163], off
	s_waitcnt vmcnt(8)
	s_waitcnt lgkmcnt(0)
	s_barrier
	s_setprio 1
	s_waitcnt lgkmcnt(0)
	v_mfma_f32_16x16x32_bf16 v[62:65], v[130:133], v[178:181], v[62:65]
	v_mfma_f32_16x16x32_bf16 v[58:61], v[138:141], v[178:181], v[58:61]
	v_mfma_f32_16x16x32_bf16 v[46:49], v[130:133], v[186:189], v[46:49]
	v_mfma_f32_16x16x32_bf16 v[42:45], v[138:141], v[186:189], v[42:45]
	v_mfma_f32_16x16x32_bf16 v[30:33], v[130:133], v[194:197], v[30:33]
	v_mfma_f32_16x16x32_bf16 v[26:29], v[138:141], v[194:197], v[26:29]
	v_mfma_f32_16x16x32_bf16 v[14:17], v[130:133], v[202:205], v[14:17]
	v_mfma_f32_16x16x32_bf16 v[10:13], v[138:141], v[202:205], v[10:13]
	v_mfma_f32_16x16x32_bf16 v[62:65], v[134:137], v[182:185], v[62:65]
	v_mfma_f32_16x16x32_bf16 v[58:61], v[142:145], v[182:185], v[58:61]
	v_mfma_f32_16x16x32_bf16 v[46:49], v[134:137], v[190:193], v[46:49]
	v_mfma_f32_16x16x32_bf16 v[42:45], v[142:145], v[190:193], v[42:45]
	v_mfma_f32_16x16x32_bf16 v[30:33], v[134:137], v[198:201], v[30:33]
	v_mfma_f32_16x16x32_bf16 v[26:29], v[142:145], v[198:201], v[26:29]
	v_mfma_f32_16x16x32_bf16 v[14:17], v[134:137], v[206:209], v[14:17]
	v_mfma_f32_16x16x32_bf16 v[10:13], v[142:145], v[206:209], v[10:13]
	s_setprio 0
	s_setprio 1
	v_mfma_f32_16x16x32_bf16 v[54:57], v[158:161], v[178:181], v[54:57]
	v_mfma_f32_16x16x32_bf16 v[50:53], v[170:173], v[178:181], v[50:53]
	v_mfma_f32_16x16x32_bf16 v[38:41], v[158:161], v[186:189], v[38:41]
	v_mfma_f32_16x16x32_bf16 v[34:37], v[170:173], v[186:189], v[34:37]
	v_mfma_f32_16x16x32_bf16 v[22:25], v[158:161], v[194:197], v[22:25]
	v_mfma_f32_16x16x32_bf16 v[18:21], v[170:173], v[194:197], v[18:21]
	v_mfma_f32_16x16x32_bf16 v[6:9], v[158:161], v[202:205], v[6:9]
	v_mfma_f32_16x16x32_bf16 v[2:5], v[170:173], v[202:205], v[2:5]
	v_mfma_f32_16x16x32_bf16 v[54:57], v[166:169], v[182:185], v[54:57]
	v_mfma_f32_16x16x32_bf16 v[50:53], v[174:177], v[182:185], v[50:53]
	v_mfma_f32_16x16x32_bf16 v[38:41], v[166:169], v[190:193], v[38:41]
	v_mfma_f32_16x16x32_bf16 v[34:37], v[174:177], v[190:193], v[34:37]
	v_mfma_f32_16x16x32_bf16 v[22:25], v[166:169], v[198:201], v[22:25]
	v_mfma_f32_16x16x32_bf16 v[18:21], v[174:177], v[198:201], v[18:21]
	v_mfma_f32_16x16x32_bf16 v[6:9], v[166:169], v[206:209], v[6:9]
	v_mfma_f32_16x16x32_bf16 v[2:5], v[174:177], v[206:209], v[2:5]
	s_setprio 0
	s_barrier
	s_add_i32 s48, s48, 2
	s_add_u32 s24, s24, 0x100
	s_addc_u32 s25, s25, 0
	s_add_u32 s46, s46, 0x100
	s_addc_u32 s47, s47, 0
	s_cmp_gt_u32 s48, 13
	s_cbranch_scc0 .LBB0_2277
	s_and_b64 vcc, exec, s[8:9]
	s_cbranch_vccz .LBB0_2280
	s_barrier

.LBB0_2357:
	s_add_u32 s40, s38, 0xfffc0080
	s_addc_u32 s41, s39, -1
	s_add_i32 s64, 0, 0x10000
	s_cmp_eq_u32 s63, 12
	s_cselect_b32 s43, s1, s41
	s_cselect_b32 s42, s25, s40
	s_cselect_b32 s41, s27, s62
	s_cselect_b32 s40, s37, s61
	s_add_i32 s66, 0, 0x14000
	v_add_u32_e32 v102, s64, v185
	v_add_u32_e32 v170, s66, v185
	ds_read_b128 v[86:89], v102
	ds_read_b128 v[94:97], v102 offset:1024
	ds_read_b128 v[98:101], v102 offset:2048
	ds_read_b128 v[102:105], v102 offset:3072
	ds_read_b128 v[146:149], v170
	ds_read_b128 v[150:153], v170 offset:1024
	ds_read_b128 v[166:169], v170 offset:2048
	ds_read_b128 v[170:173], v170 offset:3072
	v_lshl_add_u64 v[182:183], s[38:39], 0, v[162:163]
	s_add_i32 m0, s49, 0xc000
	ds_read_b128 v[174:177], v191
	ds_read_b128 v[178:181], v191 offset:1024
	ds_read_b128 v[198:201], v191 offset:2048
	ds_read_b128 v[202:205], v191 offset:3072
	ds_read_b128 v[206:209], v191 offset:4096
	ds_read_b128 v[210:213], v191 offset:5120
	ds_read_b128 v[214:217], v191 offset:6144
	ds_read_b128 v[218:221], v191 offset:7168
	global_load_lds_dwordx4 v[182:183], off
	v_lshl_add_u64 v[182:183], s[38:39], 0, v[164:165]
	s_add_i32 m0, s49, 0xe000
	s_nop 0
	global_load_lds_dwordx4 v[182:183], off
	s_waitcnt vmcnt(8)
	s_waitcnt lgkmcnt(0)
	s_barrier
	s_setprio 1
	s_waitcnt lgkmcnt(0)
	v_mfma_f32_16x16x32_bf16 v[142:145], v[86:89], v[174:177], v[142:145]
	v_mfma_f32_16x16x32_bf16 v[138:141], v[98:101], v[174:177], v[138:141]
	v_mfma_f32_16x16x32_bf16 v[126:129], v[86:89], v[198:201], v[126:129]
	v_mfma_f32_16x16x32_bf16 v[122:125], v[98:101], v[198:201], v[122:125]
	v_mfma_f32_16x16x32_bf16 v[110:113], v[86:89], v[206:209], v[110:113]
	v_mfma_f32_16x16x32_bf16 v[106:109], v[98:101], v[206:209], v[106:109]
	v_mfma_f32_16x16x32_bf16 v[78:81], v[86:89], v[214:217], v[78:81]
	v_mfma_f32_16x16x32_bf16 v[74:77], v[98:101], v[214:217], v[74:77]
	v_mfma_f32_16x16x32_bf16 v[142:145], v[94:97], v[178:181], v[142:145]
	v_mfma_f32_16x16x32_bf16 v[138:141], v[102:105], v[178:181], v[138:141]
	v_mfma_f32_16x16x32_bf16 v[126:129], v[94:97], v[202:205], v[126:129]
	v_mfma_f32_16x16x32_bf16 v[122:125], v[102:105], v[202:205], v[122:125]
	v_mfma_f32_16x16x32_bf16 v[110:113], v[94:97], v[210:213], v[110:113]
	v_mfma_f32_16x16x32_bf16 v[106:109], v[102:105], v[210:213], v[106:109]
	v_mfma_f32_16x16x32_bf16 v[78:81], v[94:97], v[218:221], v[78:81]
	v_mfma_f32_16x16x32_bf16 v[74:77], v[102:105], v[218:221], v[74:77]
	s_setprio 0
	s_setprio 1
	v_mfma_f32_16x16x32_bf16 v[134:137], v[146:149], v[174:177], v[134:137]
	v_mfma_f32_16x16x32_bf16 v[130:133], v[166:169], v[174:177], v[130:133]
	v_mfma_f32_16x16x32_bf16 v[118:121], v[146:149], v[198:201], v[118:121]
	v_mfma_f32_16x16x32_bf16 v[114:117], v[166:169], v[198:201], v[114:117]
	v_mfma_f32_16x16x32_bf16 v[90:93], v[146:149], v[206:209], v[90:93]
	v_mfma_f32_16x16x32_bf16 v[82:85], v[166:169], v[206:209], v[82:85]
	v_mfma_f32_16x16x32_bf16 v[70:73], v[146:149], v[214:217], v[70:73]
	v_mfma_f32_16x16x32_bf16 v[66:69], v[166:169], v[214:217], v[66:69]
	v_mfma_f32_16x16x32_bf16 v[134:137], v[150:153], v[178:181], v[134:137]
	v_mfma_f32_16x16x32_bf16 v[130:133], v[170:173], v[178:181], v[130:133]
	v_mfma_f32_16x16x32_bf16 v[118:121], v[150:153], v[202:205], v[118:121]
	v_mfma_f32_16x16x32_bf16 v[114:117], v[170:173], v[202:205], v[114:117]
	v_mfma_f32_16x16x32_bf16 v[90:93], v[150:153], v[210:213], v[90:93]
	v_mfma_f32_16x16x32_bf16 v[82:85], v[170:173], v[210:213], v[82:85]
	v_mfma_f32_16x16x32_bf16 v[70:73], v[150:153], v[218:221], v[70:73]
	v_mfma_f32_16x16x32_bf16 v[66:69], v[170:173], v[218:221], v[66:69]
	s_setprio 0
	s_barrier
	s_add_i32 s64, s64, s48
	v_lshl_add_u64 v[182:183], s[40:41], 0, v[0:1]
	s_mov_b32 m0, s64
	ds_read_b128 v[174:177], v191 offset:16384
	ds_read_b128 v[178:181], v191 offset:17408
	ds_read_b128 v[198:201], v191 offset:18432
	ds_read_b128 v[202:205], v191 offset:19456
	ds_read_b128 v[206:209], v191 offset:20480
	ds_read_b128 v[210:213], v191 offset:21504
	ds_read_b128 v[214:217], v191 offset:22528
	ds_read_b128 v[218:221], v191 offset:23552
	global_load_lds_dwordx4 v[182:183], off
	s_add_i32 m0, s64, 0x2000
	s_add_u32 s64, s40, 0x40000
	v_lshl_add_u64 v[222:223], s[40:41], 0, v[158:159]
	s_addc_u32 s65, s41, 0
	s_add_i32 s66, s66, s48
	global_load_lds_dwordx4 v[222:223], off
	v_lshl_add_u64 v[224:225], s[64:65], 0, v[0:1]
	s_mov_b32 m0, s66
	v_lshl_add_u64 v[226:227], s[42:43], 0, v[156:157]
	global_load_lds_dwordx4 v[224:225], off
	v_lshl_add_u64 v[224:225], s[64:65], 0, v[158:159]
	s_add_i32 m0, s66, 0x2000
	s_nop 0
	global_load_lds_dwordx4 v[224:225], off
	s_waitcnt vmcnt(6)
	s_waitcnt lgkmcnt(0)
	s_barrier
	s_setprio 1
	s_waitcnt lgkmcnt(0)
	v_mfma_f32_16x16x32_bf16 v[62:65], v[86:89], v[174:177], v[62:65]
	v_mfma_f32_16x16x32_bf16 v[58:61], v[98:101], v[174:177], v[58:61]
	v_mfma_f32_16x16x32_bf16 v[46:49], v[86:89], v[198:201], v[46:49]
	v_mfma_f32_16x16x32_bf16 v[42:45], v[98:101], v[198:201], v[42:45]
	v_mfma_f32_16x16x32_bf16 v[30:33], v[86:89], v[206:209], v[30:33]
	v_mfma_f32_16x16x32_bf16 v[26:29], v[98:101], v[206:209], v[26:29]
	v_mfma_f32_16x16x32_bf16 v[14:17], v[86:89], v[214:217], v[14:17]
	v_mfma_f32_16x16x32_bf16 v[10:13], v[98:101], v[214:217], v[10:13]
	v_mfma_f32_16x16x32_bf16 v[62:65], v[94:97], v[178:181], v[62:65]
	v_mfma_f32_16x16x32_bf16 v[58:61], v[102:105], v[178:181], v[58:61]
	v_mfma_f32_16x16x32_bf16 v[46:49], v[94:97], v[202:205], v[46:49]
	v_mfma_f32_16x16x32_bf16 v[42:45], v[102:105], v[202:205], v[42:45]
	v_mfma_f32_16x16x32_bf16 v[30:33], v[94:97], v[210:213], v[30:33]
	v_mfma_f32_16x16x32_bf16 v[26:29], v[102:105], v[210:213], v[26:29]
	v_mfma_f32_16x16x32_bf16 v[14:17], v[94:97], v[218:221], v[14:17]
	v_mfma_f32_16x16x32_bf16 v[10:13], v[102:105], v[218:221], v[10:13]
	s_setprio 0
	s_setprio 1
	v_mfma_f32_16x16x32_bf16 v[54:57], v[146:149], v[174:177], v[54:57]
	v_mfma_f32_16x16x32_bf16 v[50:53], v[166:169], v[174:177], v[50:53]
	v_mfma_f32_16x16x32_bf16 v[38:41], v[146:149], v[198:201], v[38:41]
	v_mfma_f32_16x16x32_bf16 v[34:37], v[166:169], v[198:201], v[34:37]
	v_mfma_f32_16x16x32_bf16 v[22:25], v[146:149], v[206:209], v[22:25]
	v_mfma_f32_16x16x32_bf16 v[18:21], v[166:169], v[206:209], v[18:21]
	v_mfma_f32_16x16x32_bf16 v[6:9], v[146:149], v[214:217], v[6:9]
	v_mfma_f32_16x16x32_bf16 v[2:5], v[166:169], v[214:217], v[2:5]
	v_mfma_f32_16x16x32_bf16 v[54:57], v[150:153], v[178:181], v[54:57]
	v_mfma_f32_16x16x32_bf16 v[50:53], v[170:173], v[178:181], v[50:53]
	v_mfma_f32_16x16x32_bf16 v[38:41], v[150:153], v[202:205], v[38:41]
	v_mfma_f32_16x16x32_bf16 v[34:37], v[170:173], v[202:205], v[34:37]
	v_mfma_f32_16x16x32_bf16 v[22:25], v[150:153], v[210:213], v[22:25]
	v_mfma_f32_16x16x32_bf16 v[18:21], v[170:173], v[210:213], v[18:21]
	v_mfma_f32_16x16x32_bf16 v[6:9], v[150:153], v[218:221], v[6:9]
	v_mfma_f32_16x16x32_bf16 v[2:5], v[170:173], v[218:221], v[2:5]
	s_setprio 0
	s_barrier
	s_add_i32 s64, 0, 0x18000
	s_add_i32 s65, 0, 0x1c000
	v_add_u32_e32 v102, s64, v185
	v_add_u32_e32 v170, s65, v185
	ds_read_b128 v[86:89], v102
	ds_read_b128 v[94:97], v102 offset:1024
	ds_read_b128 v[98:101], v102 offset:2048
	ds_read_b128 v[102:105], v102 offset:3072
	ds_read_b128 v[146:149], v170
	ds_read_b128 v[150:153], v170 offset:1024
	ds_read_b128 v[166:169], v170 offset:2048
	ds_read_b128 v[170:173], v170 offset:3072
	v_lshl_add_u64 v[224:225], s[42:43], 0, v[154:155]
	s_mov_b32 m0, s49
	s_nop 0
	global_load_lds_dwordx4 v[224:225], off
	s_mov_b32 m0, s50
	s_nop 0
	global_load_lds_dwordx4 v[226:227], off
	s_add_u32 s42, s42, 0x40000
	s_addc_u32 s43, s43, 0
	s_mov_b32 m0, s51
	v_lshl_add_u64 v[228:229], s[42:43], 0, v[154:155]
	ds_read_b128 v[174:177], v191 offset:32768
	ds_read_b128 v[178:181], v191 offset:33792
	ds_read_b128 v[198:201], v191 offset:34816
	ds_read_b128 v[202:205], v191 offset:35840
	ds_read_b128 v[206:209], v191 offset:36864
	ds_read_b128 v[210:213], v191 offset:37888
	ds_read_b128 v[214:217], v191 offset:38912
	ds_read_b128 v[218:221], v191 offset:39936
	global_load_lds_dwordx4 v[228:229], off
	v_lshl_add_u64 v[228:229], s[42:43], 0, v[156:157]
	s_mov_b32 m0, s52
	s_nop 0
	global_load_lds_dwordx4 v[228:229], off
	s_waitcnt vmcnt(8)
	s_waitcnt lgkmcnt(0)
	s_barrier
	s_setprio 1
	s_waitcnt lgkmcnt(0)
	v_mfma_f32_16x16x32_bf16 v[142:145], v[86:89], v[174:177], v[142:145]
	v_mfma_f32_16x16x32_bf16 v[138:141], v[98:101], v[174:177], v[138:141]
	v_mfma_f32_16x16x32_bf16 v[126:129], v[86:89], v[198:201], v[126:129]
	v_mfma_f32_16x16x32_bf16 v[122:125], v[98:101], v[198:201], v[122:125]
	v_mfma_f32_16x16x32_bf16 v[110:113], v[86:89], v[206:209], v[110:113]
	v_mfma_f32_16x16x32_bf16 v[106:109], v[98:101], v[206:209], v[106:109]
	v_mfma_f32_16x16x32_bf16 v[78:81], v[86:89], v[214:217], v[78:81]
	v_mfma_f32_16x16x32_bf16 v[74:77], v[98:101], v[214:217], v[74:77]
	v_mfma_f32_16x16x32_bf16 v[142:145], v[94:97], v[178:181], v[142:145]
	v_mfma_f32_16x16x32_bf16 v[138:141], v[102:105], v[178:181], v[138:141]
	v_mfma_f32_16x16x32_bf16 v[126:129], v[94:97], v[202:205], v[126:129]
	v_mfma_f32_16x16x32_bf16 v[122:125], v[102:105], v[202:205], v[122:125]
	v_mfma_f32_16x16x32_bf16 v[110:113], v[94:97], v[210:213], v[110:113]
	v_mfma_f32_16x16x32_bf16 v[106:109], v[102:105], v[210:213], v[106:109]
	v_mfma_f32_16x16x32_bf16 v[78:81], v[94:97], v[218:221], v[78:81]
	v_mfma_f32_16x16x32_bf16 v[74:77], v[102:105], v[218:221], v[74:77]
	s_setprio 0
	s_setprio 1
	v_mfma_f32_16x16x32_bf16 v[134:137], v[146:149], v[174:177], v[134:137]
	v_mfma_f32_16x16x32_bf16 v[130:133], v[166:169], v[174:177], v[130:133]
	v_mfma_f32_16x16x32_bf16 v[118:121], v[146:149], v[198:201], v[118:121]
	v_mfma_f32_16x16x32_bf16 v[114:117], v[166:169], v[198:201], v[114:117]
	v_mfma_f32_16x16x32_bf16 v[90:93], v[146:149], v[206:209], v[90:93]
	v_mfma_f32_16x16x32_bf16 v[82:85], v[166:169], v[206:209], v[82:85]
	v_mfma_f32_16x16x32_bf16 v[70:73], v[146:149], v[214:217], v[70:73]
	v_mfma_f32_16x16x32_bf16 v[66:69], v[166:169], v[214:217], v[66:69]
	v_mfma_f32_16x16x32_bf16 v[134:137], v[150:153], v[178:181], v[134:137]
	v_mfma_f32_16x16x32_bf16 v[130:133], v[170:173], v[178:181], v[130:133]
	v_mfma_f32_16x16x32_bf16 v[118:121], v[150:153], v[202:205], v[118:121]
	v_mfma_f32_16x16x32_bf16 v[114:117], v[170:173], v[202:205], v[114:117]
	v_mfma_f32_16x16x32_bf16 v[90:93], v[150:153], v[210:213], v[90:93]
	v_mfma_f32_16x16x32_bf16 v[82:85], v[170:173], v[210:213], v[82:85]
	v_mfma_f32_16x16x32_bf16 v[70:73], v[150:153], v[218:221], v[70:73]
	v_mfma_f32_16x16x32_bf16 v[66:69], v[170:173], v[218:221], v[66:69]
	s_setprio 0
	s_barrier
	s_add_i32 s42, s64, s48
	v_lshl_add_u64 v[182:183], v[182:183], 0, s[80:81]
	s_mov_b32 m0, s42
	ds_read_b128 v[174:177], v191 offset:49152
	ds_read_b128 v[178:181], v191 offset:50176
	ds_read_b128 v[198:201], v191 offset:51200
	ds_read_b128 v[202:205], v191 offset:52224
	ds_read_b128 v[206:209], v191 offset:53248
	ds_read_b128 v[210:213], v191 offset:54272
	ds_read_b128 v[214:217], v191 offset:55296
	ds_read_b128 v[218:221], v191 offset:56320
	global_load_lds_dwordx4 v[182:183], off
	s_add_i32 m0, s42, 0x2000
	s_add_u32 s40, s40, 0x40080
	v_lshl_add_u64 v[182:183], v[222:223], 0, s[80:81]
	s_addc_u32 s41, s41, 0
	s_add_i32 s42, s65, s48
	global_load_lds_dwordx4 v[182:183], off
	v_lshl_add_u64 v[182:183], s[40:41], 0, v[0:1]
	s_mov_b32 m0, s42
	s_nop 0
	global_load_lds_dwordx4 v[182:183], off
	v_lshl_add_u64 v[182:183], s[40:41], 0, v[158:159]
	s_add_i32 m0, s42, 0x2000
	s_nop 0
	global_load_lds_dwordx4 v[182:183], off
	v_lshl_add_u64 v[182:183], v[224:225], 0, s[80:81]
	s_mov_b32 m0, s55
	s_nop 0
	global_load_lds_dwordx4 v[182:183], off
	v_lshl_add_u64 v[182:183], v[226:227], 0, s[80:81]
	s_mov_b32 m0, s56
	s_nop 0
	global_load_lds_dwordx4 v[182:183], off
	s_waitcnt vmcnt(8)
	s_waitcnt lgkmcnt(0)
	s_barrier
	s_setprio 1
	s_waitcnt lgkmcnt(0)
	v_mfma_f32_16x16x32_bf16 v[62:65], v[86:89], v[174:177], v[62:65]
	v_mfma_f32_16x16x32_bf16 v[58:61], v[98:101], v[174:177], v[58:61]
	v_mfma_f32_16x16x32_bf16 v[46:49], v[86:89], v[198:201], v[46:49]
	v_mfma_f32_16x16x32_bf16 v[42:45], v[98:101], v[198:201], v[42:45]
	v_mfma_f32_16x16x32_bf16 v[30:33], v[86:89], v[206:209], v[30:33]
	v_mfma_f32_16x16x32_bf16 v[26:29], v[98:101], v[206:209], v[26:29]
	v_mfma_f32_16x16x32_bf16 v[14:17], v[86:89], v[214:217], v[14:17]
	v_mfma_f32_16x16x32_bf16 v[10:13], v[98:101], v[214:217], v[10:13]
	v_mfma_f32_16x16x32_bf16 v[62:65], v[94:97], v[178:181], v[62:65]
	v_mfma_f32_16x16x32_bf16 v[58:61], v[102:105], v[178:181], v[58:61]
	v_mfma_f32_16x16x32_bf16 v[46:49], v[94:97], v[202:205], v[46:49]
	v_mfma_f32_16x16x32_bf16 v[42:45], v[102:105], v[202:205], v[42:45]
	v_mfma_f32_16x16x32_bf16 v[30:33], v[94:97], v[210:213], v[30:33]
	v_mfma_f32_16x16x32_bf16 v[26:29], v[102:105], v[210:213], v[26:29]
	v_mfma_f32_16x16x32_bf16 v[14:17], v[94:97], v[218:221], v[14:17]
	v_mfma_f32_16x16x32_bf16 v[10:13], v[102:105], v[218:221], v[10:13]
	s_setprio 0
	s_setprio 1
	v_mfma_f32_16x16x32_bf16 v[54:57], v[146:149], v[174:177], v[54:57]
	v_mfma_f32_16x16x32_bf16 v[50:53], v[166:169], v[174:177], v[50:53]
	v_mfma_f32_16x16x32_bf16 v[38:41], v[146:149], v[198:201], v[38:41]
	v_mfma_f32_16x16x32_bf16 v[34:37], v[166:169], v[198:201], v[34:37]
	v_mfma_f32_16x16x32_bf16 v[22:25], v[146:149], v[206:209], v[22:25]
	v_mfma_f32_16x16x32_bf16 v[18:21], v[166:169], v[206:209], v[18:21]
	v_mfma_f32_16x16x32_bf16 v[6:9], v[146:149], v[214:217], v[6:9]
	v_mfma_f32_16x16x32_bf16 v[2:5], v[166:169], v[214:217], v[2:5]
	v_mfma_f32_16x16x32_bf16 v[54:57], v[150:153], v[178:181], v[54:57]
	v_mfma_f32_16x16x32_bf16 v[50:53], v[170:173], v[178:181], v[50:53]
	v_mfma_f32_16x16x32_bf16 v[38:41], v[150:153], v[202:205], v[38:41]
	v_mfma_f32_16x16x32_bf16 v[34:37], v[170:173], v[202:205], v[34:37]
	v_mfma_f32_16x16x32_bf16 v[22:25], v[150:153], v[210:213], v[22:25]
	v_mfma_f32_16x16x32_bf16 v[18:21], v[170:173], v[210:213], v[18:21]
	v_mfma_f32_16x16x32_bf16 v[6:9], v[150:153], v[218:221], v[6:9]
	v_mfma_f32_16x16x32_bf16 v[2:5], v[170:173], v[218:221], v[2:5]
	s_setprio 0
	s_barrier
	s_add_i32 s63, s63, 2
	s_add_u32 s38, s38, 0x100
	s_addc_u32 s39, s39, 0
	s_add_u32 s61, s61, 0x100
	s_addc_u32 s62, s62, 0
	s_cmp_gt_u32 s63, 13
	s_cbranch_scc0 .LBB0_2357
	s_and_b64 vcc, exec, s[14:15]
	s_cbranch_vccz .LBB0_2360
	s_barrier

.LBB0_2460:
	s_add_u32 s22, s20, 0xfffc0080
	s_addc_u32 s23, s21, -1
	s_add_i32 s45, 0, 0x10000
	s_cmp_eq_u32 s44, 12
	s_cselect_b32 s25, s7, s23
	s_cselect_b32 s24, s40, s22
	s_cselect_b32 s23, s9, s43
	s_cselect_b32 s22, s41, s42
	s_add_i32 s48, 0, 0x14000
	v_add_u32_e32 v156, s45, v141
	v_add_u32_e32 v172, s48, v141
	ds_read_b128 v[144:147], v156
	ds_read_b128 v[148:151], v156 offset:1024
	ds_read_b128 v[152:155], v156 offset:2048
	ds_read_b128 v[156:159], v156 offset:3072
	ds_read_b128 v[160:163], v172
	ds_read_b128 v[164:167], v172 offset:1024
	ds_read_b128 v[168:171], v172 offset:2048
	ds_read_b128 v[172:175], v172 offset:3072
	v_lshl_add_u64 v[208:209], s[20:21], 0, v[136:137]
	s_add_i32 m0, s33, 0xc000
	ds_read_b128 v[176:179], v143
	ds_read_b128 v[180:183], v143 offset:1024
	ds_read_b128 v[184:187], v143 offset:2048
	ds_read_b128 v[188:191], v143 offset:3072
	ds_read_b128 v[192:195], v143 offset:4096
	ds_read_b128 v[196:199], v143 offset:5120
	ds_read_b128 v[200:203], v143 offset:6144
	ds_read_b128 v[204:207], v143 offset:7168
	global_load_lds_dwordx4 v[208:209], off
	v_lshl_add_u64 v[208:209], s[20:21], 0, v[138:139]
	s_add_i32 m0, s33, 0xe000
	s_nop 0
	global_load_lds_dwordx4 v[208:209], off
	s_waitcnt vmcnt(8)
	s_waitcnt lgkmcnt(0)
	s_barrier
	s_setprio 1
	s_waitcnt lgkmcnt(0)
	v_mfma_f32_16x16x32_bf16 v[126:129], v[144:147], v[176:179], v[126:129]
	v_mfma_f32_16x16x32_bf16 v[118:121], v[152:155], v[176:179], v[118:121]
	v_mfma_f32_16x16x32_bf16 v[110:113], v[144:147], v[184:187], v[110:113]
	v_mfma_f32_16x16x32_bf16 v[102:105], v[152:155], v[184:187], v[102:105]
	v_mfma_f32_16x16x32_bf16 v[94:97], v[144:147], v[192:195], v[94:97]
	v_mfma_f32_16x16x32_bf16 v[86:89], v[152:155], v[192:195], v[86:89]
	v_mfma_f32_16x16x32_bf16 v[78:81], v[144:147], v[200:203], v[78:81]
	v_mfma_f32_16x16x32_bf16 v[70:73], v[152:155], v[200:203], v[70:73]
	v_mfma_f32_16x16x32_bf16 v[126:129], v[148:151], v[180:183], v[126:129]
	v_mfma_f32_16x16x32_bf16 v[118:121], v[156:159], v[180:183], v[118:121]
	v_mfma_f32_16x16x32_bf16 v[110:113], v[148:151], v[188:191], v[110:113]
	v_mfma_f32_16x16x32_bf16 v[102:105], v[156:159], v[188:191], v[102:105]
	v_mfma_f32_16x16x32_bf16 v[94:97], v[148:151], v[196:199], v[94:97]
	v_mfma_f32_16x16x32_bf16 v[86:89], v[156:159], v[196:199], v[86:89]
	v_mfma_f32_16x16x32_bf16 v[78:81], v[148:151], v[204:207], v[78:81]
	v_mfma_f32_16x16x32_bf16 v[70:73], v[156:159], v[204:207], v[70:73]
	s_setprio 0
	s_setprio 1
	v_mfma_f32_16x16x32_bf16 v[122:125], v[160:163], v[176:179], v[122:125]
	v_mfma_f32_16x16x32_bf16 v[114:117], v[168:171], v[176:179], v[114:117]
	v_mfma_f32_16x16x32_bf16 v[106:109], v[160:163], v[184:187], v[106:109]
	v_mfma_f32_16x16x32_bf16 v[98:101], v[168:171], v[184:187], v[98:101]
	v_mfma_f32_16x16x32_bf16 v[90:93], v[160:163], v[192:195], v[90:93]
	v_mfma_f32_16x16x32_bf16 v[82:85], v[168:171], v[192:195], v[82:85]
	v_mfma_f32_16x16x32_bf16 v[74:77], v[160:163], v[200:203], v[74:77]
	v_mfma_f32_16x16x32_bf16 v[66:69], v[168:171], v[200:203], v[66:69]
	v_mfma_f32_16x16x32_bf16 v[122:125], v[164:167], v[180:183], v[122:125]
	v_mfma_f32_16x16x32_bf16 v[114:117], v[172:175], v[180:183], v[114:117]
	v_mfma_f32_16x16x32_bf16 v[106:109], v[164:167], v[188:191], v[106:109]
	v_mfma_f32_16x16x32_bf16 v[98:101], v[172:175], v[188:191], v[98:101]
	v_mfma_f32_16x16x32_bf16 v[90:93], v[164:167], v[196:199], v[90:93]
	v_mfma_f32_16x16x32_bf16 v[82:85], v[172:175], v[196:199], v[82:85]
	v_mfma_f32_16x16x32_bf16 v[74:77], v[164:167], v[204:207], v[74:77]
	v_mfma_f32_16x16x32_bf16 v[66:69], v[172:175], v[204:207], v[66:69]
	s_setprio 0
	s_barrier
	s_add_i32 s45, s45, s31
	v_lshl_add_u64 v[208:209], s[22:23], 0, v[0:1]
	s_mov_b32 m0, s45
	ds_read_b128 v[176:179], v143 offset:16384
	ds_read_b128 v[180:183], v143 offset:17408
	ds_read_b128 v[184:187], v143 offset:18432
	ds_read_b128 v[188:191], v143 offset:19456
	ds_read_b128 v[192:195], v143 offset:20480
	ds_read_b128 v[196:199], v143 offset:21504
	ds_read_b128 v[200:203], v143 offset:22528
	ds_read_b128 v[204:207], v143 offset:23552
	global_load_lds_dwordx4 v[208:209], off
	s_add_i32 m0, s45, 0x2000
	s_add_u32 s46, s22, 0x40000
	v_lshl_add_u64 v[210:211], s[22:23], 0, v[130:131]
	s_addc_u32 s47, s23, 0
	s_add_i32 s45, s48, s31
	global_load_lds_dwordx4 v[210:211], off
	v_lshl_add_u64 v[212:213], s[46:47], 0, v[0:1]
	s_mov_b32 m0, s45
	v_lshl_add_u64 v[214:215], s[24:25], 0, v[132:133]
	global_load_lds_dwordx4 v[212:213], off
	v_lshl_add_u64 v[212:213], s[46:47], 0, v[130:131]
	s_add_i32 m0, s45, 0x2000
	s_nop 0
	global_load_lds_dwordx4 v[212:213], off
	s_waitcnt vmcnt(6)
	s_waitcnt lgkmcnt(0)
	s_barrier
	s_setprio 1
	s_waitcnt lgkmcnt(0)
	v_mfma_f32_16x16x32_bf16 v[62:65], v[144:147], v[176:179], v[62:65]
	v_mfma_f32_16x16x32_bf16 v[54:57], v[152:155], v[176:179], v[54:57]
	v_mfma_f32_16x16x32_bf16 v[46:49], v[144:147], v[184:187], v[46:49]
	v_mfma_f32_16x16x32_bf16 v[38:41], v[152:155], v[184:187], v[38:41]
	v_mfma_f32_16x16x32_bf16 v[30:33], v[144:147], v[192:195], v[30:33]
	v_mfma_f32_16x16x32_bf16 v[22:25], v[152:155], v[192:195], v[22:25]
	v_mfma_f32_16x16x32_bf16 v[14:17], v[144:147], v[200:203], v[14:17]
	v_mfma_f32_16x16x32_bf16 v[6:9], v[152:155], v[200:203], v[6:9]
	v_mfma_f32_16x16x32_bf16 v[62:65], v[148:151], v[180:183], v[62:65]
	v_mfma_f32_16x16x32_bf16 v[54:57], v[156:159], v[180:183], v[54:57]
	v_mfma_f32_16x16x32_bf16 v[46:49], v[148:151], v[188:191], v[46:49]
	v_mfma_f32_16x16x32_bf16 v[38:41], v[156:159], v[188:191], v[38:41]
	v_mfma_f32_16x16x32_bf16 v[30:33], v[148:151], v[196:199], v[30:33]
	v_mfma_f32_16x16x32_bf16 v[22:25], v[156:159], v[196:199], v[22:25]
	v_mfma_f32_16x16x32_bf16 v[14:17], v[148:151], v[204:207], v[14:17]
	v_mfma_f32_16x16x32_bf16 v[6:9], v[156:159], v[204:207], v[6:9]
	s_setprio 0
	s_setprio 1
	v_mfma_f32_16x16x32_bf16 v[58:61], v[160:163], v[176:179], v[58:61]
	v_mfma_f32_16x16x32_bf16 v[50:53], v[168:171], v[176:179], v[50:53]
	v_mfma_f32_16x16x32_bf16 v[42:45], v[160:163], v[184:187], v[42:45]
	v_mfma_f32_16x16x32_bf16 v[34:37], v[168:171], v[184:187], v[34:37]
	v_mfma_f32_16x16x32_bf16 v[26:29], v[160:163], v[192:195], v[26:29]
	v_mfma_f32_16x16x32_bf16 v[18:21], v[168:171], v[192:195], v[18:21]
	v_mfma_f32_16x16x32_bf16 v[10:13], v[160:163], v[200:203], v[10:13]
	v_mfma_f32_16x16x32_bf16 v[2:5], v[168:171], v[200:203], v[2:5]
	v_mfma_f32_16x16x32_bf16 v[58:61], v[164:167], v[180:183], v[58:61]
	v_mfma_f32_16x16x32_bf16 v[50:53], v[172:175], v[180:183], v[50:53]
	v_mfma_f32_16x16x32_bf16 v[42:45], v[164:167], v[188:191], v[42:45]
	v_mfma_f32_16x16x32_bf16 v[34:37], v[172:175], v[188:191], v[34:37]
	v_mfma_f32_16x16x32_bf16 v[26:29], v[164:167], v[196:199], v[26:29]
	v_mfma_f32_16x16x32_bf16 v[18:21], v[172:175], v[196:199], v[18:21]
	v_mfma_f32_16x16x32_bf16 v[10:13], v[164:167], v[204:207], v[10:13]
	v_mfma_f32_16x16x32_bf16 v[2:5], v[172:175], v[204:207], v[2:5]
	s_setprio 0
	s_barrier
	s_add_i32 s45, 0, 0x18000
	s_add_i32 s46, 0, 0x1c000
	v_add_u32_e32 v156, s45, v141
	v_add_u32_e32 v172, s46, v141
	ds_read_b128 v[144:147], v156
	ds_read_b128 v[148:151], v156 offset:1024
	ds_read_b128 v[152:155], v156 offset:2048
	ds_read_b128 v[156:159], v156 offset:3072
	ds_read_b128 v[160:163], v172
	ds_read_b128 v[164:167], v172 offset:1024
	ds_read_b128 v[168:171], v172 offset:2048
	ds_read_b128 v[172:175], v172 offset:3072
	v_lshl_add_u64 v[212:213], s[24:25], 0, v[134:135]
	s_mov_b32 m0, s33
	s_nop 0
	global_load_lds_dwordx4 v[212:213], off
	s_mov_b32 m0, s34
	s_nop 0
	global_load_lds_dwordx4 v[214:215], off
	s_add_u32 s24, s24, 0x40000
	s_addc_u32 s25, s25, 0
	s_mov_b32 m0, s35
	v_lshl_add_u64 v[216:217], s[24:25], 0, v[134:135]
	ds_read_b128 v[176:179], v143 offset:32768
	ds_read_b128 v[180:183], v143 offset:33792
	ds_read_b128 v[184:187], v143 offset:34816
	ds_read_b128 v[188:191], v143 offset:35840
	ds_read_b128 v[192:195], v143 offset:36864
	ds_read_b128 v[196:199], v143 offset:37888
	ds_read_b128 v[200:203], v143 offset:38912
	ds_read_b128 v[204:207], v143 offset:39936
	global_load_lds_dwordx4 v[216:217], off
	v_lshl_add_u64 v[216:217], s[24:25], 0, v[132:133]
	s_mov_b32 m0, s36
	s_nop 0
	global_load_lds_dwordx4 v[216:217], off
	s_waitcnt vmcnt(8)
	s_waitcnt lgkmcnt(0)
	s_barrier
	s_setprio 1
	s_waitcnt lgkmcnt(0)
	v_mfma_f32_16x16x32_bf16 v[126:129], v[144:147], v[176:179], v[126:129]
	v_mfma_f32_16x16x32_bf16 v[118:121], v[152:155], v[176:179], v[118:121]
	v_mfma_f32_16x16x32_bf16 v[110:113], v[144:147], v[184:187], v[110:113]
	v_mfma_f32_16x16x32_bf16 v[102:105], v[152:155], v[184:187], v[102:105]
	v_mfma_f32_16x16x32_bf16 v[94:97], v[144:147], v[192:195], v[94:97]
	v_mfma_f32_16x16x32_bf16 v[86:89], v[152:155], v[192:195], v[86:89]
	v_mfma_f32_16x16x32_bf16 v[78:81], v[144:147], v[200:203], v[78:81]
	v_mfma_f32_16x16x32_bf16 v[70:73], v[152:155], v[200:203], v[70:73]
	v_mfma_f32_16x16x32_bf16 v[126:129], v[148:151], v[180:183], v[126:129]
	v_mfma_f32_16x16x32_bf16 v[118:121], v[156:159], v[180:183], v[118:121]
	v_mfma_f32_16x16x32_bf16 v[110:113], v[148:151], v[188:191], v[110:113]
	v_mfma_f32_16x16x32_bf16 v[102:105], v[156:159], v[188:191], v[102:105]
	v_mfma_f32_16x16x32_bf16 v[94:97], v[148:151], v[196:199], v[94:97]
	v_mfma_f32_16x16x32_bf16 v[86:89], v[156:159], v[196:199], v[86:89]
	v_mfma_f32_16x16x32_bf16 v[78:81], v[148:151], v[204:207], v[78:81]
	v_mfma_f32_16x16x32_bf16 v[70:73], v[156:159], v[204:207], v[70:73]
	s_setprio 0
	s_setprio 1
	v_mfma_f32_16x16x32_bf16 v[122:125], v[160:163], v[176:179], v[122:125]
	v_mfma_f32_16x16x32_bf16 v[114:117], v[168:171], v[176:179], v[114:117]
	v_mfma_f32_16x16x32_bf16 v[106:109], v[160:163], v[184:187], v[106:109]
	v_mfma_f32_16x16x32_bf16 v[98:101], v[168:171], v[184:187], v[98:101]
	v_mfma_f32_16x16x32_bf16 v[90:93], v[160:163], v[192:195], v[90:93]
	v_mfma_f32_16x16x32_bf16 v[82:85], v[168:171], v[192:195], v[82:85]
	v_mfma_f32_16x16x32_bf16 v[74:77], v[160:163], v[200:203], v[74:77]
	v_mfma_f32_16x16x32_bf16 v[66:69], v[168:171], v[200:203], v[66:69]
	v_mfma_f32_16x16x32_bf16 v[122:125], v[164:167], v[180:183], v[122:125]
	v_mfma_f32_16x16x32_bf16 v[114:117], v[172:175], v[180:183], v[114:117]
	v_mfma_f32_16x16x32_bf16 v[106:109], v[164:167], v[188:191], v[106:109]
	v_mfma_f32_16x16x32_bf16 v[98:101], v[172:175], v[188:191], v[98:101]
	v_mfma_f32_16x16x32_bf16 v[90:93], v[164:167], v[196:199], v[90:93]
	v_mfma_f32_16x16x32_bf16 v[82:85], v[172:175], v[196:199], v[82:85]
	v_mfma_f32_16x16x32_bf16 v[74:77], v[164:167], v[204:207], v[74:77]
	v_mfma_f32_16x16x32_bf16 v[66:69], v[172:175], v[204:207], v[66:69]
	s_setprio 0
	s_barrier
	s_add_i32 s24, s45, s31
	v_lshl_add_u64 v[208:209], v[208:209], 0, s[80:81]
	s_mov_b32 m0, s24
	ds_read_b128 v[176:179], v143 offset:49152
	ds_read_b128 v[180:183], v143 offset:50176
	ds_read_b128 v[184:187], v143 offset:51200
	ds_read_b128 v[188:191], v143 offset:52224
	ds_read_b128 v[192:195], v143 offset:53248
	ds_read_b128 v[196:199], v143 offset:54272
	ds_read_b128 v[200:203], v143 offset:55296
	ds_read_b128 v[204:207], v143 offset:56320
	global_load_lds_dwordx4 v[208:209], off
	s_add_i32 m0, s24, 0x2000
	s_add_u32 s22, s22, 0x40080
	v_lshl_add_u64 v[208:209], v[210:211], 0, s[80:81]
	s_addc_u32 s23, s23, 0
	s_add_i32 s24, s46, s31
	global_load_lds_dwordx4 v[208:209], off
	v_lshl_add_u64 v[208:209], s[22:23], 0, v[0:1]
	s_mov_b32 m0, s24
	s_nop 0
	global_load_lds_dwordx4 v[208:209], off
	v_lshl_add_u64 v[208:209], s[22:23], 0, v[130:131]
	s_add_i32 m0, s24, 0x2000
	s_nop 0
	global_load_lds_dwordx4 v[208:209], off
	v_lshl_add_u64 v[208:209], v[212:213], 0, s[80:81]
	s_mov_b32 m0, s37
	s_nop 0
	global_load_lds_dwordx4 v[208:209], off
	v_lshl_add_u64 v[208:209], v[214:215], 0, s[80:81]
	s_mov_b32 m0, s38
	s_nop 0
	global_load_lds_dwordx4 v[208:209], off
	s_waitcnt vmcnt(8)
	s_waitcnt lgkmcnt(0)
	s_barrier
	s_setprio 1
	s_waitcnt lgkmcnt(0)
	v_mfma_f32_16x16x32_bf16 v[62:65], v[144:147], v[176:179], v[62:65]
	v_mfma_f32_16x16x32_bf16 v[54:57], v[152:155], v[176:179], v[54:57]
	v_mfma_f32_16x16x32_bf16 v[46:49], v[144:147], v[184:187], v[46:49]
	v_mfma_f32_16x16x32_bf16 v[38:41], v[152:155], v[184:187], v[38:41]
	v_mfma_f32_16x16x32_bf16 v[30:33], v[144:147], v[192:195], v[30:33]
	v_mfma_f32_16x16x32_bf16 v[22:25], v[152:155], v[192:195], v[22:25]
	v_mfma_f32_16x16x32_bf16 v[14:17], v[144:147], v[200:203], v[14:17]
	v_mfma_f32_16x16x32_bf16 v[6:9], v[152:155], v[200:203], v[6:9]
	v_mfma_f32_16x16x32_bf16 v[62:65], v[148:151], v[180:183], v[62:65]
	v_mfma_f32_16x16x32_bf16 v[54:57], v[156:159], v[180:183], v[54:57]
	v_mfma_f32_16x16x32_bf16 v[46:49], v[148:151], v[188:191], v[46:49]
	v_mfma_f32_16x16x32_bf16 v[38:41], v[156:159], v[188:191], v[38:41]
	v_mfma_f32_16x16x32_bf16 v[30:33], v[148:151], v[196:199], v[30:33]
	v_mfma_f32_16x16x32_bf16 v[22:25], v[156:159], v[196:199], v[22:25]
	v_mfma_f32_16x16x32_bf16 v[14:17], v[148:151], v[204:207], v[14:17]
	v_mfma_f32_16x16x32_bf16 v[6:9], v[156:159], v[204:207], v[6:9]
	s_setprio 0
	s_setprio 1
	v_mfma_f32_16x16x32_bf16 v[58:61], v[160:163], v[176:179], v[58:61]
	v_mfma_f32_16x16x32_bf16 v[50:53], v[168:171], v[176:179], v[50:53]
	v_mfma_f32_16x16x32_bf16 v[42:45], v[160:163], v[184:187], v[42:45]
	v_mfma_f32_16x16x32_bf16 v[34:37], v[168:171], v[184:187], v[34:37]
	v_mfma_f32_16x16x32_bf16 v[26:29], v[160:163], v[192:195], v[26:29]
	v_mfma_f32_16x16x32_bf16 v[18:21], v[168:171], v[192:195], v[18:21]
	v_mfma_f32_16x16x32_bf16 v[10:13], v[160:163], v[200:203], v[10:13]
	v_mfma_f32_16x16x32_bf16 v[2:5], v[168:171], v[200:203], v[2:5]
	v_mfma_f32_16x16x32_bf16 v[58:61], v[164:167], v[180:183], v[58:61]
	v_mfma_f32_16x16x32_bf16 v[50:53], v[172:175], v[180:183], v[50:53]
	v_mfma_f32_16x16x32_bf16 v[42:45], v[164:167], v[188:191], v[42:45]
	v_mfma_f32_16x16x32_bf16 v[34:37], v[172:175], v[188:191], v[34:37]
	v_mfma_f32_16x16x32_bf16 v[26:29], v[164:167], v[196:199], v[26:29]
	v_mfma_f32_16x16x32_bf16 v[18:21], v[172:175], v[196:199], v[18:21]
	v_mfma_f32_16x16x32_bf16 v[10:13], v[164:167], v[204:207], v[10:13]
	v_mfma_f32_16x16x32_bf16 v[2:5], v[172:175], v[204:207], v[2:5]
	s_setprio 0
	s_barrier
	s_add_i32 s44, s44, 2
	s_add_u32 s20, s20, 0x100
	s_addc_u32 s21, s21, 0
	s_add_u32 s42, s42, 0x100
	s_addc_u32 s43, s43, 0
	s_cmp_gt_u32 s44, 13
	s_cbranch_scc0 .LBB0_2460
	s_and_b64 vcc, exec, s[4:5]
	s_cbranch_vccz .LBB0_2463
	s_barrier

.LBB0_2545:
	s_add_u32 s34, s30, 0x100
	s_addc_u32 s35, s31, 0
	s_add_i32 s65, 0, 0x10000
	s_cmp_eq_u32 s64, 40
	s_cselect_b32 s39, s27, s35
	s_cselect_b32 s38, s26, s34
	s_cselect_b32 s37, s29, s63
	s_cselect_b32 s36, s28, s1
	s_add_i32 s66, 0, 0x14000
	v_add_u32_e32 v154, s65, v185
	v_add_u32_e32 v170, s66, v185
	ds_read_b128 v[130:133], v154
	ds_read_b128 v[134:137], v154 offset:1024
	ds_read_b128 v[150:153], v154 offset:2048
	ds_read_b128 v[154:157], v154 offset:3072
	ds_read_b128 v[158:161], v170
	ds_read_b128 v[162:165], v170 offset:1024
	ds_read_b128 v[166:169], v170 offset:2048
	ds_read_b128 v[170:173], v170 offset:3072
	v_lshl_add_u64 v[182:183], s[30:31], 0, v[146:147]
	s_add_i32 m0, s46, 0xc000
	ds_read_b128 v[174:177], v191
	ds_read_b128 v[178:181], v191 offset:1024
	ds_read_b128 v[198:201], v191 offset:2048
	ds_read_b128 v[202:205], v191 offset:3072
	ds_read_b128 v[206:209], v191 offset:4096
	ds_read_b128 v[210:213], v191 offset:5120
	ds_read_b128 v[214:217], v191 offset:6144
	ds_read_b128 v[218:221], v191 offset:7168
	global_load_lds_dwordx4 v[182:183], off
	v_lshl_add_u64 v[182:183], s[30:31], 0, v[148:149]
	s_add_i32 m0, s46, 0xe000
	s_nop 0
	global_load_lds_dwordx4 v[182:183], off
	s_waitcnt vmcnt(8)
	s_waitcnt lgkmcnt(0)
	s_barrier
	s_setprio 1
	s_waitcnt lgkmcnt(0)
	v_mfma_f32_16x16x32_bf16 v[126:129], v[130:133], v[174:177], v[126:129]
	v_mfma_f32_16x16x32_bf16 v[122:125], v[150:153], v[174:177], v[122:125]
	v_mfma_f32_16x16x32_bf16 v[110:113], v[130:133], v[198:201], v[110:113]
	v_mfma_f32_16x16x32_bf16 v[106:109], v[150:153], v[198:201], v[106:109]
	v_mfma_f32_16x16x32_bf16 v[94:97], v[130:133], v[206:209], v[94:97]
	v_mfma_f32_16x16x32_bf16 v[90:93], v[150:153], v[206:209], v[90:93]
	v_mfma_f32_16x16x32_bf16 v[78:81], v[130:133], v[214:217], v[78:81]
	v_mfma_f32_16x16x32_bf16 v[74:77], v[150:153], v[214:217], v[74:77]
	v_mfma_f32_16x16x32_bf16 v[126:129], v[134:137], v[178:181], v[126:129]
	v_mfma_f32_16x16x32_bf16 v[122:125], v[154:157], v[178:181], v[122:125]
	v_mfma_f32_16x16x32_bf16 v[110:113], v[134:137], v[202:205], v[110:113]
	v_mfma_f32_16x16x32_bf16 v[106:109], v[154:157], v[202:205], v[106:109]
	v_mfma_f32_16x16x32_bf16 v[94:97], v[134:137], v[210:213], v[94:97]
	v_mfma_f32_16x16x32_bf16 v[90:93], v[154:157], v[210:213], v[90:93]
	v_mfma_f32_16x16x32_bf16 v[78:81], v[134:137], v[218:221], v[78:81]
	v_mfma_f32_16x16x32_bf16 v[74:77], v[154:157], v[218:221], v[74:77]
	s_setprio 0
	s_setprio 1
	v_mfma_f32_16x16x32_bf16 v[118:121], v[158:161], v[174:177], v[118:121]
	v_mfma_f32_16x16x32_bf16 v[114:117], v[166:169], v[174:177], v[114:117]
	v_mfma_f32_16x16x32_bf16 v[102:105], v[158:161], v[198:201], v[102:105]
	v_mfma_f32_16x16x32_bf16 v[98:101], v[166:169], v[198:201], v[98:101]
	v_mfma_f32_16x16x32_bf16 v[86:89], v[158:161], v[206:209], v[86:89]
	v_mfma_f32_16x16x32_bf16 v[82:85], v[166:169], v[206:209], v[82:85]
	v_mfma_f32_16x16x32_bf16 v[70:73], v[158:161], v[214:217], v[70:73]
	v_mfma_f32_16x16x32_bf16 v[66:69], v[166:169], v[214:217], v[66:69]
	v_mfma_f32_16x16x32_bf16 v[118:121], v[162:165], v[178:181], v[118:121]
	v_mfma_f32_16x16x32_bf16 v[114:117], v[170:173], v[178:181], v[114:117]
	v_mfma_f32_16x16x32_bf16 v[102:105], v[162:165], v[202:205], v[102:105]
	v_mfma_f32_16x16x32_bf16 v[98:101], v[170:173], v[202:205], v[98:101]
	v_mfma_f32_16x16x32_bf16 v[86:89], v[162:165], v[210:213], v[86:89]
	v_mfma_f32_16x16x32_bf16 v[82:85], v[170:173], v[210:213], v[82:85]
	v_mfma_f32_16x16x32_bf16 v[70:73], v[162:165], v[218:221], v[70:73]
	v_mfma_f32_16x16x32_bf16 v[66:69], v[170:173], v[218:221], v[66:69]
	s_setprio 0
	s_barrier
	s_add_i32 s30, s65, s33
	v_lshl_add_u64 v[182:183], s[36:37], 0, v[0:1]
	s_mov_b32 m0, s30
	ds_read_b128 v[174:177], v191 offset:16384
	ds_read_b128 v[178:181], v191 offset:17408
	ds_read_b128 v[198:201], v191 offset:18432
	ds_read_b128 v[202:205], v191 offset:19456
	ds_read_b128 v[206:209], v191 offset:20480
	ds_read_b128 v[210:213], v191 offset:21504
	ds_read_b128 v[214:217], v191 offset:22528
	ds_read_b128 v[218:221], v191 offset:23552
	global_load_lds_dwordx4 v[182:183], off
	s_add_i32 m0, s30, 0x2000
	s_add_u32 s30, s36, 0xb0000
	v_lshl_add_u64 v[222:223], s[36:37], 0, v[142:143]
	s_addc_u32 s31, s37, 0
	s_add_i32 s65, s66, s33
	global_load_lds_dwordx4 v[222:223], off
	v_lshl_add_u64 v[224:225], s[30:31], 0, v[0:1]
	s_mov_b32 m0, s65
	v_lshl_add_u64 v[226:227], s[38:39], 0, v[140:141]
	global_load_lds_dwordx4 v[224:225], off
	v_lshl_add_u64 v[224:225], s[30:31], 0, v[142:143]
	s_add_i32 m0, s65, 0x2000
	s_nop 0
	global_load_lds_dwordx4 v[224:225], off
	s_waitcnt vmcnt(6)
	s_waitcnt lgkmcnt(0)
	s_barrier
	s_setprio 1
	s_waitcnt lgkmcnt(0)
	v_mfma_f32_16x16x32_bf16 v[62:65], v[130:133], v[174:177], v[62:65]
	v_mfma_f32_16x16x32_bf16 v[58:61], v[150:153], v[174:177], v[58:61]
	v_mfma_f32_16x16x32_bf16 v[46:49], v[130:133], v[198:201], v[46:49]
	v_mfma_f32_16x16x32_bf16 v[42:45], v[150:153], v[198:201], v[42:45]
	v_mfma_f32_16x16x32_bf16 v[30:33], v[130:133], v[206:209], v[30:33]
	v_mfma_f32_16x16x32_bf16 v[26:29], v[150:153], v[206:209], v[26:29]
	v_mfma_f32_16x16x32_bf16 v[14:17], v[130:133], v[214:217], v[14:17]
	v_mfma_f32_16x16x32_bf16 v[10:13], v[150:153], v[214:217], v[10:13]
	v_mfma_f32_16x16x32_bf16 v[62:65], v[134:137], v[178:181], v[62:65]
	v_mfma_f32_16x16x32_bf16 v[58:61], v[154:157], v[178:181], v[58:61]
	v_mfma_f32_16x16x32_bf16 v[46:49], v[134:137], v[202:205], v[46:49]
	v_mfma_f32_16x16x32_bf16 v[42:45], v[154:157], v[202:205], v[42:45]
	v_mfma_f32_16x16x32_bf16 v[30:33], v[134:137], v[210:213], v[30:33]
	v_mfma_f32_16x16x32_bf16 v[26:29], v[154:157], v[210:213], v[26:29]
	v_mfma_f32_16x16x32_bf16 v[14:17], v[134:137], v[218:221], v[14:17]
	v_mfma_f32_16x16x32_bf16 v[10:13], v[154:157], v[218:221], v[10:13]
	s_setprio 0
	s_setprio 1
	v_mfma_f32_16x16x32_bf16 v[54:57], v[158:161], v[174:177], v[54:57]
	v_mfma_f32_16x16x32_bf16 v[50:53], v[166:169], v[174:177], v[50:53]
	v_mfma_f32_16x16x32_bf16 v[38:41], v[158:161], v[198:201], v[38:41]
	v_mfma_f32_16x16x32_bf16 v[34:37], v[166:169], v[198:201], v[34:37]
	v_mfma_f32_16x16x32_bf16 v[22:25], v[158:161], v[206:209], v[22:25]
	v_mfma_f32_16x16x32_bf16 v[18:21], v[166:169], v[206:209], v[18:21]
	v_mfma_f32_16x16x32_bf16 v[6:9], v[158:161], v[214:217], v[6:9]
	v_mfma_f32_16x16x32_bf16 v[2:5], v[166:169], v[214:217], v[2:5]
	v_mfma_f32_16x16x32_bf16 v[54:57], v[162:165], v[178:181], v[54:57]
	v_mfma_f32_16x16x32_bf16 v[50:53], v[170:173], v[178:181], v[50:53]
	v_mfma_f32_16x16x32_bf16 v[38:41], v[162:165], v[202:205], v[38:41]
	v_mfma_f32_16x16x32_bf16 v[34:37], v[170:173], v[202:205], v[34:37]
	v_mfma_f32_16x16x32_bf16 v[22:25], v[162:165], v[210:213], v[22:25]
	v_mfma_f32_16x16x32_bf16 v[18:21], v[170:173], v[210:213], v[18:21]
	v_mfma_f32_16x16x32_bf16 v[6:9], v[162:165], v[218:221], v[6:9]
	v_mfma_f32_16x16x32_bf16 v[2:5], v[170:173], v[218:221], v[2:5]
	s_setprio 0
	s_barrier
	s_add_i32 s65, 0, 0x18000
	s_add_i32 s66, 0, 0x1c000
	v_add_u32_e32 v154, s65, v185
	v_add_u32_e32 v170, s66, v185
	ds_read_b128 v[130:133], v154
	ds_read_b128 v[134:137], v154 offset:1024
	ds_read_b128 v[150:153], v154 offset:2048
	ds_read_b128 v[154:157], v154 offset:3072
	ds_read_b128 v[158:161], v170
	ds_read_b128 v[162:165], v170 offset:1024
	ds_read_b128 v[166:169], v170 offset:2048
	ds_read_b128 v[170:173], v170 offset:3072
	s_add_u32 s30, s38, 0xb0000
	s_addc_u32 s31, s39, 0
	v_lshl_add_u64 v[224:225], s[38:39], 0, v[138:139]
	s_mov_b32 m0, s46
	s_nop 0
	global_load_lds_dwordx4 v[224:225], off
	s_mov_b32 m0, s47
	s_nop 0
	global_load_lds_dwordx4 v[226:227], off
	s_mov_b32 m0, s48
	v_lshl_add_u64 v[228:229], s[30:31], 0, v[138:139]
	ds_read_b128 v[174:177], v191 offset:32768
	ds_read_b128 v[178:181], v191 offset:33792
	ds_read_b128 v[198:201], v191 offset:34816
	ds_read_b128 v[202:205], v191 offset:35840
	ds_read_b128 v[206:209], v191 offset:36864
	ds_read_b128 v[210:213], v191 offset:37888
	ds_read_b128 v[214:217], v191 offset:38912
	ds_read_b128 v[218:221], v191 offset:39936
	global_load_lds_dwordx4 v[228:229], off
	v_lshl_add_u64 v[228:229], s[30:31], 0, v[140:141]
	s_mov_b32 m0, s49
	s_nop 0
	global_load_lds_dwordx4 v[228:229], off
	s_waitcnt vmcnt(8)
	s_waitcnt lgkmcnt(0)
	s_barrier
	s_setprio 1
	s_waitcnt lgkmcnt(0)
	v_mfma_f32_16x16x32_bf16 v[126:129], v[130:133], v[174:177], v[126:129]
	v_mfma_f32_16x16x32_bf16 v[122:125], v[150:153], v[174:177], v[122:125]
	v_mfma_f32_16x16x32_bf16 v[110:113], v[130:133], v[198:201], v[110:113]
	v_mfma_f32_16x16x32_bf16 v[106:109], v[150:153], v[198:201], v[106:109]
	v_mfma_f32_16x16x32_bf16 v[94:97], v[130:133], v[206:209], v[94:97]
	v_mfma_f32_16x16x32_bf16 v[90:93], v[150:153], v[206:209], v[90:93]
	v_mfma_f32_16x16x32_bf16 v[78:81], v[130:133], v[214:217], v[78:81]
	v_mfma_f32_16x16x32_bf16 v[74:77], v[150:153], v[214:217], v[74:77]
	v_mfma_f32_16x16x32_bf16 v[126:129], v[134:137], v[178:181], v[126:129]
	v_mfma_f32_16x16x32_bf16 v[122:125], v[154:157], v[178:181], v[122:125]
	v_mfma_f32_16x16x32_bf16 v[110:113], v[134:137], v[202:205], v[110:113]
	v_mfma_f32_16x16x32_bf16 v[106:109], v[154:157], v[202:205], v[106:109]
	v_mfma_f32_16x16x32_bf16 v[94:97], v[134:137], v[210:213], v[94:97]
	v_mfma_f32_16x16x32_bf16 v[90:93], v[154:157], v[210:213], v[90:93]
	v_mfma_f32_16x16x32_bf16 v[78:81], v[134:137], v[218:221], v[78:81]
	v_mfma_f32_16x16x32_bf16 v[74:77], v[154:157], v[218:221], v[74:77]
	s_setprio 0
	s_setprio 1
	v_mfma_f32_16x16x32_bf16 v[118:121], v[158:161], v[174:177], v[118:121]
	v_mfma_f32_16x16x32_bf16 v[114:117], v[166:169], v[174:177], v[114:117]
	v_mfma_f32_16x16x32_bf16 v[102:105], v[158:161], v[198:201], v[102:105]
	v_mfma_f32_16x16x32_bf16 v[98:101], v[166:169], v[198:201], v[98:101]
	v_mfma_f32_16x16x32_bf16 v[86:89], v[158:161], v[206:209], v[86:89]
	v_mfma_f32_16x16x32_bf16 v[82:85], v[166:169], v[206:209], v[82:85]
	v_mfma_f32_16x16x32_bf16 v[70:73], v[158:161], v[214:217], v[70:73]
	v_mfma_f32_16x16x32_bf16 v[66:69], v[166:169], v[214:217], v[66:69]
	v_mfma_f32_16x16x32_bf16 v[118:121], v[162:165], v[178:181], v[118:121]
	v_mfma_f32_16x16x32_bf16 v[114:117], v[170:173], v[178:181], v[114:117]
	v_mfma_f32_16x16x32_bf16 v[102:105], v[162:165], v[202:205], v[102:105]
	v_mfma_f32_16x16x32_bf16 v[98:101], v[170:173], v[202:205], v[98:101]
	v_mfma_f32_16x16x32_bf16 v[86:89], v[162:165], v[210:213], v[86:89]
	v_mfma_f32_16x16x32_bf16 v[82:85], v[170:173], v[210:213], v[82:85]
	v_mfma_f32_16x16x32_bf16 v[70:73], v[162:165], v[218:221], v[70:73]
	v_mfma_f32_16x16x32_bf16 v[66:69], v[170:173], v[218:221], v[66:69]
	s_setprio 0
	s_barrier
	s_add_i32 s30, s65, s33
	v_lshl_add_u64 v[182:183], v[182:183], 0, s[80:81]
	s_mov_b32 m0, s30
	ds_read_b128 v[174:177], v191 offset:49152
	ds_read_b128 v[178:181], v191 offset:50176
	ds_read_b128 v[198:201], v191 offset:51200
	ds_read_b128 v[202:205], v191 offset:52224
	ds_read_b128 v[206:209], v191 offset:53248
	ds_read_b128 v[210:213], v191 offset:54272
	ds_read_b128 v[214:217], v191 offset:55296
	ds_read_b128 v[218:221], v191 offset:56320
	global_load_lds_dwordx4 v[182:183], off
	s_add_i32 m0, s30, 0x2000
	s_add_u32 s30, s36, 0xb0080
	v_lshl_add_u64 v[182:183], v[222:223], 0, s[80:81]
	s_addc_u32 s31, s37, 0
	s_add_i32 s36, s66, s33
	global_load_lds_dwordx4 v[182:183], off
	v_lshl_add_u64 v[182:183], s[30:31], 0, v[0:1]
	s_mov_b32 m0, s36
	s_nop 0
	global_load_lds_dwordx4 v[182:183], off
	v_lshl_add_u64 v[182:183], s[30:31], 0, v[142:143]
	s_add_i32 m0, s36, 0x2000
	s_nop 0
	global_load_lds_dwordx4 v[182:183], off
	v_lshl_add_u64 v[182:183], v[224:225], 0, s[80:81]
	s_mov_b32 m0, s52
	s_nop 0
	global_load_lds_dwordx4 v[182:183], off
	v_lshl_add_u64 v[182:183], v[226:227], 0, s[80:81]
	s_mov_b32 m0, s53
	s_nop 0
	global_load_lds_dwordx4 v[182:183], off
	s_waitcnt vmcnt(8)
	s_waitcnt lgkmcnt(0)
	s_barrier
	s_setprio 1
	s_waitcnt lgkmcnt(0)
	v_mfma_f32_16x16x32_bf16 v[62:65], v[130:133], v[174:177], v[62:65]
	v_mfma_f32_16x16x32_bf16 v[58:61], v[150:153], v[174:177], v[58:61]
	v_mfma_f32_16x16x32_bf16 v[46:49], v[130:133], v[198:201], v[46:49]
	v_mfma_f32_16x16x32_bf16 v[42:45], v[150:153], v[198:201], v[42:45]
	v_mfma_f32_16x16x32_bf16 v[30:33], v[130:133], v[206:209], v[30:33]
	v_mfma_f32_16x16x32_bf16 v[26:29], v[150:153], v[206:209], v[26:29]
	v_mfma_f32_16x16x32_bf16 v[14:17], v[130:133], v[214:217], v[14:17]
	v_mfma_f32_16x16x32_bf16 v[10:13], v[150:153], v[214:217], v[10:13]
	v_mfma_f32_16x16x32_bf16 v[62:65], v[134:137], v[178:181], v[62:65]
	v_mfma_f32_16x16x32_bf16 v[58:61], v[154:157], v[178:181], v[58:61]
	v_mfma_f32_16x16x32_bf16 v[46:49], v[134:137], v[202:205], v[46:49]
	v_mfma_f32_16x16x32_bf16 v[42:45], v[154:157], v[202:205], v[42:45]
	v_mfma_f32_16x16x32_bf16 v[30:33], v[134:137], v[210:213], v[30:33]
	v_mfma_f32_16x16x32_bf16 v[26:29], v[154:157], v[210:213], v[26:29]
	v_mfma_f32_16x16x32_bf16 v[14:17], v[134:137], v[218:221], v[14:17]
	v_mfma_f32_16x16x32_bf16 v[10:13], v[154:157], v[218:221], v[10:13]
	s_setprio 0
	s_setprio 1
	v_mfma_f32_16x16x32_bf16 v[54:57], v[158:161], v[174:177], v[54:57]
	v_mfma_f32_16x16x32_bf16 v[50:53], v[166:169], v[174:177], v[50:53]
	v_mfma_f32_16x16x32_bf16 v[38:41], v[158:161], v[198:201], v[38:41]
	v_mfma_f32_16x16x32_bf16 v[34:37], v[166:169], v[198:201], v[34:37]
	v_mfma_f32_16x16x32_bf16 v[22:25], v[158:161], v[206:209], v[22:25]
	v_mfma_f32_16x16x32_bf16 v[18:21], v[166:169], v[206:209], v[18:21]
	v_mfma_f32_16x16x32_bf16 v[6:9], v[158:161], v[214:217], v[6:9]
	v_mfma_f32_16x16x32_bf16 v[2:5], v[166:169], v[214:217], v[2:5]
	v_mfma_f32_16x16x32_bf16 v[54:57], v[162:165], v[178:181], v[54:57]
	v_mfma_f32_16x16x32_bf16 v[50:53], v[170:173], v[178:181], v[50:53]
	v_mfma_f32_16x16x32_bf16 v[38:41], v[162:165], v[202:205], v[38:41]
	v_mfma_f32_16x16x32_bf16 v[34:37], v[170:173], v[202:205], v[34:37]
	v_mfma_f32_16x16x32_bf16 v[22:25], v[162:165], v[210:213], v[22:25]
	v_mfma_f32_16x16x32_bf16 v[18:21], v[170:173], v[210:213], v[18:21]
	v_mfma_f32_16x16x32_bf16 v[6:9], v[162:165], v[218:221], v[6:9]
	v_mfma_f32_16x16x32_bf16 v[2:5], v[170:173], v[218:221], v[2:5]
	s_setprio 0
	s_barrier
	s_add_i32 s64, s64, 2
	s_add_u32 s1, s1, 0x100
	s_addc_u32 s63, s63, 0
	s_cmp_gt_u32 s64, 41
	s_mov_b64 s[30:31], s[34:35]
	s_cbranch_scc0 .LBB0_2545
	s_and_b64 vcc, exec, s[16:17]
	s_cbranch_vccz .LBB0_2548
	s_barrier

.LBB0_2608:
	s_add_u32 s16, s14, 0x100
	s_addc_u32 s17, s15, 0
	s_add_i32 s47, 0, 0x10000
	s_cmp_eq_u32 s46, 40
	s_cselect_b32 s21, s1, s17
	s_cselect_b32 s20, s0, s16
	v_add_u32_e32 v0, s47, v168
	s_cselect_b32 s19, s11, s39
	s_cselect_b32 s18, s10, s38
	s_add_i32 s48, 0, 0x14000
	ds_read_b128 v[130:133], v0
	ds_read_b128 v[148:151], v0 offset:1024
	ds_read_b128 v[152:155], v0 offset:2048
	ds_read_b128 v[156:159], v0 offset:3072
	v_add_u32_e32 v0, s48, v168
	ds_read_b128 v[160:163], v0
	ds_read_b128 v[164:167], v0 offset:1024
	ds_read_b128 v[170:173], v0 offset:2048
	ds_read_b128 v[174:177], v0 offset:3072
	v_lshl_add_u64 v[210:211], s[14:15], 0, v[144:145]
	s_add_i32 m0, s23, 0xc000
	ds_read_b128 v[178:181], v169
	ds_read_b128 v[182:185], v169 offset:1024
	ds_read_b128 v[186:189], v169 offset:2048
	ds_read_b128 v[190:193], v169 offset:3072
	ds_read_b128 v[194:197], v169 offset:4096
	ds_read_b128 v[198:201], v169 offset:5120
	ds_read_b128 v[202:205], v169 offset:6144
	ds_read_b128 v[206:209], v169 offset:7168
	global_load_lds_dwordx4 v[210:211], off
	v_lshl_add_u64 v[210:211], s[14:15], 0, v[146:147]
	s_add_i32 m0, s23, 0xe000
	s_nop 0
	global_load_lds_dwordx4 v[210:211], off
	s_waitcnt vmcnt(8)
	s_waitcnt lgkmcnt(0)
	s_barrier
	s_setprio 1
	s_waitcnt lgkmcnt(0)
	v_mfma_f32_16x16x32_bf16 v[126:129], v[130:133], v[178:181], v[126:129]
	v_mfma_f32_16x16x32_bf16 v[122:125], v[152:155], v[178:181], v[122:125]
	v_mfma_f32_16x16x32_bf16 v[110:113], v[130:133], v[186:189], v[110:113]
	v_mfma_f32_16x16x32_bf16 v[106:109], v[152:155], v[186:189], v[106:109]
	v_mfma_f32_16x16x32_bf16 v[94:97], v[130:133], v[194:197], v[94:97]
	v_mfma_f32_16x16x32_bf16 v[90:93], v[152:155], v[194:197], v[90:93]
	v_mfma_f32_16x16x32_bf16 v[78:81], v[130:133], v[202:205], v[78:81]
	v_mfma_f32_16x16x32_bf16 v[74:77], v[152:155], v[202:205], v[74:77]
	v_mfma_f32_16x16x32_bf16 v[126:129], v[148:151], v[182:185], v[126:129]
	v_mfma_f32_16x16x32_bf16 v[122:125], v[156:159], v[182:185], v[122:125]
	v_mfma_f32_16x16x32_bf16 v[110:113], v[148:151], v[190:193], v[110:113]
	v_mfma_f32_16x16x32_bf16 v[106:109], v[156:159], v[190:193], v[106:109]
	v_mfma_f32_16x16x32_bf16 v[94:97], v[148:151], v[198:201], v[94:97]
	v_mfma_f32_16x16x32_bf16 v[90:93], v[156:159], v[198:201], v[90:93]
	v_mfma_f32_16x16x32_bf16 v[78:81], v[148:151], v[206:209], v[78:81]
	v_mfma_f32_16x16x32_bf16 v[74:77], v[156:159], v[206:209], v[74:77]
	s_setprio 0
	s_setprio 1
	v_mfma_f32_16x16x32_bf16 v[118:121], v[160:163], v[178:181], v[118:121]
	v_mfma_f32_16x16x32_bf16 v[114:117], v[170:173], v[178:181], v[114:117]
	v_mfma_f32_16x16x32_bf16 v[102:105], v[160:163], v[186:189], v[102:105]
	v_mfma_f32_16x16x32_bf16 v[98:101], v[170:173], v[186:189], v[98:101]
	v_mfma_f32_16x16x32_bf16 v[86:89], v[160:163], v[194:197], v[86:89]
	v_mfma_f32_16x16x32_bf16 v[82:85], v[170:173], v[194:197], v[82:85]
	v_mfma_f32_16x16x32_bf16 v[70:73], v[160:163], v[202:205], v[70:73]
	v_mfma_f32_16x16x32_bf16 v[66:69], v[170:173], v[202:205], v[66:69]
	v_mfma_f32_16x16x32_bf16 v[118:121], v[164:167], v[182:185], v[118:121]
	v_mfma_f32_16x16x32_bf16 v[114:117], v[174:177], v[182:185], v[114:117]
	v_mfma_f32_16x16x32_bf16 v[102:105], v[164:167], v[190:193], v[102:105]
	v_mfma_f32_16x16x32_bf16 v[98:101], v[174:177], v[190:193], v[98:101]
	v_mfma_f32_16x16x32_bf16 v[86:89], v[164:167], v[198:201], v[86:89]
	v_mfma_f32_16x16x32_bf16 v[82:85], v[174:177], v[198:201], v[82:85]
	v_mfma_f32_16x16x32_bf16 v[70:73], v[164:167], v[206:209], v[70:73]
	v_mfma_f32_16x16x32_bf16 v[66:69], v[174:177], v[206:209], v[66:69]
	s_setprio 0
	s_barrier
	s_add_i32 s14, s47, s22
	v_lshl_add_u64 v[210:211], s[18:19], 0, v[136:137]
	s_mov_b32 m0, s14
	ds_read_b128 v[178:181], v169 offset:16384
	ds_read_b128 v[182:185], v169 offset:17408
	ds_read_b128 v[186:189], v169 offset:18432
	ds_read_b128 v[190:193], v169 offset:19456
	ds_read_b128 v[194:197], v169 offset:20480
	ds_read_b128 v[198:201], v169 offset:21504
	ds_read_b128 v[202:205], v169 offset:22528
	ds_read_b128 v[206:209], v169 offset:23552
	global_load_lds_dwordx4 v[210:211], off
	s_add_i32 m0, s14, 0x2000
	s_add_u32 s14, s18, 0xb0000
	v_lshl_add_u64 v[212:213], s[18:19], 0, v[140:141]
	s_addc_u32 s15, s19, 0
	s_add_i32 s47, s48, s22
	global_load_lds_dwordx4 v[212:213], off
	v_lshl_add_u64 v[214:215], s[14:15], 0, v[136:137]
	s_mov_b32 m0, s47
	v_lshl_add_u64 v[216:217], s[20:21], 0, v[138:139]
	global_load_lds_dwordx4 v[214:215], off
	v_lshl_add_u64 v[214:215], s[14:15], 0, v[140:141]
	s_add_i32 m0, s47, 0x2000
	s_nop 0
	global_load_lds_dwordx4 v[214:215], off
	s_waitcnt vmcnt(6)
	s_waitcnt lgkmcnt(0)
	s_barrier
	s_setprio 1
	s_waitcnt lgkmcnt(0)
	v_mfma_f32_16x16x32_bf16 v[62:65], v[130:133], v[178:181], v[62:65]
	v_mfma_f32_16x16x32_bf16 v[58:61], v[152:155], v[178:181], v[58:61]
	v_mfma_f32_16x16x32_bf16 v[46:49], v[130:133], v[186:189], v[46:49]
	v_mfma_f32_16x16x32_bf16 v[42:45], v[152:155], v[186:189], v[42:45]
	v_mfma_f32_16x16x32_bf16 v[30:33], v[130:133], v[194:197], v[30:33]
	v_mfma_f32_16x16x32_bf16 v[26:29], v[152:155], v[194:197], v[26:29]
	v_mfma_f32_16x16x32_bf16 v[14:17], v[130:133], v[202:205], v[14:17]
	v_mfma_f32_16x16x32_bf16 v[10:13], v[152:155], v[202:205], v[10:13]
	v_mfma_f32_16x16x32_bf16 v[62:65], v[148:151], v[182:185], v[62:65]
	v_mfma_f32_16x16x32_bf16 v[58:61], v[156:159], v[182:185], v[58:61]
	v_mfma_f32_16x16x32_bf16 v[46:49], v[148:151], v[190:193], v[46:49]
	v_mfma_f32_16x16x32_bf16 v[42:45], v[156:159], v[190:193], v[42:45]
	v_mfma_f32_16x16x32_bf16 v[30:33], v[148:151], v[198:201], v[30:33]
	v_mfma_f32_16x16x32_bf16 v[26:29], v[156:159], v[198:201], v[26:29]
	v_mfma_f32_16x16x32_bf16 v[14:17], v[148:151], v[206:209], v[14:17]
	v_mfma_f32_16x16x32_bf16 v[10:13], v[156:159], v[206:209], v[10:13]
	s_setprio 0
	s_setprio 1
	v_mfma_f32_16x16x32_bf16 v[54:57], v[160:163], v[178:181], v[54:57]
	v_mfma_f32_16x16x32_bf16 v[50:53], v[170:173], v[178:181], v[50:53]
	v_mfma_f32_16x16x32_bf16 v[38:41], v[160:163], v[186:189], v[38:41]
	v_mfma_f32_16x16x32_bf16 v[34:37], v[170:173], v[186:189], v[34:37]
	v_mfma_f32_16x16x32_bf16 v[22:25], v[160:163], v[194:197], v[22:25]
	v_mfma_f32_16x16x32_bf16 v[18:21], v[170:173], v[194:197], v[18:21]
	v_mfma_f32_16x16x32_bf16 v[6:9], v[160:163], v[202:205], v[6:9]
	v_mfma_f32_16x16x32_bf16 v[2:5], v[170:173], v[202:205], v[2:5]
	v_mfma_f32_16x16x32_bf16 v[54:57], v[164:167], v[182:185], v[54:57]
	v_mfma_f32_16x16x32_bf16 v[50:53], v[174:177], v[182:185], v[50:53]
	v_mfma_f32_16x16x32_bf16 v[38:41], v[164:167], v[190:193], v[38:41]
	v_mfma_f32_16x16x32_bf16 v[34:37], v[174:177], v[190:193], v[34:37]
	v_mfma_f32_16x16x32_bf16 v[22:25], v[164:167], v[198:201], v[22:25]
	v_mfma_f32_16x16x32_bf16 v[18:21], v[174:177], v[198:201], v[18:21]
	v_mfma_f32_16x16x32_bf16 v[6:9], v[164:167], v[206:209], v[6:9]
	v_mfma_f32_16x16x32_bf16 v[2:5], v[174:177], v[206:209], v[2:5]
	s_setprio 0
	s_barrier
	s_add_i32 s47, 0, 0x18000
	v_add_u32_e32 v0, s47, v168
	s_add_i32 s48, 0, 0x1c000
	ds_read_b128 v[130:133], v0
	ds_read_b128 v[148:151], v0 offset:1024
	ds_read_b128 v[152:155], v0 offset:2048
	ds_read_b128 v[156:159], v0 offset:3072
	v_add_u32_e32 v0, s48, v168
	ds_read_b128 v[160:163], v0
	ds_read_b128 v[164:167], v0 offset:1024
	ds_read_b128 v[170:173], v0 offset:2048
	ds_read_b128 v[174:177], v0 offset:3072
	s_add_u32 s14, s20, 0xb0000
	s_addc_u32 s15, s21, 0
	v_lshl_add_u64 v[214:215], s[20:21], 0, v[134:135]
	s_mov_b32 m0, s23
	s_nop 0
	global_load_lds_dwordx4 v[214:215], off
	s_mov_b32 m0, s24
	s_nop 0
	global_load_lds_dwordx4 v[216:217], off
	s_mov_b32 m0, s25
	v_lshl_add_u64 v[218:219], s[14:15], 0, v[134:135]
	ds_read_b128 v[178:181], v169 offset:32768
	ds_read_b128 v[182:185], v169 offset:33792
	ds_read_b128 v[186:189], v169 offset:34816
	ds_read_b128 v[190:193], v169 offset:35840
	ds_read_b128 v[194:197], v169 offset:36864
	ds_read_b128 v[198:201], v169 offset:37888
	ds_read_b128 v[202:205], v169 offset:38912
	ds_read_b128 v[206:209], v169 offset:39936
	global_load_lds_dwordx4 v[218:219], off
	v_lshl_add_u64 v[218:219], s[14:15], 0, v[138:139]
	s_mov_b32 m0, s26
	s_nop 0
	global_load_lds_dwordx4 v[218:219], off
	s_waitcnt vmcnt(8)
	s_waitcnt lgkmcnt(0)
	s_barrier
	s_setprio 1
	s_waitcnt lgkmcnt(0)
	v_mfma_f32_16x16x32_bf16 v[126:129], v[130:133], v[178:181], v[126:129]
	v_mfma_f32_16x16x32_bf16 v[122:125], v[152:155], v[178:181], v[122:125]
	v_mfma_f32_16x16x32_bf16 v[110:113], v[130:133], v[186:189], v[110:113]
	v_mfma_f32_16x16x32_bf16 v[106:109], v[152:155], v[186:189], v[106:109]
	v_mfma_f32_16x16x32_bf16 v[94:97], v[130:133], v[194:197], v[94:97]
	v_mfma_f32_16x16x32_bf16 v[90:93], v[152:155], v[194:197], v[90:93]
	v_mfma_f32_16x16x32_bf16 v[78:81], v[130:133], v[202:205], v[78:81]
	v_mfma_f32_16x16x32_bf16 v[74:77], v[152:155], v[202:205], v[74:77]
	v_mfma_f32_16x16x32_bf16 v[126:129], v[148:151], v[182:185], v[126:129]
	v_mfma_f32_16x16x32_bf16 v[122:125], v[156:159], v[182:185], v[122:125]
	v_mfma_f32_16x16x32_bf16 v[110:113], v[148:151], v[190:193], v[110:113]
	v_mfma_f32_16x16x32_bf16 v[106:109], v[156:159], v[190:193], v[106:109]
	v_mfma_f32_16x16x32_bf16 v[94:97], v[148:151], v[198:201], v[94:97]
	v_mfma_f32_16x16x32_bf16 v[90:93], v[156:159], v[198:201], v[90:93]
	v_mfma_f32_16x16x32_bf16 v[78:81], v[148:151], v[206:209], v[78:81]
	v_mfma_f32_16x16x32_bf16 v[74:77], v[156:159], v[206:209], v[74:77]
	s_setprio 0
	s_setprio 1
	v_mfma_f32_16x16x32_bf16 v[118:121], v[160:163], v[178:181], v[118:121]
	v_mfma_f32_16x16x32_bf16 v[114:117], v[170:173], v[178:181], v[114:117]
	v_mfma_f32_16x16x32_bf16 v[102:105], v[160:163], v[186:189], v[102:105]
	v_mfma_f32_16x16x32_bf16 v[98:101], v[170:173], v[186:189], v[98:101]
	v_mfma_f32_16x16x32_bf16 v[86:89], v[160:163], v[194:197], v[86:89]
	v_mfma_f32_16x16x32_bf16 v[82:85], v[170:173], v[194:197], v[82:85]
	v_mfma_f32_16x16x32_bf16 v[70:73], v[160:163], v[202:205], v[70:73]
	v_mfma_f32_16x16x32_bf16 v[66:69], v[170:173], v[202:205], v[66:69]
	v_mfma_f32_16x16x32_bf16 v[118:121], v[164:167], v[182:185], v[118:121]
	v_mfma_f32_16x16x32_bf16 v[114:117], v[174:177], v[182:185], v[114:117]
	v_mfma_f32_16x16x32_bf16 v[102:105], v[164:167], v[190:193], v[102:105]
	v_mfma_f32_16x16x32_bf16 v[98:101], v[174:177], v[190:193], v[98:101]
	v_mfma_f32_16x16x32_bf16 v[86:89], v[164:167], v[198:201], v[86:89]
	v_mfma_f32_16x16x32_bf16 v[82:85], v[174:177], v[198:201], v[82:85]
	v_mfma_f32_16x16x32_bf16 v[70:73], v[164:167], v[206:209], v[70:73]
	v_mfma_f32_16x16x32_bf16 v[66:69], v[174:177], v[206:209], v[66:69]
	s_setprio 0
	s_barrier
	s_add_i32 s14, s47, s22
	v_lshl_add_u64 v[210:211], v[210:211], 0, s[80:81]
	s_mov_b32 m0, s14
	ds_read_b128 v[178:181], v169 offset:49152
	ds_read_b128 v[182:185], v169 offset:50176
	ds_read_b128 v[186:189], v169 offset:51200
	ds_read_b128 v[190:193], v169 offset:52224
	ds_read_b128 v[194:197], v169 offset:53248
	ds_read_b128 v[198:201], v169 offset:54272
	ds_read_b128 v[202:205], v169 offset:55296
	ds_read_b128 v[206:209], v169 offset:56320
	global_load_lds_dwordx4 v[210:211], off
	s_add_i32 m0, s14, 0x2000
	s_add_u32 s14, s18, 0xb0080
	v_lshl_add_u64 v[210:211], v[212:213], 0, s[80:81]
	s_addc_u32 s15, s19, 0
	s_add_i32 s18, s48, s22
	global_load_lds_dwordx4 v[210:211], off
	v_lshl_add_u64 v[210:211], s[14:15], 0, v[136:137]
	s_mov_b32 m0, s18
	s_nop 0
	global_load_lds_dwordx4 v[210:211], off
	v_lshl_add_u64 v[210:211], s[14:15], 0, v[140:141]
	s_add_i32 m0, s18, 0x2000
	s_nop 0
	global_load_lds_dwordx4 v[210:211], off
	v_lshl_add_u64 v[210:211], v[214:215], 0, s[80:81]
	s_mov_b32 m0, s30
	s_nop 0
	global_load_lds_dwordx4 v[210:211], off
	v_lshl_add_u64 v[210:211], v[216:217], 0, s[80:81]
	s_mov_b32 m0, s31
	s_nop 0
	global_load_lds_dwordx4 v[210:211], off
	s_waitcnt vmcnt(8)
	s_waitcnt lgkmcnt(0)
	s_barrier
	s_setprio 1
	s_waitcnt lgkmcnt(0)
	v_mfma_f32_16x16x32_bf16 v[62:65], v[130:133], v[178:181], v[62:65]
	v_mfma_f32_16x16x32_bf16 v[58:61], v[152:155], v[178:181], v[58:61]
	v_mfma_f32_16x16x32_bf16 v[46:49], v[130:133], v[186:189], v[46:49]
	v_mfma_f32_16x16x32_bf16 v[42:45], v[152:155], v[186:189], v[42:45]
	v_mfma_f32_16x16x32_bf16 v[30:33], v[130:133], v[194:197], v[30:33]
	v_mfma_f32_16x16x32_bf16 v[26:29], v[152:155], v[194:197], v[26:29]
	v_mfma_f32_16x16x32_bf16 v[14:17], v[130:133], v[202:205], v[14:17]
	v_mfma_f32_16x16x32_bf16 v[10:13], v[152:155], v[202:205], v[10:13]
	v_mfma_f32_16x16x32_bf16 v[62:65], v[148:151], v[182:185], v[62:65]
	v_mfma_f32_16x16x32_bf16 v[58:61], v[156:159], v[182:185], v[58:61]
	v_mfma_f32_16x16x32_bf16 v[46:49], v[148:151], v[190:193], v[46:49]
	v_mfma_f32_16x16x32_bf16 v[42:45], v[156:159], v[190:193], v[42:45]
	v_mfma_f32_16x16x32_bf16 v[30:33], v[148:151], v[198:201], v[30:33]
	v_mfma_f32_16x16x32_bf16 v[26:29], v[156:159], v[198:201], v[26:29]
	v_mfma_f32_16x16x32_bf16 v[14:17], v[148:151], v[206:209], v[14:17]
	v_mfma_f32_16x16x32_bf16 v[10:13], v[156:159], v[206:209], v[10:13]
	s_setprio 0
	s_setprio 1
	v_mfma_f32_16x16x32_bf16 v[54:57], v[160:163], v[178:181], v[54:57]
	v_mfma_f32_16x16x32_bf16 v[50:53], v[170:173], v[178:181], v[50:53]
	v_mfma_f32_16x16x32_bf16 v[38:41], v[160:163], v[186:189], v[38:41]
	v_mfma_f32_16x16x32_bf16 v[34:37], v[170:173], v[186:189], v[34:37]
	v_mfma_f32_16x16x32_bf16 v[22:25], v[160:163], v[194:197], v[22:25]
	v_mfma_f32_16x16x32_bf16 v[18:21], v[170:173], v[194:197], v[18:21]
	v_mfma_f32_16x16x32_bf16 v[6:9], v[160:163], v[202:205], v[6:9]
	v_mfma_f32_16x16x32_bf16 v[2:5], v[170:173], v[202:205], v[2:5]
	v_mfma_f32_16x16x32_bf16 v[54:57], v[164:167], v[182:185], v[54:57]
	v_mfma_f32_16x16x32_bf16 v[50:53], v[174:177], v[182:185], v[50:53]
	v_mfma_f32_16x16x32_bf16 v[38:41], v[164:167], v[190:193], v[38:41]
	v_mfma_f32_16x16x32_bf16 v[34:37], v[174:177], v[190:193], v[34:37]
	v_mfma_f32_16x16x32_bf16 v[22:25], v[164:167], v[198:201], v[22:25]
	v_mfma_f32_16x16x32_bf16 v[18:21], v[174:177], v[198:201], v[18:21]
	v_mfma_f32_16x16x32_bf16 v[6:9], v[164:167], v[206:209], v[6:9]
	v_mfma_f32_16x16x32_bf16 v[2:5], v[174:177], v[206:209], v[2:5]
	s_setprio 0
	s_barrier
	s_add_i32 s46, s46, 2
	s_add_u32 s38, s38, 0x100
	s_addc_u32 s39, s39, 0
	s_cmp_gt_u32 s46, 41
	s_mov_b64 s[14:15], s[16:17]
	s_cbranch_scc0 .LBB0_2608
	s_and_b64 vcc, exec, s[8:9]
	s_cbranch_vccz .LBB0_2611
	s_barrier
